# GEMM K-loops: LDS-DMA loads use the 32-bit-offset + scalar-base form (no per-load 64-bit VALU address add)
# speedup vs baseline: 1.1101x; 1.0081x over previous
; #define PG8_STAGE(bufoff, gbase, voff) do { _Pragma("unroll") for (int _i = 0; _i < 2; ++_i) \
;         __builtin_amdgcn_global_load_lds((const unsigned*)((const char*)(gbase) + (voff)[_i]), (PG8_LAS unsigned*)(lds + (bufoff) + ldsw + _i * 8192), 16, 0, 0); } while (0)
; #define PG8_WAIT_V(n) asm volatile("s_waitcnt vmcnt(" #n ")" ::: "memory")
; #define PG8_BAR __builtin_amdgcn_s_barrier()
; template <class Epi, class Sched, bool ALIGN_EPI = false, bool SP2 = false>
; __device__ __forceinline__ void gemm_phase(PG8_LAS unsigned char* lds, const Gemm g, const Sched& S, const Epi& E) {
;     ...
;         PG8_STAGE(PG8_SB(1, 0), cB + kstep, voffB); PG8_STAGE(PG8_SA(1, 0), cA + kstep, voffA); PG8_STAGE(PG8_SB(1, 1), cB + hstepB + kstep, voffB);
;         PG8_WAIT_V(6); PG8_BAR;
.LBB0_144:
	s_and_b32 s53, s8, 3
	s_lshl_b32 s8, s14, 6
	s_lshl_b32 s15, s14, 13
	s_lshl_b32 s16, s53, 12
	s_add_u32 s12, s26, 0x8000
	s_addc_u32 s13, s27, 0
	s_add_i32 m0, s23, 0x18000
	v_lshl_add_u64 v[8:9], s[12:13], 0, v[134:135]
	s_waitcnt vmcnt(2)
	s_barrier
	global_load_lds_dwordx4 v[8:9], off
	s_add_i32 m0, s23, 0x1a000
	v_lshl_add_u64 v[8:9], s[12:13], 0, v[130:131]
	s_add_u32 s12, s24, 0x8000
	s_addc_u32 s13, s25, 0
	s_add_i32 s54, s23, 0x8000
	global_load_lds_dwordx4 v[8:9], off
	s_mov_b32 m0, s54
	s_add_i32 s55, s23, 0xa000
	global_load_lds_dwordx4 v136, s[12:13]
	v_lshl_add_u64 v[8:9], s[12:13], 0, v[132:133]
	s_add_u32 s12, s26, 0x9000
	s_mov_b32 m0, s55
	s_addc_u32 s13, s27, 0
	global_load_lds_dwordx4 v[8:9], off
	s_add_i32 m0, s23, 0x1c000
	s_nop 0
	global_load_lds_dwordx4 v134, s[12:13]
	s_add_i32 m0, s23, 0x1e000
	v_and_b32_e32 v7, 15, v218
	global_load_lds_dwordx4 v130, s[12:13]
	v_and_b32_e32 v10, 48, v218
	v_lshlrev_b32_e32 v9, 2, v218
	v_lshl_or_b32 v8, v7, 6, v10
	v_and_b32_e32 v9, 32, v9
	s_sext_i32_i16 s70, s4
	v_bitop3_b32 v11, v8, s15, v9 bitop3:0xde
	v_lshlrev_b32_e32 v8, 6, v218
	s_movk_i32 s4, 0x3c0
	s_cmpk_lt_u32 s5, 0x100
	v_and_or_b32 v8, v8, s4, v10
	s_cselect_b64 s[12:13], -1, 0
	s_lshl_b32 s4, s14, 2
	s_or_b32 s4, s4, s53
	s_mul_i32 s14, s4, 0x900
	s_lshl_b64 s[4:5], s[8:9], 7
	s_ashr_i32 s8, s33, 31
	s_add_u32 s4, s38, s4
	v_bitop3_b32 v149, s16, v8, v9 bitop3:0xf6
	v_lshlrev_b32_e32 v8, 4, v1
	v_mov_b32_e32 v9, v135
	s_addc_u32 s5, s39, s5
	v_lshl_add_u64 v[138:139], s[4:5], 0, v[8:9]
	s_add_i32 s4, s14, 0
	s_add_i32 s4, s4, 0x20000
	s_waitcnt vmcnt(6)
	v_lshrrev_b32_e32 v12, 3, v1
	v_and_b32_e32 v13, 0x70, v3
	s_movk_i32 s5, 0x90
	v_mov_b32_e32 v8, s4
	v_and_b32_e32 v3, 0x3800, v3
	v_lshlrev_b32_e32 v6, 7, v6
	v_and_b32_e32 v2, 0x7800, v2
	v_mad_u32_u24 v7, v7, s5, v8
	v_mad_u32_u24 v8, v12, s5, v8
	v_or3_b32 v3, v4, v3, v6
	v_or3_b32 v2, v4, v2, v6
	s_add_i32 s56, 0, 0x10000
	s_add_i32 s57, 0, 0x14000
	v_add_u32_e32 v140, v3, v5
	v_mov_b32_e32 v141, v135
	v_add_u32_e32 v142, v2, v5
	v_mov_b32_e32 v143, v135
	v_mov_b64_e32 v[144:145], 0x1100
	v_mov_b64_e32 v[146:147], 0x10ff
	v_add_u32_e32 v150, s56, v149
	v_add_u32_e32 v151, s57, v149
	v_add_u32_e32 v152, 0, v11
	v_add_u32_e32 v153, v7, v10
	v_add_u32_e32 v154, v8, v13
	s_movk_i32 s58, 0x1000
	s_movk_i32 s59, 0x5000
	v_mov_b32_e32 v155, 0x3e38aa3b
	s_barrier
	s_branch .LBB0_147

; #define PG8_STAGE(bufoff, gbase, voff) do { _Pragma("unroll") for (int _i = 0; _i < 2; ++_i) \
;         __builtin_amdgcn_global_load_lds((const unsigned*)((const char*)(gbase) + (voff)[_i]), (PG8_LAS unsigned*)(lds + (bufoff) + ldsw + _i * 8192), 16, 0, 0); } while (0)
; #define PG8_LDA(dst, b, h) do { _Pragma("unroll") for (int m = 0; m < 4; ++m) _Pragma("unroll") for (int k = 0; k < 2; ++k) dst[m][k] = *(const PG8_LAS bf16x8*)(lds + PG8_SA(b, h) + aoff + m * 2048 + k * 1024); } while (0)
; #define PG8_LDB(dst, b, h) do { _Pragma("unroll") for (int n = 0; n < 2; ++n) _Pragma("unroll") for (int k = 0; k < 2; ++k) dst[n][k] = *(const PG8_LAS bf16x8*)(lds + PG8_SB(b, h) + boff + n * 2048 + k * 1024); } while (0)
; #define PG8_MMA(ai, bj, At, Bt) do { __builtin_amdgcn_s_setprio(1); _Pragma("unroll") for (int m = 0; m < 4; ++m) _Pragma("unroll") for (int n = 0; n < 2; ++n) _Pragma("unroll") for (int k = 0; k < 2; ++k) \
;         acc[ai][bj][m][n] = __builtin_amdgcn_mfma_f32_16x16x32_bf16(Bt[n][k], At[m][k], acc[ai][bj][m][n], 0, 0, 0); __builtin_amdgcn_s_setprio(0); } while (0)
; #define PG8_WAIT_V(n) asm volatile("s_waitcnt vmcnt(" #n ")" ::: "memory")
; #define PG8_WAIT_L(n) asm volatile("s_waitcnt lgkmcnt(" #n ")" ::: "memory")
; #define PG8_BAR __builtin_amdgcn_s_barrier()
; template <class Epi, class Sched, bool ALIGN_EPI = false, bool SP2 = false>
; __device__ __forceinline__ void gemm_phase(PG8_LAS unsigned char* lds, const Gemm g, const Sched& S, const Epi& E) {
;     ...
;             const char* a1 = cA + (size_t)(t + 1) * kstep;
;             const char* a2 = last ? nA : cA + (size_t)(t + 2) * kstep; const char* b2 = last ? nB : cB + (size_t)(t + 2) * kstep;
;             const char* a3 = a2 + kstep; const char* b3 = b2 + kstep;
;             if (last && has_next) S.a_ready(nxt);
;             if constexpr (SP2) {
;             PG8_LDB(B0, 0, 0); PG8_LDB(B1, 0, 1); PG8_SCHED; PG8_LDA(At, 0, 0); PG8_STAGE(PG8_SA(1, 1), a1 + hstep, voffA);
;             PG8_WAIT_V(8); PG8_WAIT_L(0); PG8_BAR; PG8_MMA(0, 0, At, B0); PG8_MMA(0, 1, At, B1); PG8_BAR; PG8_SCHED;
;             PG8_LDA(At, 0, 1); PG8_STAGE(PG8_SB(0, 0), b2, voffB); PG8_STAGE(PG8_SB(0, 1), b2 + hstepB, voffB); PG8_STAGE(PG8_SA(0, 0), a2, voffA);
;             PG8_WAIT_V(8); PG8_WAIT_L(0); PG8_BAR; PG8_MMA(1, 0, At, B0); PG8_MMA(1, 1, At, B1); PG8_BAR; PG8_SCHED;
.LBB0_150:
	ds_read_b128 v[156:159], v150
	ds_read_b128 v[160:163], v150 offset:1024
	ds_read_b128 v[164:167], v150 offset:2048
	ds_read_b128 v[168:171], v150 offset:3072
	ds_read_b128 v[172:175], v151
	ds_read_b128 v[176:179], v151 offset:1024
	ds_read_b128 v[180:183], v151 offset:2048
	ds_read_b128 v[184:187], v151 offset:3072
	s_add_u32 s26, s24, 0x4000
	s_addc_u32 s27, s25, 0
	s_cmp_eq_u32 s75, 12
	s_cselect_b32 s40, s71, s26
	s_cselect_b32 s41, s17, s27
	s_cselect_b32 s28, s72, s73
	s_cselect_b32 s29, s15, s74
	s_add_u32 s26, s40, 0x8000
	s_addc_u32 s27, s41, 0
	s_add_i32 m0, s23, 0xc000
	ds_read_b128 v[188:191], v152
	ds_read_b128 v[192:195], v152 offset:1024
	ds_read_b128 v[196:199], v152 offset:2048
	ds_read_b128 v[200:203], v152 offset:3072
	ds_read_b128 v[204:207], v152 offset:4096
	ds_read_b128 v[208:211], v152 offset:5120
	ds_read_b128 v[212:215], v152 offset:6144
	ds_read_b128 v[220:223], v152 offset:7168
	global_load_lds_dwordx4 v140, s[24:25]
	s_add_i32 m0, s23, 0xe000
	s_nop 0
	global_load_lds_dwordx4 v142, s[24:25]
	s_waitcnt vmcnt(8)
	s_waitcnt lgkmcnt(0)
	s_setprio 1
	s_barrier
	v_mfma_f32_16x16x32_bf16 v[126:129], v[156:159], v[188:191], v[126:129]
	v_mfma_f32_16x16x32_bf16 v[122:125], v[164:167], v[188:191], v[122:125]
	v_mfma_f32_16x16x32_bf16 v[114:117], v[156:159], v[196:199], v[114:117]
	v_mfma_f32_16x16x32_bf16 v[106:109], v[164:167], v[196:199], v[106:109]
	v_mfma_f32_16x16x32_bf16 v[98:101], v[156:159], v[204:207], v[98:101]
	v_mfma_f32_16x16x32_bf16 v[90:93], v[164:167], v[204:207], v[90:93]
	v_mfma_f32_16x16x32_bf16 v[78:81], v[156:159], v[212:215], v[78:81]
	v_mfma_f32_16x16x32_bf16 v[74:77], v[164:167], v[212:215], v[74:77]
	v_mfma_f32_16x16x32_bf16 v[126:129], v[160:163], v[192:195], v[126:129]
	v_mfma_f32_16x16x32_bf16 v[122:125], v[168:171], v[192:195], v[122:125]
	v_mfma_f32_16x16x32_bf16 v[114:117], v[160:163], v[200:203], v[114:117]
	v_mfma_f32_16x16x32_bf16 v[106:109], v[168:171], v[200:203], v[106:109]
	v_mfma_f32_16x16x32_bf16 v[98:101], v[160:163], v[208:211], v[98:101]
	v_mfma_f32_16x16x32_bf16 v[90:93], v[168:171], v[208:211], v[90:93]
	v_mfma_f32_16x16x32_bf16 v[78:81], v[160:163], v[220:223], v[78:81]
	v_mfma_f32_16x16x32_bf16 v[74:77], v[168:171], v[220:223], v[74:77]
	s_setprio 0
	s_setprio 1
	v_mfma_f32_16x16x32_bf16 v[118:121], v[172:175], v[188:191], v[118:121]
	v_mfma_f32_16x16x32_bf16 v[110:113], v[180:183], v[188:191], v[110:113]
	v_mfma_f32_16x16x32_bf16 v[102:105], v[172:175], v[196:199], v[102:105]
	v_mfma_f32_16x16x32_bf16 v[94:97], v[180:183], v[196:199], v[94:97]
	v_mfma_f32_16x16x32_bf16 v[86:89], v[172:175], v[204:207], v[86:89]
	v_mfma_f32_16x16x32_bf16 v[82:85], v[180:183], v[204:207], v[82:85]
	v_mfma_f32_16x16x32_bf16 v[70:73], v[172:175], v[212:215], v[70:73]
	v_mfma_f32_16x16x32_bf16 v[66:69], v[180:183], v[212:215], v[66:69]
	v_mfma_f32_16x16x32_bf16 v[118:121], v[176:179], v[192:195], v[118:121]
	v_mfma_f32_16x16x32_bf16 v[110:113], v[184:187], v[192:195], v[110:113]
	v_mfma_f32_16x16x32_bf16 v[102:105], v[176:179], v[200:203], v[102:105]
	v_mfma_f32_16x16x32_bf16 v[94:97], v[184:187], v[200:203], v[94:97]
	v_mfma_f32_16x16x32_bf16 v[86:89], v[176:179], v[208:211], v[86:89]
	v_mfma_f32_16x16x32_bf16 v[82:85], v[184:187], v[208:211], v[82:85]
	v_mfma_f32_16x16x32_bf16 v[70:73], v[176:179], v[220:223], v[70:73]
	v_mfma_f32_16x16x32_bf16 v[66:69], v[184:187], v[220:223], v[66:69]
	s_barrier
	s_setprio 0
	s_add_i32 s76, s56, s0
	s_mov_b32 m0, s76
	ds_read_b128 v[188:191], v152 offset:16384
	ds_read_b128 v[192:195], v152 offset:17408
	ds_read_b128 v[196:199], v152 offset:18432
	ds_read_b128 v[200:203], v152 offset:19456
	ds_read_b128 v[204:207], v152 offset:20480
	ds_read_b128 v[208:211], v152 offset:21504
	ds_read_b128 v[212:215], v152 offset:22528
	ds_read_b128 v[220:223], v152 offset:23552
	global_load_lds_dwordx4 v134, s[28:29]
	s_add_i32 m0, s76, 0x2000
	s_add_u32 s76, s28, 0x1000
	s_addc_u32 s77, s29, 0
	s_add_i32 s78, s57, s0
	global_load_lds_dwordx4 v130, s[28:29]
	s_mov_b32 m0, s78
	s_nop 0
	global_load_lds_dwordx4 v134, s[76:77]
	s_add_i32 m0, s78, 0x2000
	s_nop 0
	global_load_lds_dwordx4 v130, s[76:77]
	s_mov_b32 m0, s23
	s_nop 0
	global_load_lds_dwordx4 v136, s[40:41]
	s_mov_b32 m0, s49
	s_nop 0
	global_load_lds_dwordx4 v132, s[40:41]
	s_waitcnt vmcnt(8)
	s_waitcnt lgkmcnt(0)
	s_setprio 1
	s_barrier
	v_mfma_f32_16x16x32_bf16 v[62:65], v[156:159], v[188:191], v[62:65]
	v_mfma_f32_16x16x32_bf16 v[58:61], v[164:167], v[188:191], v[58:61]
	v_mfma_f32_16x16x32_bf16 v[46:49], v[156:159], v[196:199], v[46:49]
	v_mfma_f32_16x16x32_bf16 v[42:45], v[164:167], v[196:199], v[42:45]
	v_mfma_f32_16x16x32_bf16 v[34:37], v[156:159], v[204:207], v[34:37]
	v_mfma_f32_16x16x32_bf16 v[26:29], v[164:167], v[204:207], v[26:29]
	v_mfma_f32_16x16x32_bf16 v[18:21], v[156:159], v[212:215], v[18:21]
	v_mfma_f32_16x16x32_bf16 v[10:13], v[164:167], v[212:215], v[10:13]
	v_mfma_f32_16x16x32_bf16 v[62:65], v[160:163], v[192:195], v[62:65]
	v_mfma_f32_16x16x32_bf16 v[58:61], v[168:171], v[192:195], v[58:61]
	v_mfma_f32_16x16x32_bf16 v[46:49], v[160:163], v[200:203], v[46:49]
	v_mfma_f32_16x16x32_bf16 v[42:45], v[168:171], v[200:203], v[42:45]
	v_mfma_f32_16x16x32_bf16 v[34:37], v[160:163], v[208:211], v[34:37]
	v_mfma_f32_16x16x32_bf16 v[26:29], v[168:171], v[208:211], v[26:29]
	v_mfma_f32_16x16x32_bf16 v[18:21], v[160:163], v[220:223], v[18:21]
	v_mfma_f32_16x16x32_bf16 v[10:13], v[168:171], v[220:223], v[10:13]
	s_setprio 0
	s_setprio 1
	v_mfma_f32_16x16x32_bf16 v[54:57], v[172:175], v[188:191], v[54:57]
	v_mfma_f32_16x16x32_bf16 v[50:53], v[180:183], v[188:191], v[50:53]
	v_mfma_f32_16x16x32_bf16 v[38:41], v[172:175], v[196:199], v[38:41]
	v_mfma_f32_16x16x32_bf16 v[30:33], v[180:183], v[196:199], v[30:33]
	v_mfma_f32_16x16x32_bf16 v[22:25], v[172:175], v[204:207], v[22:25]
	v_mfma_f32_16x16x32_bf16 v[14:17], v[180:183], v[204:207], v[14:17]
	v_mfma_f32_16x16x32_bf16 v[6:9], v[172:175], v[212:215], v[6:9]
	v_mfma_f32_16x16x32_bf16 v[2:5], v[180:183], v[212:215], v[2:5]
	v_mfma_f32_16x16x32_bf16 v[54:57], v[176:179], v[192:195], v[54:57]
	v_mfma_f32_16x16x32_bf16 v[50:53], v[184:187], v[192:195], v[50:53]
	v_mfma_f32_16x16x32_bf16 v[38:41], v[176:179], v[200:203], v[38:41]
	v_mfma_f32_16x16x32_bf16 v[30:33], v[184:187], v[200:203], v[30:33]
	v_mfma_f32_16x16x32_bf16 v[22:25], v[176:179], v[208:211], v[22:25]
	v_mfma_f32_16x16x32_bf16 v[14:17], v[184:187], v[208:211], v[14:17]
	v_mfma_f32_16x16x32_bf16 v[6:9], v[176:179], v[220:223], v[6:9]
	v_mfma_f32_16x16x32_bf16 v[2:5], v[184:187], v[220:223], v[2:5]
	s_barrier
; #define PG8_STAGE(bufoff, gbase, voff) do { _Pragma("unroll") for (int _i = 0; _i < 2; ++_i) \
;         __builtin_amdgcn_global_load_lds((const unsigned*)((const char*)(gbase) + (voff)[_i]), (PG8_LAS unsigned*)(lds + (bufoff) + ldsw + _i * 8192), 16, 0, 0); } while (0)
; #define PG8_LDA(dst, b, h) do { _Pragma("unroll") for (int m = 0; m < 4; ++m) _Pragma("unroll") for (int k = 0; k < 2; ++k) dst[m][k] = *(const PG8_LAS bf16x8*)(lds + PG8_SA(b, h) + aoff + m * 2048 + k * 1024); } while (0)
; #define PG8_LDB(dst, b, h) do { _Pragma("unroll") for (int n = 0; n < 2; ++n) _Pragma("unroll") for (int k = 0; k < 2; ++k) dst[n][k] = *(const PG8_LAS bf16x8*)(lds + PG8_SB(b, h) + boff + n * 2048 + k * 1024); } while (0)
; #define PG8_MMA(ai, bj, At, Bt) do { __builtin_amdgcn_s_setprio(1); _Pragma("unroll") for (int m = 0; m < 4; ++m) _Pragma("unroll") for (int n = 0; n < 2; ++n) _Pragma("unroll") for (int k = 0; k < 2; ++k) \
;         acc[ai][bj][m][n] = __builtin_amdgcn_mfma_f32_16x16x32_bf16(Bt[n][k], At[m][k], acc[ai][bj][m][n], 0, 0, 0); __builtin_amdgcn_s_setprio(0); } while (0)
; #define PG8_WAIT_V(n) asm volatile("s_waitcnt vmcnt(" #n ")" ::: "memory")
; #define PG8_WAIT_L(n) asm volatile("s_waitcnt lgkmcnt(" #n ")" ::: "memory")
; #define PG8_BAR __builtin_amdgcn_s_barrier()
; #define PG8_SCHED __builtin_amdgcn_sched_barrier(0)
; template <class Epi, class Sched, bool ALIGN_EPI = false, bool SP2 = false>
; __device__ __forceinline__ void gemm_phase(PG8_LAS unsigned char* lds, const Gemm g, const Sched& S, const Epi& E) {
;     ...
;             PG8_LDB(B0, 1, 0); PG8_LDB(B1, 1, 1); PG8_SCHED; PG8_LDA(At, 1, 0); PG8_STAGE(PG8_SA(0, 1), a2 + hstep, voffA);
;             PG8_WAIT_V(8); PG8_WAIT_L(0); PG8_BAR; PG8_MMA(0, 0, At, B0); PG8_MMA(0, 1, At, B1); PG8_BAR; PG8_SCHED;
;             PG8_LDA(At, 1, 1); PG8_STAGE(PG8_SB(1, 0), b3, voffB); PG8_STAGE(PG8_SB(1, 1), b3 + hstepB, voffB); PG8_STAGE(PG8_SA(1, 0), a3, voffA);
;             PG8_WAIT_V(8); PG8_WAIT_L(0); PG8_BAR; PG8_MMA(1, 0, At, B0); PG8_MMA(1, 1, At, B1); PG8_BAR; PG8_SCHED;
;     ...
;         if constexpr (ALIGN_EPI) { if (wr == 0) PG8_BAR; }
	s_setprio 0
	s_add_i32 s76, 0, 0x18000
	v_add_u32_e32 v148, s76, v149
	s_add_i32 s77, 0, 0x1c000
	ds_read_b128 v[156:159], v148
	ds_read_b128 v[160:163], v148 offset:1024
	ds_read_b128 v[164:167], v148 offset:2048
	ds_read_b128 v[168:171], v148 offset:3072
	v_add_u32_e32 v148, s77, v149
	ds_read_b128 v[172:175], v148
	ds_read_b128 v[176:179], v148 offset:1024
	ds_read_b128 v[180:183], v148 offset:2048
	ds_read_b128 v[184:187], v148 offset:3072
	s_add_u32 s40, s40, 0x4000
	s_addc_u32 s41, s41, 0
	s_mov_b32 m0, s50
	ds_read_b128 v[188:191], v152 offset:32768
	ds_read_b128 v[192:195], v152 offset:33792
	ds_read_b128 v[196:199], v152 offset:34816
	ds_read_b128 v[200:203], v152 offset:35840
	ds_read_b128 v[204:207], v152 offset:36864
	ds_read_b128 v[208:211], v152 offset:37888
	ds_read_b128 v[212:215], v152 offset:38912
	ds_read_b128 v[220:223], v152 offset:39936
	global_load_lds_dwordx4 v136, s[40:41]
	s_mov_b32 m0, s51
	s_nop 0
	global_load_lds_dwordx4 v132, s[40:41]
	s_waitcnt vmcnt(8)
	s_waitcnt lgkmcnt(0)
	s_setprio 1
	s_barrier
	v_mfma_f32_16x16x32_bf16 v[126:129], v[156:159], v[188:191], v[126:129]
	v_mfma_f32_16x16x32_bf16 v[122:125], v[164:167], v[188:191], v[122:125]
	v_mfma_f32_16x16x32_bf16 v[114:117], v[156:159], v[196:199], v[114:117]
	v_mfma_f32_16x16x32_bf16 v[106:109], v[164:167], v[196:199], v[106:109]
	v_mfma_f32_16x16x32_bf16 v[98:101], v[156:159], v[204:207], v[98:101]
	v_mfma_f32_16x16x32_bf16 v[90:93], v[164:167], v[204:207], v[90:93]
	v_mfma_f32_16x16x32_bf16 v[78:81], v[156:159], v[212:215], v[78:81]
	v_mfma_f32_16x16x32_bf16 v[74:77], v[164:167], v[212:215], v[74:77]
	v_mfma_f32_16x16x32_bf16 v[126:129], v[160:163], v[192:195], v[126:129]
	v_mfma_f32_16x16x32_bf16 v[122:125], v[168:171], v[192:195], v[122:125]
	v_mfma_f32_16x16x32_bf16 v[114:117], v[160:163], v[200:203], v[114:117]
	v_mfma_f32_16x16x32_bf16 v[106:109], v[168:171], v[200:203], v[106:109]
	v_mfma_f32_16x16x32_bf16 v[98:101], v[160:163], v[208:211], v[98:101]
	v_mfma_f32_16x16x32_bf16 v[90:93], v[168:171], v[208:211], v[90:93]
	v_mfma_f32_16x16x32_bf16 v[78:81], v[160:163], v[220:223], v[78:81]
	v_mfma_f32_16x16x32_bf16 v[74:77], v[168:171], v[220:223], v[74:77]
	s_setprio 0
	s_setprio 1
	v_mfma_f32_16x16x32_bf16 v[118:121], v[172:175], v[188:191], v[118:121]
	v_mfma_f32_16x16x32_bf16 v[110:113], v[180:183], v[188:191], v[110:113]
	v_mfma_f32_16x16x32_bf16 v[102:105], v[172:175], v[196:199], v[102:105]
	v_mfma_f32_16x16x32_bf16 v[94:97], v[180:183], v[196:199], v[94:97]
	v_mfma_f32_16x16x32_bf16 v[86:89], v[172:175], v[204:207], v[86:89]
	v_mfma_f32_16x16x32_bf16 v[82:85], v[180:183], v[204:207], v[82:85]
	v_mfma_f32_16x16x32_bf16 v[70:73], v[172:175], v[212:215], v[70:73]
	v_mfma_f32_16x16x32_bf16 v[66:69], v[180:183], v[212:215], v[66:69]
	v_mfma_f32_16x16x32_bf16 v[118:121], v[176:179], v[192:195], v[118:121]
	v_mfma_f32_16x16x32_bf16 v[110:113], v[184:187], v[192:195], v[110:113]
	v_mfma_f32_16x16x32_bf16 v[102:105], v[176:179], v[200:203], v[102:105]
	v_mfma_f32_16x16x32_bf16 v[94:97], v[184:187], v[200:203], v[94:97]
	v_mfma_f32_16x16x32_bf16 v[86:89], v[176:179], v[208:211], v[86:89]
	v_mfma_f32_16x16x32_bf16 v[82:85], v[184:187], v[208:211], v[82:85]
	v_mfma_f32_16x16x32_bf16 v[70:73], v[176:179], v[220:223], v[70:73]
	v_mfma_f32_16x16x32_bf16 v[66:69], v[184:187], v[220:223], v[66:69]
	s_barrier
	s_setprio 0
	s_add_u32 s40, s28, 0x8000
	s_addc_u32 s41, s29, 0
	s_add_i32 s76, s76, s0
	s_mov_b32 m0, s76
	ds_read_b128 v[188:191], v152 offset:49152
	ds_read_b128 v[192:195], v152 offset:50176
	ds_read_b128 v[196:199], v152 offset:51200
	ds_read_b128 v[200:203], v152 offset:52224
	ds_read_b128 v[204:207], v152 offset:53248
	ds_read_b128 v[208:211], v152 offset:54272
	ds_read_b128 v[212:215], v152 offset:55296
	ds_read_b128 v[220:223], v152 offset:56320
	global_load_lds_dwordx4 v134, s[40:41]
	s_add_i32 m0, s76, 0x2000
	s_add_u32 s28, s28, 0x9000
	v_lshl_add_u64 v[216:217], s[40:41], 0, v[130:131]
	s_addc_u32 s29, s29, 0
	s_add_i32 s40, s77, s0
	global_load_lds_dwordx4 v[216:217], off
	s_mov_b32 m0, s40
	s_nop 0
	global_load_lds_dwordx4 v134, s[28:29]
	s_add_i32 m0, s40, 0x2000
	s_nop 0
	global_load_lds_dwordx4 v130, s[28:29]
	s_mov_b32 m0, s54
	s_nop 0
	global_load_lds_dwordx4 v136, s[26:27]
	s_mov_b32 m0, s55
	s_nop 0
	global_load_lds_dwordx4 v132, s[26:27]
	s_waitcnt vmcnt(8)
	s_waitcnt lgkmcnt(0)
	s_setprio 1
	s_barrier
	v_mfma_f32_16x16x32_bf16 v[62:65], v[156:159], v[188:191], v[62:65]
	v_mfma_f32_16x16x32_bf16 v[58:61], v[164:167], v[188:191], v[58:61]
	v_mfma_f32_16x16x32_bf16 v[46:49], v[156:159], v[196:199], v[46:49]
	v_mfma_f32_16x16x32_bf16 v[42:45], v[164:167], v[196:199], v[42:45]
	v_mfma_f32_16x16x32_bf16 v[34:37], v[156:159], v[204:207], v[34:37]
	v_mfma_f32_16x16x32_bf16 v[26:29], v[164:167], v[204:207], v[26:29]
	v_mfma_f32_16x16x32_bf16 v[18:21], v[156:159], v[212:215], v[18:21]
	v_mfma_f32_16x16x32_bf16 v[10:13], v[164:167], v[212:215], v[10:13]
	v_mfma_f32_16x16x32_bf16 v[62:65], v[160:163], v[192:195], v[62:65]
	v_mfma_f32_16x16x32_bf16 v[58:61], v[168:171], v[192:195], v[58:61]
	v_mfma_f32_16x16x32_bf16 v[46:49], v[160:163], v[200:203], v[46:49]
	v_mfma_f32_16x16x32_bf16 v[42:45], v[168:171], v[200:203], v[42:45]
	v_mfma_f32_16x16x32_bf16 v[34:37], v[160:163], v[208:211], v[34:37]
	v_mfma_f32_16x16x32_bf16 v[26:29], v[168:171], v[208:211], v[26:29]
	v_mfma_f32_16x16x32_bf16 v[18:21], v[160:163], v[220:223], v[18:21]
	v_mfma_f32_16x16x32_bf16 v[10:13], v[168:171], v[220:223], v[10:13]
	s_setprio 0
	s_setprio 1
	v_mfma_f32_16x16x32_bf16 v[54:57], v[172:175], v[188:191], v[54:57]
	v_mfma_f32_16x16x32_bf16 v[50:53], v[180:183], v[188:191], v[50:53]
	v_mfma_f32_16x16x32_bf16 v[38:41], v[172:175], v[196:199], v[38:41]
	v_mfma_f32_16x16x32_bf16 v[30:33], v[180:183], v[196:199], v[30:33]
	v_mfma_f32_16x16x32_bf16 v[22:25], v[172:175], v[204:207], v[22:25]
	v_mfma_f32_16x16x32_bf16 v[14:17], v[180:183], v[204:207], v[14:17]
	v_mfma_f32_16x16x32_bf16 v[6:9], v[172:175], v[212:215], v[6:9]
	v_mfma_f32_16x16x32_bf16 v[2:5], v[180:183], v[212:215], v[2:5]
	v_mfma_f32_16x16x32_bf16 v[54:57], v[176:179], v[192:195], v[54:57]
	v_mfma_f32_16x16x32_bf16 v[50:53], v[184:187], v[192:195], v[50:53]
	v_mfma_f32_16x16x32_bf16 v[38:41], v[176:179], v[200:203], v[38:41]
	v_mfma_f32_16x16x32_bf16 v[30:33], v[184:187], v[200:203], v[30:33]
	v_mfma_f32_16x16x32_bf16 v[22:25], v[176:179], v[208:211], v[22:25]
	v_mfma_f32_16x16x32_bf16 v[14:17], v[184:187], v[208:211], v[14:17]
	v_mfma_f32_16x16x32_bf16 v[6:9], v[176:179], v[220:223], v[6:9]
	v_mfma_f32_16x16x32_bf16 v[2:5], v[184:187], v[220:223], v[2:5]
	s_barrier
	s_setprio 0
	s_add_i32 s75, s75, 2
	s_add_u32 s24, s24, 0x10000
	s_addc_u32 s25, s25, 0
	s_add_u32 s73, s73, 0x10000
	s_addc_u32 s74, s74, 0
	s_cmp_gt_u32 s75, 13
	s_cbranch_scc0 .LBB0_150
	s_and_b64 vcc, exec, s[12:13]
	s_cbranch_vccz .LBB0_153
	s_barrier

; __device__ __forceinline__ size_t tm_block(int pm, int ct, int nct) { return ((size_t)pm * nct + ct) * 32768; }
; #define PG8_STAGE(bufoff, gbase, voff) do { _Pragma("unroll") for (int _i = 0; _i < 2; ++_i) \
;         __builtin_amdgcn_global_load_lds((const unsigned*)((const char*)(gbase) + (voff)[_i]), (PG8_LAS unsigned*)(lds + (bufoff) + ldsw + _i * 8192), 16, 0, 0); } while (0)
; #define PG8_WAIT_V(n) asm volatile("s_waitcnt vmcnt(" #n ")" ::: "memory")
; #define PG8_BAR __builtin_amdgcn_s_barrier()
;     __device__ __forceinline__ void mid(f32x4 (&acc)[2][2][4][2], const Unit& u, int wr, int wc, int fr, int fq) const {
;     ...
;         const PieceIn pa(scr, Z, tm_block(pm, ga_ct + cb, znct), wr, wc, fr, fq), pb(scr, Z, tm_block(pm, gb_ct + cb, znct), wr, wc, fr, fq);
;         const int col0 = cb * 64 + 8 * fq;
;         f32x4 ba[2][2], bb[2][2];
; #pragma unroll
;         for (int bj = 0; bj < 2; ++bj) { ba[bj][0] = *(const f32x4*)(bg + col0 + bj * 32); ba[bj][1] = *(const f32x4*)(bg + col0 + bj * 32 + 4); bb[bj][0] = *(const f32x4*)(bg + 1024 + col0 + bj * 32); bb[bj][1] = *(const f32x4*)(bg + 1024 + col0 + bj * 32 + 4); }
; template <class Epi, class Sched, bool ALIGN_EPI = false, bool SP2 = false>
; __device__ __forceinline__ void gemm_phase(PG8_LAS unsigned char* lds, const Gemm g, const Sched& S, const Epi& E) {
;     ...
;         PG8_STAGE(PG8_SB(1, 0), cB + kstep, voffB); PG8_STAGE(PG8_SA(1, 0), cA + kstep, voffA); PG8_STAGE(PG8_SB(1, 1), cB + hstepB + kstep, voffB);
;         PG8_WAIT_V(6); PG8_BAR;
.LBB0_370:
	s_and_b32 s80, s5, 3
	s_lshl_b32 s8, s1, 6
	s_lshl_b32 s5, s1, 13
	s_lshl_b32 s14, s80, 12
	s_add_u32 s12, s46, 0x8000
	s_addc_u32 s13, s47, 0
	s_add_i32 m0, s74, 0x18000
	v_lshl_add_u64 v[8:9], s[12:13], 0, v[200:201]
	s_waitcnt vmcnt(2)
	s_barrier
	global_load_lds_dwordx4 v[8:9], off
	s_add_i32 m0, s74, 0x1a000
	v_lshl_add_u64 v[8:9], s[12:13], 0, v[204:205]
	s_add_u32 s12, s28, 0x8000
	s_addc_u32 s13, s29, 0
	s_add_i32 s81, s74, 0x8000
	global_load_lds_dwordx4 v[8:9], off
	s_mov_b32 m0, s81
	s_add_i32 s82, s74, 0xa000
	global_load_lds_dwordx4 v198, s[12:13]
	v_lshl_add_u64 v[8:9], s[12:13], 0, v[202:203]
	s_add_u32 s12, s46, 0x9000
	s_mov_b32 m0, s82
	s_addc_u32 s13, s47, 0
	global_load_lds_dwordx4 v[8:9], off
	s_add_i32 m0, s74, 0x1c000
	s_nop 0
	global_load_lds_dwordx4 v200, s[12:13]
	s_add_i32 m0, s74, 0x1e000
	v_lshlrev_b32_e32 v10, 2, v218
	global_load_lds_dwordx4 v204, s[12:13]
	v_bfe_u32 v9, v218, 4, 2
	v_and_b32_e32 v8, 15, v218
	v_lshlrev_b32_e32 v220, 4, v9
	v_lshlrev_b32_e32 v219, 3, v9
	v_lshl_or_b32 v9, v8, 6, v220
	v_and_b32_e32 v10, 32, v10
	s_lshl_b32 s1, s1, 2
	s_sext_i32_i8 s27, s4
	v_bitop3_b32 v11, v9, s5, v10 bitop3:0xde
	v_lshlrev_b32_e32 v9, 6, v218
	s_movk_i32 s4, 0x3c0
	s_or_b32 s1, s1, s80
	s_lshl_b64 s[12:13], s[8:9], 7
	v_and_or_b32 v9, v9, s4, v220
	s_cmpk_lt_u32 s0, 0x100
	v_bitop3_b32 v221, s14, v9, v10 bitop3:0xf6
	s_cselect_b64 s[14:15], -1, 0
	s_ashr_i32 s8, s33, 31
	s_add_u32 s0, s38, s12
	s_mul_i32 s4, s1, 0x900
	v_lshlrev_b32_e32 v206, 4, v1
	v_mov_b32_e32 v207, v2
	s_addc_u32 s1, s39, s13
	v_lshl_add_u64 v[208:209], s[0:1], 0, v[206:207]
	s_add_i32 s0, s4, 0
	v_and_b32_e32 v222, 0x70, v5
	s_add_i32 s0, s0, 0x20000
	v_and_b32_e32 v5, 0x3800, v5
	v_lshlrev_b32_e32 v6, 7, v6
	s_movk_i32 s1, 0x90
	v_mov_b32_e32 v10, s0
	v_or3_b32 v5, v3, v5, v6
	v_mad_u32_u24 v223, v8, s1, v10
	v_add_u32_e32 v8, v5, v4
	v_and_b32_e32 v5, 0x7800, v7
	s_waitcnt vmcnt(6)
	v_lshrrev_b32_e32 v9, 3, v1
	v_or3_b32 v3, v3, v5, v6
	v_mad_u32_u24 v224, v9, s1, v10
	s_add_u32 s16, s42, 0x1000
	v_mov_b32_e32 v9, v2
	s_mov_b64 s[0:1], 0xc000
	v_add_u32_e32 v4, v3, v4
	v_mov_b32_e32 v5, v2
	s_addc_u32 s17, s43, 0
	v_lshl_add_u64 v[210:211], v[8:9], 0, s[0:1]
	v_lshl_add_u64 v[212:213], v[4:5], 0, s[0:1]
	v_mov_b64_e32 v[214:215], 0x400
	v_mov_b64_e32 v[216:217], 0x3ff
	s_movk_i32 s83, 0x44
	s_movk_i32 s84, 0x1000
	s_mov_b32 s85, 0xc1f00000
	s_movk_i32 s86, 0x5000
	s_add_i32 s87, 0, 0x10000
	s_add_i32 s88, 0, 0x14000
	v_add_u32_e32 v225, 0, v11
	v_mov_b32_e32 v226, 0x41f00000
	s_barrier
	s_branch .LBB0_373

; #define PG8_STAGE(bufoff, gbase, voff) do { _Pragma("unroll") for (int _i = 0; _i < 2; ++_i) \
;         __builtin_amdgcn_global_load_lds((const unsigned*)((const char*)(gbase) + (voff)[_i]), (PG8_LAS unsigned*)(lds + (bufoff) + ldsw + _i * 8192), 16, 0, 0); } while (0)
; #define PG8_LDA(dst, b, h) do { _Pragma("unroll") for (int m = 0; m < 4; ++m) _Pragma("unroll") for (int k = 0; k < 2; ++k) dst[m][k] = *(const PG8_LAS bf16x8*)(lds + PG8_SA(b, h) + aoff + m * 2048 + k * 1024); } while (0)
; #define PG8_LDB(dst, b, h) do { _Pragma("unroll") for (int n = 0; n < 2; ++n) _Pragma("unroll") for (int k = 0; k < 2; ++k) dst[n][k] = *(const PG8_LAS bf16x8*)(lds + PG8_SB(b, h) + boff + n * 2048 + k * 1024); } while (0)
; #define PG8_MMA(ai, bj, At, Bt) do { __builtin_amdgcn_s_setprio(1); _Pragma("unroll") for (int m = 0; m < 4; ++m) _Pragma("unroll") for (int n = 0; n < 2; ++n) _Pragma("unroll") for (int k = 0; k < 2; ++k) \
;         acc[ai][bj][m][n] = __builtin_amdgcn_mfma_f32_16x16x32_bf16(Bt[n][k], At[m][k], acc[ai][bj][m][n], 0, 0, 0); __builtin_amdgcn_s_setprio(0); } while (0)
; #define PG8_WAIT_V(n) asm volatile("s_waitcnt vmcnt(" #n ")" ::: "memory")
; #define PG8_WAIT_L(n) asm volatile("s_waitcnt lgkmcnt(" #n ")" ::: "memory")
; #define PG8_BAR __builtin_amdgcn_s_barrier()
; template <class Epi, class Sched, bool ALIGN_EPI = false, bool SP2 = false>
; __device__ __forceinline__ void gemm_phase(PG8_LAS unsigned char* lds, const Gemm g, const Sched& S, const Epi& E) {
;     ...
;             const char* a1 = cA + (size_t)(t + 1) * kstep;
;             const char* a2 = last ? nA : cA + (size_t)(t + 2) * kstep; const char* b2 = last ? nB : cB + (size_t)(t + 2) * kstep;
;             const char* a3 = a2 + kstep; const char* b3 = b2 + kstep;
;             if (last && has_next) S.a_ready(nxt);
;             if constexpr (SP2) {
;             PG8_LDB(B0, 0, 0); PG8_LDB(B1, 0, 1); PG8_SCHED; PG8_LDA(At, 0, 0); PG8_STAGE(PG8_SA(1, 1), a1 + hstep, voffA);
;             PG8_WAIT_V(8); PG8_WAIT_L(0); PG8_BAR; PG8_MMA(0, 0, At, B0); PG8_MMA(0, 1, At, B1); PG8_BAR; PG8_SCHED;
;             PG8_LDA(At, 0, 1); PG8_STAGE(PG8_SB(0, 0), b2, voffB); PG8_STAGE(PG8_SB(0, 1), b2 + hstepB, voffB); PG8_STAGE(PG8_SA(0, 0), a2, voffA);
;             PG8_WAIT_V(8); PG8_WAIT_L(0); PG8_BAR; PG8_MMA(1, 0, At, B0); PG8_MMA(1, 1, At, B1); PG8_BAR; PG8_SCHED;
.LBB0_380:
	s_add_u32 s48, s28, s46
	v_add_u32_e32 v3, s87, v221
	s_addc_u32 s49, s29, s47
	ds_read_b128 v[134:137], v3
	ds_read_b128 v[138:141], v3 offset:1024
	ds_read_b128 v[142:145], v3 offset:2048
	ds_read_b128 v[146:149], v3 offset:3072
	v_add_u32_e32 v3, s88, v221
	s_add_u32 s48, s48, 0x10000
	ds_read_b128 v[150:153], v3
	ds_read_b128 v[154:157], v3 offset:1024
	ds_read_b128 v[158:161], v3 offset:2048
	ds_read_b128 v[162:165], v3 offset:3072
	s_addc_u32 s49, s49, 0
	s_add_u32 s50, s27, s46
	s_addc_u32 s51, s45, s47
	s_cmp_eq_u32 s46, 0x70000
	s_cselect_b32 s70, s1, s48
	s_cselect_b32 s71, s0, s49
	s_cselect_b32 s50, s21, s50
	s_cselect_b32 s51, s19, s51
	s_add_u32 s48, s70, 0x8000
	s_addc_u32 s49, s71, 0
	v_lshl_add_u64 v[4:5], v[182:183], 0, s[46:47]
	s_add_i32 m0, s74, 0xc000
	ds_read_b128 v[166:169], v225
	ds_read_b128 v[170:173], v225 offset:1024
	ds_read_b128 v[174:177], v225 offset:2048
	ds_read_b128 v[178:181], v225 offset:3072
	ds_read_b128 v[186:189], v225 offset:4096
	ds_read_b128 v[190:193], v225 offset:5120
	ds_read_b128 v[194:197], v225 offset:6144
	ds_read_b128 v[228:231], v225 offset:7168
	global_load_lds_dwordx4 v[4:5], off
	v_lshl_add_u64 v[4:5], v[184:185], 0, s[46:47]
	s_add_i32 m0, s74, 0xe000
	s_nop 0
	global_load_lds_dwordx4 v[4:5], off
	s_waitcnt vmcnt(8)
	s_waitcnt lgkmcnt(0)
	s_setprio 1
	s_barrier
	v_mfma_f32_16x16x32_bf16 v[130:133], v[134:137], v[166:169], v[130:133]
	v_mfma_f32_16x16x32_bf16 v[126:129], v[142:145], v[166:169], v[126:129]
	v_mfma_f32_16x16x32_bf16 v[114:117], v[134:137], v[174:177], v[114:117]
	v_mfma_f32_16x16x32_bf16 v[110:113], v[142:145], v[174:177], v[110:113]
	v_mfma_f32_16x16x32_bf16 v[98:101], v[134:137], v[186:189], v[98:101]
	v_mfma_f32_16x16x32_bf16 v[94:97], v[142:145], v[186:189], v[94:97]
	v_mfma_f32_16x16x32_bf16 v[82:85], v[134:137], v[194:197], v[82:85]
	v_mfma_f32_16x16x32_bf16 v[78:81], v[142:145], v[194:197], v[78:81]
	v_mfma_f32_16x16x32_bf16 v[130:133], v[138:141], v[170:173], v[130:133]
	v_mfma_f32_16x16x32_bf16 v[126:129], v[146:149], v[170:173], v[126:129]
	v_mfma_f32_16x16x32_bf16 v[114:117], v[138:141], v[178:181], v[114:117]
	v_mfma_f32_16x16x32_bf16 v[110:113], v[146:149], v[178:181], v[110:113]
	v_mfma_f32_16x16x32_bf16 v[98:101], v[138:141], v[190:193], v[98:101]
	v_mfma_f32_16x16x32_bf16 v[94:97], v[146:149], v[190:193], v[94:97]
	v_mfma_f32_16x16x32_bf16 v[82:85], v[138:141], v[228:231], v[82:85]
	v_mfma_f32_16x16x32_bf16 v[78:81], v[146:149], v[228:231], v[78:81]
	s_setprio 0
	s_setprio 1
	v_mfma_f32_16x16x32_bf16 v[122:125], v[150:153], v[166:169], v[122:125]
	v_mfma_f32_16x16x32_bf16 v[118:121], v[158:161], v[166:169], v[118:121]
	v_mfma_f32_16x16x32_bf16 v[106:109], v[150:153], v[174:177], v[106:109]
	v_mfma_f32_16x16x32_bf16 v[102:105], v[158:161], v[174:177], v[102:105]
	v_mfma_f32_16x16x32_bf16 v[90:93], v[150:153], v[186:189], v[90:93]
	v_mfma_f32_16x16x32_bf16 v[86:89], v[158:161], v[186:189], v[86:89]
	v_mfma_f32_16x16x32_bf16 v[74:77], v[150:153], v[194:197], v[74:77]
	v_mfma_f32_16x16x32_bf16 v[70:73], v[158:161], v[194:197], v[70:73]
	v_mfma_f32_16x16x32_bf16 v[122:125], v[154:157], v[170:173], v[122:125]
	v_mfma_f32_16x16x32_bf16 v[118:121], v[162:165], v[170:173], v[118:121]
	v_mfma_f32_16x16x32_bf16 v[106:109], v[154:157], v[178:181], v[106:109]
	v_mfma_f32_16x16x32_bf16 v[102:105], v[162:165], v[178:181], v[102:105]
	v_mfma_f32_16x16x32_bf16 v[90:93], v[154:157], v[190:193], v[90:93]
	v_mfma_f32_16x16x32_bf16 v[86:89], v[162:165], v[190:193], v[86:89]
	v_mfma_f32_16x16x32_bf16 v[74:77], v[154:157], v[228:231], v[74:77]
	v_mfma_f32_16x16x32_bf16 v[70:73], v[162:165], v[228:231], v[70:73]
	s_barrier
	s_setprio 0
	s_add_i32 s52, s87, s73
	s_mov_b32 m0, s52
	ds_read_b128 v[166:169], v225 offset:16384
	ds_read_b128 v[170:173], v225 offset:17408
	ds_read_b128 v[174:177], v225 offset:18432
	ds_read_b128 v[178:181], v225 offset:19456
	ds_read_b128 v[186:189], v225 offset:20480
	ds_read_b128 v[190:193], v225 offset:21504
	ds_read_b128 v[194:197], v225 offset:22528
	ds_read_b128 v[228:231], v225 offset:23552
	global_load_lds_dwordx4 v200, s[50:51]
	s_add_i32 m0, s52, 0x2000
	s_add_u32 s52, s50, 0x1000
	s_addc_u32 s53, s51, 0
	s_add_i32 s54, s88, s73
	global_load_lds_dwordx4 v204, s[50:51]
	s_mov_b32 m0, s54
	s_nop 0
	global_load_lds_dwordx4 v200, s[52:53]
	s_add_i32 m0, s54, 0x2000
	s_nop 0
	global_load_lds_dwordx4 v204, s[52:53]
	s_mov_b32 m0, s74
	s_nop 0
	global_load_lds_dwordx4 v198, s[70:71]
	s_mov_b32 m0, s75
	s_nop 0
	global_load_lds_dwordx4 v202, s[70:71]
	s_waitcnt vmcnt(8)
	s_waitcnt lgkmcnt(0)
	s_setprio 1
	s_barrier
; #define PG8_STAGE(bufoff, gbase, voff) do { _Pragma("unroll") for (int _i = 0; _i < 2; ++_i) \
;         __builtin_amdgcn_global_load_lds((const unsigned*)((const char*)(gbase) + (voff)[_i]), (PG8_LAS unsigned*)(lds + (bufoff) + ldsw + _i * 8192), 16, 0, 0); } while (0)
; #define PG8_LDA(dst, b, h) do { _Pragma("unroll") for (int m = 0; m < 4; ++m) _Pragma("unroll") for (int k = 0; k < 2; ++k) dst[m][k] = *(const PG8_LAS bf16x8*)(lds + PG8_SA(b, h) + aoff + m * 2048 + k * 1024); } while (0)
; #define PG8_LDB(dst, b, h) do { _Pragma("unroll") for (int n = 0; n < 2; ++n) _Pragma("unroll") for (int k = 0; k < 2; ++k) dst[n][k] = *(const PG8_LAS bf16x8*)(lds + PG8_SB(b, h) + boff + n * 2048 + k * 1024); } while (0)
; #define PG8_MMA(ai, bj, At, Bt) do { __builtin_amdgcn_s_setprio(1); _Pragma("unroll") for (int m = 0; m < 4; ++m) _Pragma("unroll") for (int n = 0; n < 2; ++n) _Pragma("unroll") for (int k = 0; k < 2; ++k) \
;         acc[ai][bj][m][n] = __builtin_amdgcn_mfma_f32_16x16x32_bf16(Bt[n][k], At[m][k], acc[ai][bj][m][n], 0, 0, 0); __builtin_amdgcn_s_setprio(0); } while (0)
; #define PG8_WAIT_V(n) asm volatile("s_waitcnt vmcnt(" #n ")" ::: "memory")
; #define PG8_WAIT_L(n) asm volatile("s_waitcnt lgkmcnt(" #n ")" ::: "memory")
; #define PG8_BAR __builtin_amdgcn_s_barrier()
; #define PG8_SCHED __builtin_amdgcn_sched_barrier(0)
; template <class Epi, class Sched, bool ALIGN_EPI = false, bool SP2 = false>
; __device__ __forceinline__ void gemm_phase(PG8_LAS unsigned char* lds, const Gemm g, const Sched& S, const Epi& E) {
;     ...
;             PG8_WAIT_V(8); PG8_WAIT_L(0); PG8_BAR; PG8_MMA(1, 0, At, B0); PG8_MMA(1, 1, At, B1); PG8_BAR; PG8_SCHED;
;             PG8_LDB(B0, 1, 0); PG8_LDB(B1, 1, 1); PG8_SCHED; PG8_LDA(At, 1, 0); PG8_STAGE(PG8_SA(0, 1), a2 + hstep, voffA);
;             PG8_WAIT_V(8); PG8_WAIT_L(0); PG8_BAR; PG8_MMA(0, 0, At, B0); PG8_MMA(0, 1, At, B1); PG8_BAR; PG8_SCHED;
	v_mfma_f32_16x16x32_bf16 v[66:69], v[134:137], v[166:169], v[66:69]
	v_mfma_f32_16x16x32_bf16 v[62:65], v[142:145], v[166:169], v[62:65]
	v_mfma_f32_16x16x32_bf16 v[50:53], v[134:137], v[174:177], v[50:53]
	v_mfma_f32_16x16x32_bf16 v[46:49], v[142:145], v[174:177], v[46:49]
	v_mfma_f32_16x16x32_bf16 v[34:37], v[134:137], v[186:189], v[34:37]
	v_mfma_f32_16x16x32_bf16 v[30:33], v[142:145], v[186:189], v[30:33]
	v_mfma_f32_16x16x32_bf16 v[18:21], v[134:137], v[194:197], v[18:21]
	v_mfma_f32_16x16x32_bf16 v[14:17], v[142:145], v[194:197], v[14:17]
	v_mfma_f32_16x16x32_bf16 v[66:69], v[138:141], v[170:173], v[66:69]
	v_mfma_f32_16x16x32_bf16 v[62:65], v[146:149], v[170:173], v[62:65]
	v_mfma_f32_16x16x32_bf16 v[50:53], v[138:141], v[178:181], v[50:53]
	v_mfma_f32_16x16x32_bf16 v[46:49], v[146:149], v[178:181], v[46:49]
	v_mfma_f32_16x16x32_bf16 v[34:37], v[138:141], v[190:193], v[34:37]
	v_mfma_f32_16x16x32_bf16 v[30:33], v[146:149], v[190:193], v[30:33]
	v_mfma_f32_16x16x32_bf16 v[18:21], v[138:141], v[228:231], v[18:21]
	v_mfma_f32_16x16x32_bf16 v[14:17], v[146:149], v[228:231], v[14:17]
	s_setprio 0
	s_setprio 1
	v_mfma_f32_16x16x32_bf16 v[58:61], v[150:153], v[166:169], v[58:61]
	v_mfma_f32_16x16x32_bf16 v[54:57], v[158:161], v[166:169], v[54:57]
	v_mfma_f32_16x16x32_bf16 v[42:45], v[150:153], v[174:177], v[42:45]
	v_mfma_f32_16x16x32_bf16 v[38:41], v[158:161], v[174:177], v[38:41]
	v_mfma_f32_16x16x32_bf16 v[26:29], v[150:153], v[186:189], v[26:29]
	v_mfma_f32_16x16x32_bf16 v[22:25], v[158:161], v[186:189], v[22:25]
	v_mfma_f32_16x16x32_bf16 v[10:13], v[150:153], v[194:197], v[10:13]
	v_mfma_f32_16x16x32_bf16 v[4:7], v[158:161], v[194:197], v[6:9]
	v_mfma_f32_16x16x32_bf16 v[58:61], v[154:157], v[170:173], v[58:61]
	v_mfma_f32_16x16x32_bf16 v[54:57], v[162:165], v[170:173], v[54:57]
	v_mfma_f32_16x16x32_bf16 v[42:45], v[154:157], v[178:181], v[42:45]
	v_mfma_f32_16x16x32_bf16 v[38:41], v[162:165], v[178:181], v[38:41]
	v_mfma_f32_16x16x32_bf16 v[26:29], v[154:157], v[190:193], v[26:29]
	v_mfma_f32_16x16x32_bf16 v[22:25], v[162:165], v[190:193], v[22:25]
	v_mfma_f32_16x16x32_bf16 v[10:13], v[154:157], v[228:231], v[10:13]
	v_mfma_f32_16x16x32_bf16 v[4:7], v[162:165], v[228:231], v[4:7]
	s_barrier
	s_setprio 0
	s_add_i32 s54, 0, 0x18000
	v_add_u32_e32 v3, s54, v221
	s_add_i32 s55, 0, 0x1c000
	ds_read_b128 v[134:137], v3
	ds_read_b128 v[138:141], v3 offset:1024
	ds_read_b128 v[142:145], v3 offset:2048
	ds_read_b128 v[146:149], v3 offset:3072
	v_add_u32_e32 v3, s55, v221
	ds_read_b128 v[150:153], v3
	ds_read_b128 v[154:157], v3 offset:1024
	ds_read_b128 v[158:161], v3 offset:2048
	ds_read_b128 v[162:165], v3 offset:3072
	s_add_u32 s52, s70, 0x4000
	s_addc_u32 s53, s71, 0
	s_mov_b32 m0, s77
	ds_read_b128 v[166:169], v225 offset:32768
	ds_read_b128 v[170:173], v225 offset:33792
	ds_read_b128 v[174:177], v225 offset:34816
	ds_read_b128 v[178:181], v225 offset:35840
	ds_read_b128 v[186:189], v225 offset:36864
	ds_read_b128 v[190:193], v225 offset:37888
	ds_read_b128 v[194:197], v225 offset:38912
	ds_read_b128 v[228:231], v225 offset:39936
	global_load_lds_dwordx4 v198, s[52:53]
	s_mov_b32 m0, s78
	s_nop 0
	global_load_lds_dwordx4 v202, s[52:53]
	s_waitcnt vmcnt(8)
	s_waitcnt lgkmcnt(0)
	s_setprio 1
	s_barrier
	v_mfma_f32_16x16x32_bf16 v[130:133], v[134:137], v[166:169], v[130:133]
	v_mfma_f32_16x16x32_bf16 v[126:129], v[142:145], v[166:169], v[126:129]
	v_mfma_f32_16x16x32_bf16 v[114:117], v[134:137], v[174:177], v[114:117]
	v_mfma_f32_16x16x32_bf16 v[110:113], v[142:145], v[174:177], v[110:113]
	v_mfma_f32_16x16x32_bf16 v[98:101], v[134:137], v[186:189], v[98:101]
	v_mfma_f32_16x16x32_bf16 v[94:97], v[142:145], v[186:189], v[94:97]
	v_mfma_f32_16x16x32_bf16 v[82:85], v[134:137], v[194:197], v[82:85]
	v_mfma_f32_16x16x32_bf16 v[78:81], v[142:145], v[194:197], v[78:81]
	v_mfma_f32_16x16x32_bf16 v[130:133], v[138:141], v[170:173], v[130:133]
	v_mfma_f32_16x16x32_bf16 v[126:129], v[146:149], v[170:173], v[126:129]
	v_mfma_f32_16x16x32_bf16 v[114:117], v[138:141], v[178:181], v[114:117]
	v_mfma_f32_16x16x32_bf16 v[110:113], v[146:149], v[178:181], v[110:113]
	v_mfma_f32_16x16x32_bf16 v[98:101], v[138:141], v[190:193], v[98:101]
	v_mfma_f32_16x16x32_bf16 v[94:97], v[146:149], v[190:193], v[94:97]
	v_mfma_f32_16x16x32_bf16 v[82:85], v[138:141], v[228:231], v[82:85]
	v_mfma_f32_16x16x32_bf16 v[78:81], v[146:149], v[228:231], v[78:81]
	s_setprio 0
	s_setprio 1
	v_mfma_f32_16x16x32_bf16 v[122:125], v[150:153], v[166:169], v[122:125]
	v_mfma_f32_16x16x32_bf16 v[118:121], v[158:161], v[166:169], v[118:121]
	v_mfma_f32_16x16x32_bf16 v[106:109], v[150:153], v[174:177], v[106:109]
	v_mfma_f32_16x16x32_bf16 v[102:105], v[158:161], v[174:177], v[102:105]
	v_mfma_f32_16x16x32_bf16 v[90:93], v[150:153], v[186:189], v[90:93]
	v_mfma_f32_16x16x32_bf16 v[86:89], v[158:161], v[186:189], v[86:89]
	v_mfma_f32_16x16x32_bf16 v[74:77], v[150:153], v[194:197], v[74:77]
	v_mfma_f32_16x16x32_bf16 v[70:73], v[158:161], v[194:197], v[70:73]
	v_mfma_f32_16x16x32_bf16 v[122:125], v[154:157], v[170:173], v[122:125]
	v_mfma_f32_16x16x32_bf16 v[118:121], v[162:165], v[170:173], v[118:121]
	v_mfma_f32_16x16x32_bf16 v[106:109], v[154:157], v[178:181], v[106:109]
	v_mfma_f32_16x16x32_bf16 v[102:105], v[162:165], v[178:181], v[102:105]
	v_mfma_f32_16x16x32_bf16 v[90:93], v[154:157], v[190:193], v[90:93]
	v_mfma_f32_16x16x32_bf16 v[86:89], v[162:165], v[190:193], v[86:89]
	v_mfma_f32_16x16x32_bf16 v[74:77], v[154:157], v[228:231], v[74:77]
	v_mfma_f32_16x16x32_bf16 v[70:73], v[162:165], v[228:231], v[70:73]
	s_barrier
; #define PG8_STAGE(bufoff, gbase, voff) do { _Pragma("unroll") for (int _i = 0; _i < 2; ++_i) \
;         __builtin_amdgcn_global_load_lds((const unsigned*)((const char*)(gbase) + (voff)[_i]), (PG8_LAS unsigned*)(lds + (bufoff) + ldsw + _i * 8192), 16, 0, 0); } while (0)
; #define PG8_LDA(dst, b, h) do { _Pragma("unroll") for (int m = 0; m < 4; ++m) _Pragma("unroll") for (int k = 0; k < 2; ++k) dst[m][k] = *(const PG8_LAS bf16x8*)(lds + PG8_SA(b, h) + aoff + m * 2048 + k * 1024); } while (0)
; #define PG8_MMA(ai, bj, At, Bt) do { __builtin_amdgcn_s_setprio(1); _Pragma("unroll") for (int m = 0; m < 4; ++m) _Pragma("unroll") for (int n = 0; n < 2; ++n) _Pragma("unroll") for (int k = 0; k < 2; ++k) \
;         acc[ai][bj][m][n] = __builtin_amdgcn_mfma_f32_16x16x32_bf16(Bt[n][k], At[m][k], acc[ai][bj][m][n], 0, 0, 0); __builtin_amdgcn_s_setprio(0); } while (0)
; #define PG8_WAIT_V(n) asm volatile("s_waitcnt vmcnt(" #n ")" ::: "memory")
; #define PG8_WAIT_L(n) asm volatile("s_waitcnt lgkmcnt(" #n ")" ::: "memory")
; #define PG8_BAR __builtin_amdgcn_s_barrier()
; #define PG8_SCHED __builtin_amdgcn_sched_barrier(0)
; template <class Epi, class Sched, bool ALIGN_EPI = false, bool SP2 = false>
; __device__ __forceinline__ void gemm_phase(PG8_LAS unsigned char* lds, const Gemm g, const Sched& S, const Epi& E) {
;     ...
;         for (int t = 0; t < nt; t += 2) {
;     ...
;             PG8_LDA(At, 1, 1); PG8_STAGE(PG8_SB(1, 0), b3, voffB); PG8_STAGE(PG8_SB(1, 1), b3 + hstepB, voffB); PG8_STAGE(PG8_SA(1, 0), a3, voffA);
;             PG8_WAIT_V(8); PG8_WAIT_L(0); PG8_BAR; PG8_MMA(1, 0, At, B0); PG8_MMA(1, 1, At, B1); PG8_BAR; PG8_SCHED;
	s_setprio 0
	s_add_u32 s52, s50, 0x8000
	s_addc_u32 s53, s51, 0
	s_add_i32 s54, s54, s73
	s_mov_b32 m0, s54
	ds_read_b128 v[166:169], v225 offset:49152
	ds_read_b128 v[170:173], v225 offset:50176
	ds_read_b128 v[174:177], v225 offset:51200
	ds_read_b128 v[178:181], v225 offset:52224
	ds_read_b128 v[186:189], v225 offset:53248
	ds_read_b128 v[190:193], v225 offset:54272
	ds_read_b128 v[194:197], v225 offset:55296
	ds_read_b128 v[228:231], v225 offset:56320
	global_load_lds_dwordx4 v200, s[52:53]
	s_add_i32 m0, s54, 0x2000
	s_add_u32 s50, s50, 0x9000
	v_lshl_add_u64 v[8:9], s[52:53], 0, v[204:205]
	s_addc_u32 s51, s51, 0
	s_add_i32 s52, s55, s73
	global_load_lds_dwordx4 v[8:9], off
	s_mov_b32 m0, s52
	s_nop 0
	global_load_lds_dwordx4 v200, s[50:51]
	s_add_i32 m0, s52, 0x2000
	s_nop 0
	global_load_lds_dwordx4 v204, s[50:51]
	s_mov_b32 m0, s81
	s_nop 0
	global_load_lds_dwordx4 v198, s[48:49]
	s_mov_b32 m0, s82
	s_nop 0
	global_load_lds_dwordx4 v202, s[48:49]
	s_waitcnt vmcnt(8)
	s_waitcnt lgkmcnt(0)
	s_setprio 1
	s_barrier
	v_mfma_f32_16x16x32_bf16 v[66:69], v[134:137], v[166:169], v[66:69]
	v_mfma_f32_16x16x32_bf16 v[62:65], v[142:145], v[166:169], v[62:65]
	v_mfma_f32_16x16x32_bf16 v[50:53], v[134:137], v[174:177], v[50:53]
	v_mfma_f32_16x16x32_bf16 v[46:49], v[142:145], v[174:177], v[46:49]
	v_mfma_f32_16x16x32_bf16 v[34:37], v[134:137], v[186:189], v[34:37]
	v_mfma_f32_16x16x32_bf16 v[30:33], v[142:145], v[186:189], v[30:33]
	v_mfma_f32_16x16x32_bf16 v[18:21], v[134:137], v[194:197], v[18:21]
	v_mfma_f32_16x16x32_bf16 v[14:17], v[142:145], v[194:197], v[14:17]
	v_mfma_f32_16x16x32_bf16 v[66:69], v[138:141], v[170:173], v[66:69]
	v_mfma_f32_16x16x32_bf16 v[62:65], v[146:149], v[170:173], v[62:65]
	v_mfma_f32_16x16x32_bf16 v[50:53], v[138:141], v[178:181], v[50:53]
	v_mfma_f32_16x16x32_bf16 v[46:49], v[146:149], v[178:181], v[46:49]
	v_mfma_f32_16x16x32_bf16 v[34:37], v[138:141], v[190:193], v[34:37]
	v_mfma_f32_16x16x32_bf16 v[30:33], v[146:149], v[190:193], v[30:33]
	v_mfma_f32_16x16x32_bf16 v[18:21], v[138:141], v[228:231], v[18:21]
	v_mfma_f32_16x16x32_bf16 v[14:17], v[146:149], v[228:231], v[14:17]
	s_setprio 0
	s_setprio 1
	v_mfma_f32_16x16x32_bf16 v[58:61], v[150:153], v[166:169], v[58:61]
	v_mfma_f32_16x16x32_bf16 v[54:57], v[158:161], v[166:169], v[54:57]
	v_mfma_f32_16x16x32_bf16 v[42:45], v[150:153], v[174:177], v[42:45]
	v_mfma_f32_16x16x32_bf16 v[38:41], v[158:161], v[174:177], v[38:41]
	v_mfma_f32_16x16x32_bf16 v[26:29], v[150:153], v[186:189], v[26:29]
	v_mfma_f32_16x16x32_bf16 v[22:25], v[158:161], v[186:189], v[22:25]
	v_mfma_f32_16x16x32_bf16 v[8:11], v[150:153], v[194:197], v[10:13]
	v_mfma_f32_16x16x32_bf16 v[4:7], v[158:161], v[194:197], v[4:7]
	v_mfma_f32_16x16x32_bf16 v[58:61], v[154:157], v[170:173], v[58:61]
	v_mfma_f32_16x16x32_bf16 v[54:57], v[162:165], v[170:173], v[54:57]
	v_mfma_f32_16x16x32_bf16 v[42:45], v[154:157], v[178:181], v[42:45]
	v_mfma_f32_16x16x32_bf16 v[38:41], v[162:165], v[178:181], v[38:41]
	v_mfma_f32_16x16x32_bf16 v[26:29], v[154:157], v[190:193], v[26:29]
	v_mfma_f32_16x16x32_bf16 v[22:25], v[162:165], v[190:193], v[22:25]
	v_mfma_f32_16x16x32_bf16 v[10:13], v[154:157], v[228:231], v[8:11]
	v_mfma_f32_16x16x32_bf16 v[6:9], v[162:165], v[228:231], v[4:7]
	s_barrier
	s_setprio 0
	s_add_i32 s56, s56, 2
	s_add_u32 s46, s46, 0x10000
	s_addc_u32 s47, s47, 0
	s_cmp_gt_u32 s56, 13
	s_cbranch_scc1 .LBB0_383

; __device__ __forceinline__ size_t tm_block(int pm, int ct, int nct) { return ((size_t)pm * nct + ct) * 32768; }
; #define PG8_STAGE(bufoff, gbase, voff) do { _Pragma("unroll") for (int _i = 0; _i < 2; ++_i) \
;         __builtin_amdgcn_global_load_lds((const unsigned*)((const char*)(gbase) + (voff)[_i]), (PG8_LAS unsigned*)(lds + (bufoff) + ldsw + _i * 8192), 16, 0, 0); } while (0)
; #define PG8_WAIT_V(n) asm volatile("s_waitcnt vmcnt(" #n ")" ::: "memory")
; #define PG8_BAR __builtin_amdgcn_s_barrier()
;     __device__ __forceinline__ void operator()(const f32x4 (&acc)[2][2][4][2], const Unit& u, int wr, int wc, int fr, int fq) const {
;         const int row0 = u.pm * BM + wr * 64 + fr, col0 = u.pn * BM + wc * 64 + 8 * fq;
;         const PieceOut po(scr, X1, tm_block(u.pm, u.pn * 4 + wc, 16), wr, wc, fr, fq);
; #pragma unroll
;         for (int ai = 0; ai < 2; ++ai) {
;             f32x4 xv[4][2][2];
; #pragma unroll
;             for (int m = 0; m < 4; ++m) { const float* xp = x + (size_t)(row0 + ai * HALF + m * 16) * 1024 + col0;
; #pragma unroll
;                 for (int bj = 0; bj < 2; ++bj) { xv[m][bj][0] = *(const f32x4*)(xp + bj * 32); xv[m][bj][1] = *(const f32x4*)(xp + bj * 32 + 4); } }
; template <class Epi, class Sched, bool ALIGN_EPI = false, bool SP2 = false>
; __device__ __forceinline__ void gemm_phase(PG8_LAS unsigned char* lds, const Gemm g, const Sched& S, const Epi& E) {
;     ...
;         PG8_STAGE(PG8_SB(1, 0), cB + kstep, voffB); PG8_STAGE(PG8_SA(1, 0), cA + kstep, voffA); PG8_STAGE(PG8_SB(1, 1), cB + hstepB + kstep, voffB);
;         PG8_WAIT_V(6); PG8_BAR;
.LBB0_467:
	s_and_b32 s58, s5, 3
	s_lshl_b32 s10, s4, 6
	s_lshl_b32 s5, s4, 13
	s_lshl_b32 s15, s58, 12
	s_add_u32 s6, s68, 0x8000
	s_addc_u32 s7, s69, 0
	s_add_i32 m0, s1, 0x18000
	v_lshl_add_u64 v[8:9], s[6:7], 0, v[180:181]
	s_waitcnt vmcnt(2)
	s_barrier
	global_load_lds_dwordx4 v[8:9], off
	s_add_i32 m0, s1, 0x1a000
	v_lshl_add_u64 v[8:9], s[6:7], 0, v[184:185]
	s_add_u32 s6, s50, 0x8000
	s_addc_u32 s7, s51, 0
	s_add_i32 s59, s1, 0x8000
	global_load_lds_dwordx4 v[8:9], off
	s_mov_b32 m0, s59
	s_add_i32 s74, s1, 0xa000
	global_load_lds_dwordx4 v178, s[6:7]
	v_lshl_add_u64 v[8:9], s[6:7], 0, v[182:183]
	s_add_u32 s6, s68, 0x9000
	s_mov_b32 m0, s74
	s_addc_u32 s7, s69, 0
	global_load_lds_dwordx4 v[8:9], off
	s_add_i32 m0, s1, 0x1c000
	s_nop 0
	global_load_lds_dwordx4 v180, s[6:7]
	s_add_i32 m0, s1, 0x1e000
	v_and_b32_e32 v7, 15, v218
	global_load_lds_dwordx4 v184, s[6:7]
	v_bfe_u32 v8, v218, 4, 2
	v_lshlrev_b32_e32 v10, 4, v8
	v_lshlrev_b32_e32 v12, 2, v218
	v_lshl_or_b32 v11, v7, 6, v10
	v_and_b32_e32 v12, 32, v12
	v_bitop3_b32 v11, v11, s5, v12 bitop3:0xde
	v_lshlrev_b32_e32 v13, 6, v218
	s_movk_i32 s5, 0x3c0
	v_and_or_b32 v13, v13, s5, v10
	s_cmpk_lt_u32 s14, 0x100
	v_bitop3_b32 v199, s15, v13, v12 bitop3:0xf6
	s_cselect_b64 s[14:15], -1, 0
	s_lshl_b32 s4, s4, 2
	s_or_b32 s4, s4, s58
	s_mulk_i32 s4, 0x900
	v_and_b32_e32 v12, 0x70, v4
	v_and_b32_e32 v4, 0x3800, v4
	v_lshlrev_b32_e32 v5, 7, v5
	s_add_i32 s4, s4, 0
	v_or3_b32 v4, v2, v4, v5
	v_lshlrev_b32_e32 v9, 3, v8
	s_add_i32 s4, s4, 0x20000
	v_add_u32_e32 v188, v4, v3
	v_and_b32_e32 v4, 0x7800, v6
	s_waitcnt vmcnt(6)
	v_lshl_or_b32 v200, s58, 6, v9
	v_lshrrev_b32_e32 v9, 3, v1
	v_cmp_eq_u32_e64 s[6:7], 0, v8
	s_movk_i32 s5, 0x90
	v_mov_b32_e32 v8, s4
	v_or3_b32 v2, v2, v4, v5
	v_or_b32_e32 v198, s10, v7
	v_mad_u32_u24 v7, v7, s5, v8
	v_mad_u32_u24 v8, v9, s5, v8
	v_add_u32_e32 v190, v2, v3
	s_add_i32 s77, 0, 0x10000
	s_add_i32 s78, 0, 0x14000
	v_mbcnt_lo_u32_b32 v2, -1, 0
	s_lshl_b64 s[16:17], s[10:11], 7
	v_lshlrev_b32_e32 v186, 4, v1
	v_mov_b32_e32 v187, v181
	s_ashr_i32 s10, s33, 31
	s_ashr_i32 s75, s2, 31
	v_mov_b32_e32 v189, v181
	v_mov_b32_e32 v191, v181
	v_mov_b64_e32 v[192:193], 0x400
	v_mov_b64_e32 v[194:195], 0x3ff
	v_add_u32_e32 v201, s77, v199
	v_add_u32_e32 v202, s78, v199
	v_add_u32_e32 v203, 0, v11
	v_mbcnt_hi_u32_b32 v204, -1, v2
	s_mov_b64 s[18:19], 0x80000
	s_mov_b64 s[20:21], 0x90000
	s_mov_b64 s[22:23], 0xa0000
	s_mov_b64 s[24:25], 0xb0000
	v_add_u32_e32 v205, v7, v10
	v_add_u32_e32 v206, v8, v12
	s_barrier
	s_branch .LBB0_470

; #define PG8_STAGE(bufoff, gbase, voff) do { _Pragma("unroll") for (int _i = 0; _i < 2; ++_i) \
;         __builtin_amdgcn_global_load_lds((const unsigned*)((const char*)(gbase) + (voff)[_i]), (PG8_LAS unsigned*)(lds + (bufoff) + ldsw + _i * 8192), 16, 0, 0); } while (0)
; #define PG8_LDA(dst, b, h) do { _Pragma("unroll") for (int m = 0; m < 4; ++m) _Pragma("unroll") for (int k = 0; k < 2; ++k) dst[m][k] = *(const PG8_LAS bf16x8*)(lds + PG8_SA(b, h) + aoff + m * 2048 + k * 1024); } while (0)
; #define PG8_LDB(dst, b, h) do { _Pragma("unroll") for (int n = 0; n < 2; ++n) _Pragma("unroll") for (int k = 0; k < 2; ++k) dst[n][k] = *(const PG8_LAS bf16x8*)(lds + PG8_SB(b, h) + boff + n * 2048 + k * 1024); } while (0)
; #define PG8_MMA(ai, bj, At, Bt) do { __builtin_amdgcn_s_setprio(1); _Pragma("unroll") for (int m = 0; m < 4; ++m) _Pragma("unroll") for (int n = 0; n < 2; ++n) _Pragma("unroll") for (int k = 0; k < 2; ++k) \
;         acc[ai][bj][m][n] = __builtin_amdgcn_mfma_f32_16x16x32_bf16(Bt[n][k], At[m][k], acc[ai][bj][m][n], 0, 0, 0); __builtin_amdgcn_s_setprio(0); } while (0)
; #define PG8_WAIT_V(n) asm volatile("s_waitcnt vmcnt(" #n ")" ::: "memory")
; #define PG8_WAIT_L(n) asm volatile("s_waitcnt lgkmcnt(" #n ")" ::: "memory")
; #define PG8_BAR __builtin_amdgcn_s_barrier()
; template <class Epi, class Sched, bool ALIGN_EPI = false, bool SP2 = false>
; __device__ __forceinline__ void gemm_phase(PG8_LAS unsigned char* lds, const Gemm g, const Sched& S, const Epi& E) {
;     ...
;             const char* a1 = cA + (size_t)(t + 1) * kstep;
;             const char* a2 = last ? nA : cA + (size_t)(t + 2) * kstep; const char* b2 = last ? nB : cB + (size_t)(t + 2) * kstep;
;             const char* a3 = a2 + kstep; const char* b3 = b2 + kstep;
;             if (last && has_next) S.a_ready(nxt);
;             if constexpr (SP2) {
;             PG8_LDB(B0, 0, 0); PG8_LDB(B1, 0, 1); PG8_SCHED; PG8_LDA(At, 0, 0); PG8_STAGE(PG8_SA(1, 1), a1 + hstep, voffA);
;             PG8_WAIT_V(8); PG8_WAIT_L(0); PG8_BAR; PG8_MMA(0, 0, At, B0); PG8_MMA(0, 1, At, B1); PG8_BAR; PG8_SCHED;
;             PG8_LDA(At, 0, 1); PG8_STAGE(PG8_SB(0, 0), b2, voffB); PG8_STAGE(PG8_SB(0, 1), b2 + hstepB, voffB); PG8_STAGE(PG8_SA(0, 0), a2, voffA);
;             PG8_WAIT_V(8); PG8_WAIT_L(0); PG8_BAR; PG8_MMA(1, 0, At, B0); PG8_MMA(1, 1, At, B1); PG8_BAR; PG8_SCHED;
.LBB0_477:
	ds_read_b128 v[130:133], v201
	ds_read_b128 v[134:137], v201 offset:1024
	ds_read_b128 v[138:141], v201 offset:2048
	ds_read_b128 v[142:145], v201 offset:3072
	ds_read_b128 v[146:149], v202
	ds_read_b128 v[150:153], v202 offset:1024
	ds_read_b128 v[154:157], v202 offset:2048
	ds_read_b128 v[158:161], v202 offset:3072
	s_add_u32 s68, s50, 0x4000
	s_addc_u32 s69, s51, 0
	s_cmp_eq_u32 s55, 12
	s_cselect_b32 s72, s47, s68
	s_cselect_b32 s73, s29, s69
	s_cselect_b32 s70, s52, s53
	s_cselect_b32 s71, s27, s54
	s_add_u32 s68, s72, 0x8000
	s_addc_u32 s69, s73, 0
	s_add_i32 m0, s1, 0xc000
	ds_read_b128 v[162:165], v203
	ds_read_b128 v[166:169], v203 offset:1024
	ds_read_b128 v[170:173], v203 offset:2048
	ds_read_b128 v[174:177], v203 offset:3072
	ds_read_b128 v[208:211], v203 offset:4096
	ds_read_b128 v[212:215], v203 offset:5120
	ds_read_b128 v[220:223], v203 offset:6144
	ds_read_b128 v[224:227], v203 offset:7168
	global_load_lds_dwordx4 v188, s[50:51]
	s_add_i32 m0, s1, 0xe000
	s_nop 0
	global_load_lds_dwordx4 v190, s[50:51]
	s_waitcnt vmcnt(8)
	s_waitcnt lgkmcnt(0)
	s_setprio 1
	s_barrier
	v_mfma_f32_16x16x32_bf16 v[126:129], v[130:133], v[162:165], v[126:129]
	v_mfma_f32_16x16x32_bf16 v[122:125], v[138:141], v[162:165], v[122:125]
	v_mfma_f32_16x16x32_bf16 v[110:113], v[130:133], v[170:173], v[110:113]
	v_mfma_f32_16x16x32_bf16 v[106:109], v[138:141], v[170:173], v[106:109]
	v_mfma_f32_16x16x32_bf16 v[94:97], v[130:133], v[208:211], v[94:97]
	v_mfma_f32_16x16x32_bf16 v[90:93], v[138:141], v[208:211], v[90:93]
	v_mfma_f32_16x16x32_bf16 v[78:81], v[130:133], v[220:223], v[78:81]
	v_mfma_f32_16x16x32_bf16 v[74:77], v[138:141], v[220:223], v[74:77]
	v_mfma_f32_16x16x32_bf16 v[126:129], v[134:137], v[166:169], v[126:129]
	v_mfma_f32_16x16x32_bf16 v[122:125], v[142:145], v[166:169], v[122:125]
	v_mfma_f32_16x16x32_bf16 v[110:113], v[134:137], v[174:177], v[110:113]
	v_mfma_f32_16x16x32_bf16 v[106:109], v[142:145], v[174:177], v[106:109]
	v_mfma_f32_16x16x32_bf16 v[94:97], v[134:137], v[212:215], v[94:97]
	v_mfma_f32_16x16x32_bf16 v[90:93], v[142:145], v[212:215], v[90:93]
	v_mfma_f32_16x16x32_bf16 v[78:81], v[134:137], v[224:227], v[78:81]
	v_mfma_f32_16x16x32_bf16 v[74:77], v[142:145], v[224:227], v[74:77]
	s_setprio 0
	s_setprio 1
	v_mfma_f32_16x16x32_bf16 v[118:121], v[146:149], v[162:165], v[118:121]
	v_mfma_f32_16x16x32_bf16 v[114:117], v[154:157], v[162:165], v[114:117]
	v_mfma_f32_16x16x32_bf16 v[102:105], v[146:149], v[170:173], v[102:105]
	v_mfma_f32_16x16x32_bf16 v[98:101], v[154:157], v[170:173], v[98:101]
	v_mfma_f32_16x16x32_bf16 v[86:89], v[146:149], v[208:211], v[86:89]
	v_mfma_f32_16x16x32_bf16 v[82:85], v[154:157], v[208:211], v[82:85]
	v_mfma_f32_16x16x32_bf16 v[70:73], v[146:149], v[220:223], v[70:73]
	v_mfma_f32_16x16x32_bf16 v[66:69], v[154:157], v[220:223], v[66:69]
	v_mfma_f32_16x16x32_bf16 v[118:121], v[150:153], v[166:169], v[118:121]
	v_mfma_f32_16x16x32_bf16 v[114:117], v[158:161], v[166:169], v[114:117]
	v_mfma_f32_16x16x32_bf16 v[102:105], v[150:153], v[174:177], v[102:105]
	v_mfma_f32_16x16x32_bf16 v[98:101], v[158:161], v[174:177], v[98:101]
	v_mfma_f32_16x16x32_bf16 v[86:89], v[150:153], v[212:215], v[86:89]
	v_mfma_f32_16x16x32_bf16 v[82:85], v[158:161], v[212:215], v[82:85]
	v_mfma_f32_16x16x32_bf16 v[70:73], v[150:153], v[224:227], v[70:73]
	v_mfma_f32_16x16x32_bf16 v[66:69], v[158:161], v[224:227], v[66:69]
	s_barrier
	s_setprio 0
	s_add_i32 s79, s77, s0
	s_mov_b32 m0, s79
	ds_read_b128 v[162:165], v203 offset:16384
	ds_read_b128 v[166:169], v203 offset:17408
	ds_read_b128 v[170:173], v203 offset:18432
	ds_read_b128 v[174:177], v203 offset:19456
	ds_read_b128 v[208:211], v203 offset:20480
	ds_read_b128 v[212:215], v203 offset:21504
	ds_read_b128 v[220:223], v203 offset:22528
	ds_read_b128 v[224:227], v203 offset:23552
	global_load_lds_dwordx4 v180, s[70:71]
	s_add_i32 m0, s79, 0x2000
	s_add_u32 s80, s70, 0x1000
	s_addc_u32 s81, s71, 0
	s_add_i32 s79, s78, s0
	global_load_lds_dwordx4 v184, s[70:71]
	s_mov_b32 m0, s79
	s_nop 0
	global_load_lds_dwordx4 v180, s[80:81]
	s_add_i32 m0, s79, 0x2000
	s_nop 0
	global_load_lds_dwordx4 v184, s[80:81]
	s_mov_b32 m0, s1
	s_nop 0
	global_load_lds_dwordx4 v178, s[72:73]
	s_mov_b32 m0, s49
	s_nop 0
	global_load_lds_dwordx4 v182, s[72:73]
	s_waitcnt vmcnt(8)
	s_waitcnt lgkmcnt(0)
	s_setprio 1
	s_barrier
	v_mfma_f32_16x16x32_bf16 v[62:65], v[130:133], v[162:165], v[62:65]
	v_mfma_f32_16x16x32_bf16 v[58:61], v[138:141], v[162:165], v[58:61]
	v_mfma_f32_16x16x32_bf16 v[46:49], v[130:133], v[170:173], v[46:49]
	v_mfma_f32_16x16x32_bf16 v[42:45], v[138:141], v[170:173], v[42:45]
	v_mfma_f32_16x16x32_bf16 v[30:33], v[130:133], v[208:211], v[30:33]
	v_mfma_f32_16x16x32_bf16 v[26:29], v[138:141], v[208:211], v[26:29]
	v_mfma_f32_16x16x32_bf16 v[14:17], v[130:133], v[220:223], v[14:17]
	v_mfma_f32_16x16x32_bf16 v[10:13], v[138:141], v[220:223], v[10:13]
	v_mfma_f32_16x16x32_bf16 v[62:65], v[134:137], v[166:169], v[62:65]
	v_mfma_f32_16x16x32_bf16 v[58:61], v[142:145], v[166:169], v[58:61]
	v_mfma_f32_16x16x32_bf16 v[46:49], v[134:137], v[174:177], v[46:49]
	v_mfma_f32_16x16x32_bf16 v[42:45], v[142:145], v[174:177], v[42:45]
	v_mfma_f32_16x16x32_bf16 v[30:33], v[134:137], v[212:215], v[30:33]
	v_mfma_f32_16x16x32_bf16 v[26:29], v[142:145], v[212:215], v[26:29]
	v_mfma_f32_16x16x32_bf16 v[14:17], v[134:137], v[224:227], v[14:17]
	v_mfma_f32_16x16x32_bf16 v[10:13], v[142:145], v[224:227], v[10:13]
	s_setprio 0
	s_setprio 1
	v_mfma_f32_16x16x32_bf16 v[54:57], v[146:149], v[162:165], v[54:57]
	v_mfma_f32_16x16x32_bf16 v[50:53], v[154:157], v[162:165], v[50:53]
	v_mfma_f32_16x16x32_bf16 v[38:41], v[146:149], v[170:173], v[38:41]
	v_mfma_f32_16x16x32_bf16 v[34:37], v[154:157], v[170:173], v[34:37]
	v_mfma_f32_16x16x32_bf16 v[22:25], v[146:149], v[208:211], v[22:25]
	v_mfma_f32_16x16x32_bf16 v[18:21], v[154:157], v[208:211], v[18:21]
	v_mfma_f32_16x16x32_bf16 v[6:9], v[146:149], v[220:223], v[6:9]
	v_mfma_f32_16x16x32_bf16 v[2:5], v[154:157], v[220:223], v[2:5]
	v_mfma_f32_16x16x32_bf16 v[54:57], v[150:153], v[166:169], v[54:57]
	v_mfma_f32_16x16x32_bf16 v[50:53], v[158:161], v[166:169], v[50:53]
	v_mfma_f32_16x16x32_bf16 v[38:41], v[150:153], v[174:177], v[38:41]
	v_mfma_f32_16x16x32_bf16 v[34:37], v[158:161], v[174:177], v[34:37]
	v_mfma_f32_16x16x32_bf16 v[22:25], v[150:153], v[212:215], v[22:25]
	v_mfma_f32_16x16x32_bf16 v[18:21], v[158:161], v[212:215], v[18:21]
	v_mfma_f32_16x16x32_bf16 v[6:9], v[150:153], v[224:227], v[6:9]
	v_mfma_f32_16x16x32_bf16 v[2:5], v[158:161], v[224:227], v[2:5]
	s_barrier
; #define PG8_STAGE(bufoff, gbase, voff) do { _Pragma("unroll") for (int _i = 0; _i < 2; ++_i) \
;         __builtin_amdgcn_global_load_lds((const unsigned*)((const char*)(gbase) + (voff)[_i]), (PG8_LAS unsigned*)(lds + (bufoff) + ldsw + _i * 8192), 16, 0, 0); } while (0)
; #define PG8_LDA(dst, b, h) do { _Pragma("unroll") for (int m = 0; m < 4; ++m) _Pragma("unroll") for (int k = 0; k < 2; ++k) dst[m][k] = *(const PG8_LAS bf16x8*)(lds + PG8_SA(b, h) + aoff + m * 2048 + k * 1024); } while (0)
; #define PG8_LDB(dst, b, h) do { _Pragma("unroll") for (int n = 0; n < 2; ++n) _Pragma("unroll") for (int k = 0; k < 2; ++k) dst[n][k] = *(const PG8_LAS bf16x8*)(lds + PG8_SB(b, h) + boff + n * 2048 + k * 1024); } while (0)
; #define PG8_MMA(ai, bj, At, Bt) do { __builtin_amdgcn_s_setprio(1); _Pragma("unroll") for (int m = 0; m < 4; ++m) _Pragma("unroll") for (int n = 0; n < 2; ++n) _Pragma("unroll") for (int k = 0; k < 2; ++k) \
;         acc[ai][bj][m][n] = __builtin_amdgcn_mfma_f32_16x16x32_bf16(Bt[n][k], At[m][k], acc[ai][bj][m][n], 0, 0, 0); __builtin_amdgcn_s_setprio(0); } while (0)
; #define PG8_WAIT_V(n) asm volatile("s_waitcnt vmcnt(" #n ")" ::: "memory")
; #define PG8_WAIT_L(n) asm volatile("s_waitcnt lgkmcnt(" #n ")" ::: "memory")
; #define PG8_BAR __builtin_amdgcn_s_barrier()
; #define PG8_SCHED __builtin_amdgcn_sched_barrier(0)
; template <class Epi, class Sched, bool ALIGN_EPI = false, bool SP2 = false>
; __device__ __forceinline__ void gemm_phase(PG8_LAS unsigned char* lds, const Gemm g, const Sched& S, const Epi& E) {
;     ...
;             PG8_LDB(B0, 1, 0); PG8_LDB(B1, 1, 1); PG8_SCHED; PG8_LDA(At, 1, 0); PG8_STAGE(PG8_SA(0, 1), a2 + hstep, voffA);
;             PG8_WAIT_V(8); PG8_WAIT_L(0); PG8_BAR; PG8_MMA(0, 0, At, B0); PG8_MMA(0, 1, At, B1); PG8_BAR; PG8_SCHED;
;             PG8_LDA(At, 1, 1); PG8_STAGE(PG8_SB(1, 0), b3, voffB); PG8_STAGE(PG8_SB(1, 1), b3 + hstepB, voffB); PG8_STAGE(PG8_SA(1, 0), a3, voffA);
;             PG8_WAIT_V(8); PG8_WAIT_L(0); PG8_BAR; PG8_MMA(1, 0, At, B0); PG8_MMA(1, 1, At, B1); PG8_BAR; PG8_SCHED;
;     ...
;         if constexpr (ALIGN_EPI) { if (wr == 0) PG8_BAR; }
	s_setprio 0
	s_add_i32 s79, 0, 0x18000
	s_add_i32 s80, 0, 0x1c000
	v_add_u32_e32 v142, s79, v199
	v_add_u32_e32 v158, s80, v199
	ds_read_b128 v[130:133], v142
	ds_read_b128 v[134:137], v142 offset:1024
	ds_read_b128 v[138:141], v142 offset:2048
	ds_read_b128 v[142:145], v142 offset:3072
	ds_read_b128 v[146:149], v158
	ds_read_b128 v[150:153], v158 offset:1024
	ds_read_b128 v[154:157], v158 offset:2048
	ds_read_b128 v[158:161], v158 offset:3072
	s_add_u32 s72, s72, 0x4000
	s_addc_u32 s73, s73, 0
	s_mov_b32 m0, s56
	ds_read_b128 v[162:165], v203 offset:32768
	ds_read_b128 v[166:169], v203 offset:33792
	ds_read_b128 v[170:173], v203 offset:34816
	ds_read_b128 v[174:177], v203 offset:35840
	ds_read_b128 v[208:211], v203 offset:36864
	ds_read_b128 v[212:215], v203 offset:37888
	ds_read_b128 v[220:223], v203 offset:38912
	ds_read_b128 v[224:227], v203 offset:39936
	global_load_lds_dwordx4 v178, s[72:73]
	s_mov_b32 m0, s57
	s_nop 0
	global_load_lds_dwordx4 v182, s[72:73]
	s_waitcnt vmcnt(8)
	s_waitcnt lgkmcnt(0)
	s_setprio 1
	s_barrier
	v_mfma_f32_16x16x32_bf16 v[126:129], v[130:133], v[162:165], v[126:129]
	v_mfma_f32_16x16x32_bf16 v[122:125], v[138:141], v[162:165], v[122:125]
	v_mfma_f32_16x16x32_bf16 v[110:113], v[130:133], v[170:173], v[110:113]
	v_mfma_f32_16x16x32_bf16 v[106:109], v[138:141], v[170:173], v[106:109]
	v_mfma_f32_16x16x32_bf16 v[94:97], v[130:133], v[208:211], v[94:97]
	v_mfma_f32_16x16x32_bf16 v[90:93], v[138:141], v[208:211], v[90:93]
	v_mfma_f32_16x16x32_bf16 v[78:81], v[130:133], v[220:223], v[78:81]
	v_mfma_f32_16x16x32_bf16 v[74:77], v[138:141], v[220:223], v[74:77]
	v_mfma_f32_16x16x32_bf16 v[126:129], v[134:137], v[166:169], v[126:129]
	v_mfma_f32_16x16x32_bf16 v[122:125], v[142:145], v[166:169], v[122:125]
	v_mfma_f32_16x16x32_bf16 v[110:113], v[134:137], v[174:177], v[110:113]
	v_mfma_f32_16x16x32_bf16 v[106:109], v[142:145], v[174:177], v[106:109]
	v_mfma_f32_16x16x32_bf16 v[94:97], v[134:137], v[212:215], v[94:97]
	v_mfma_f32_16x16x32_bf16 v[90:93], v[142:145], v[212:215], v[90:93]
	v_mfma_f32_16x16x32_bf16 v[78:81], v[134:137], v[224:227], v[78:81]
	v_mfma_f32_16x16x32_bf16 v[74:77], v[142:145], v[224:227], v[74:77]
	s_setprio 0
	s_setprio 1
	v_mfma_f32_16x16x32_bf16 v[118:121], v[146:149], v[162:165], v[118:121]
	v_mfma_f32_16x16x32_bf16 v[114:117], v[154:157], v[162:165], v[114:117]
	v_mfma_f32_16x16x32_bf16 v[102:105], v[146:149], v[170:173], v[102:105]
	v_mfma_f32_16x16x32_bf16 v[98:101], v[154:157], v[170:173], v[98:101]
	v_mfma_f32_16x16x32_bf16 v[86:89], v[146:149], v[208:211], v[86:89]
	v_mfma_f32_16x16x32_bf16 v[82:85], v[154:157], v[208:211], v[82:85]
	v_mfma_f32_16x16x32_bf16 v[70:73], v[146:149], v[220:223], v[70:73]
	v_mfma_f32_16x16x32_bf16 v[66:69], v[154:157], v[220:223], v[66:69]
	v_mfma_f32_16x16x32_bf16 v[118:121], v[150:153], v[166:169], v[118:121]
	v_mfma_f32_16x16x32_bf16 v[114:117], v[158:161], v[166:169], v[114:117]
	v_mfma_f32_16x16x32_bf16 v[102:105], v[150:153], v[174:177], v[102:105]
	v_mfma_f32_16x16x32_bf16 v[98:101], v[158:161], v[174:177], v[98:101]
	v_mfma_f32_16x16x32_bf16 v[86:89], v[150:153], v[212:215], v[86:89]
	v_mfma_f32_16x16x32_bf16 v[82:85], v[158:161], v[212:215], v[82:85]
	v_mfma_f32_16x16x32_bf16 v[70:73], v[150:153], v[224:227], v[70:73]
	v_mfma_f32_16x16x32_bf16 v[66:69], v[158:161], v[224:227], v[66:69]
	s_barrier
	s_setprio 0
	s_add_u32 s72, s70, 0x8000
	s_addc_u32 s73, s71, 0
	s_add_i32 s79, s79, s0
	s_mov_b32 m0, s79
	ds_read_b128 v[162:165], v203 offset:49152
	ds_read_b128 v[166:169], v203 offset:50176
	ds_read_b128 v[170:173], v203 offset:51200
	ds_read_b128 v[174:177], v203 offset:52224
	ds_read_b128 v[208:211], v203 offset:53248
	ds_read_b128 v[212:215], v203 offset:54272
	ds_read_b128 v[220:223], v203 offset:55296
	ds_read_b128 v[224:227], v203 offset:56320
	global_load_lds_dwordx4 v180, s[72:73]
	s_add_i32 m0, s79, 0x2000
	s_add_u32 s70, s70, 0x9000
	v_lshl_add_u64 v[196:197], s[72:73], 0, v[184:185]
	s_addc_u32 s71, s71, 0
	s_add_i32 s72, s80, s0
	global_load_lds_dwordx4 v[196:197], off
	s_mov_b32 m0, s72
	s_nop 0
	global_load_lds_dwordx4 v180, s[70:71]
	s_add_i32 m0, s72, 0x2000
	s_nop 0
	global_load_lds_dwordx4 v184, s[70:71]
	s_mov_b32 m0, s59
	s_nop 0
	global_load_lds_dwordx4 v178, s[68:69]
	s_mov_b32 m0, s74
	s_nop 0
	global_load_lds_dwordx4 v182, s[68:69]
	s_waitcnt vmcnt(8)
	s_waitcnt lgkmcnt(0)
	s_setprio 1
	s_barrier
	v_mfma_f32_16x16x32_bf16 v[62:65], v[130:133], v[162:165], v[62:65]
	v_mfma_f32_16x16x32_bf16 v[58:61], v[138:141], v[162:165], v[58:61]
	v_mfma_f32_16x16x32_bf16 v[46:49], v[130:133], v[170:173], v[46:49]
	v_mfma_f32_16x16x32_bf16 v[42:45], v[138:141], v[170:173], v[42:45]
	v_mfma_f32_16x16x32_bf16 v[30:33], v[130:133], v[208:211], v[30:33]
	v_mfma_f32_16x16x32_bf16 v[26:29], v[138:141], v[208:211], v[26:29]
	v_mfma_f32_16x16x32_bf16 v[14:17], v[130:133], v[220:223], v[14:17]
	v_mfma_f32_16x16x32_bf16 v[10:13], v[138:141], v[220:223], v[10:13]
	v_mfma_f32_16x16x32_bf16 v[62:65], v[134:137], v[166:169], v[62:65]
	v_mfma_f32_16x16x32_bf16 v[58:61], v[142:145], v[166:169], v[58:61]
	v_mfma_f32_16x16x32_bf16 v[46:49], v[134:137], v[174:177], v[46:49]
	v_mfma_f32_16x16x32_bf16 v[42:45], v[142:145], v[174:177], v[42:45]
	v_mfma_f32_16x16x32_bf16 v[30:33], v[134:137], v[212:215], v[30:33]
	v_mfma_f32_16x16x32_bf16 v[26:29], v[142:145], v[212:215], v[26:29]
	v_mfma_f32_16x16x32_bf16 v[14:17], v[134:137], v[224:227], v[14:17]
	v_mfma_f32_16x16x32_bf16 v[10:13], v[142:145], v[224:227], v[10:13]
	s_setprio 0
	s_setprio 1
	v_mfma_f32_16x16x32_bf16 v[54:57], v[146:149], v[162:165], v[54:57]
	v_mfma_f32_16x16x32_bf16 v[50:53], v[154:157], v[162:165], v[50:53]
	v_mfma_f32_16x16x32_bf16 v[38:41], v[146:149], v[170:173], v[38:41]
	v_mfma_f32_16x16x32_bf16 v[34:37], v[154:157], v[170:173], v[34:37]
	v_mfma_f32_16x16x32_bf16 v[22:25], v[146:149], v[208:211], v[22:25]
	v_mfma_f32_16x16x32_bf16 v[18:21], v[154:157], v[208:211], v[18:21]
	v_mfma_f32_16x16x32_bf16 v[6:9], v[146:149], v[220:223], v[6:9]
	v_mfma_f32_16x16x32_bf16 v[2:5], v[154:157], v[220:223], v[2:5]
	v_mfma_f32_16x16x32_bf16 v[54:57], v[150:153], v[166:169], v[54:57]
	v_mfma_f32_16x16x32_bf16 v[50:53], v[158:161], v[166:169], v[50:53]
	v_mfma_f32_16x16x32_bf16 v[38:41], v[150:153], v[174:177], v[38:41]
	v_mfma_f32_16x16x32_bf16 v[34:37], v[158:161], v[174:177], v[34:37]
	v_mfma_f32_16x16x32_bf16 v[22:25], v[150:153], v[212:215], v[22:25]
	v_mfma_f32_16x16x32_bf16 v[18:21], v[158:161], v[212:215], v[18:21]
	v_mfma_f32_16x16x32_bf16 v[6:9], v[150:153], v[224:227], v[6:9]
	v_mfma_f32_16x16x32_bf16 v[2:5], v[158:161], v[224:227], v[2:5]
	s_barrier
	s_setprio 0
	s_add_i32 s55, s55, 2
	s_add_u32 s50, s50, 0x10000
	s_addc_u32 s51, s51, 0
	s_add_u32 s53, s53, 0x10000
	s_addc_u32 s54, s54, 0
	s_cmp_gt_u32 s55, 13
	s_cbranch_scc0 .LBB0_477
	s_and_b64 vcc, exec, s[14:15]
	s_cbranch_vccz .LBB0_480
	s_barrier

; #define PG8_BAR __builtin_amdgcn_s_barrier()
; template <class Epi, class Sched, bool ALIGN_EPI = false, bool SP2 = false>
; __device__ __forceinline__ void gemm_phase(PG8_LAS unsigned char* lds, const Gemm g, const Sched& S, const Epi& E) {
;     ...
;     for (int i = 0; i < 2; ++i) { int R, C; stage_rc(tid * 16 + i * 8192, R, C); const int Rb = Epi::PERM ? (64 * (R >> 5) + perm32(R & 31)) : R;
;         voffA[i] = (unsigned)(R * 64 + C) * 2u; voffB[i] = (unsigned)(Rb * 64 + C) * 2u; }
;     const size_t kstep = (size_t)32768;
;     const size_t hstep = (size_t)HALF * 128;
;     const size_t tstep = (size_t)256 * K * 2; const size_t hstepB = Epi::PERM ? (size_t)32 * 128 : hstep;
;     const unsigned ldsw = (unsigned)wid * 1024u;
;     const int aoff = lds_byte(wr * 64 + fr, fq * 8), boff = lds_byte(wc * 32 + fr, fq * 8);
;     ...
;     Unit cur, nxt; int ui = 0;
;     if (!S.next(0, cur)) return;
;     f32x4 acc[2][2][4][2];
; #pragma unroll
;     for (int a = 0; a < 2; ++a)
; #pragma unroll
;         for (int b = 0; b < 2; ++b)
; #pragma unroll
;             for (int m = 0; m < 4; ++m)
; #pragma unroll
;                 for (int n = 0; n < 2; ++n) acc[a][b][m][n] = (f32x4){0.f, 0.f, 0.f, 0.f};
;     bf16x8 At[4][2], B0[2][2], B1[2][2];
;     const char* cA = (const char*)g.A + (size_t)cur.pm * tstep; const char* cB = (const char*)g.Bt + (size_t)cur.pn * tstep;
;     S.a_ready(cur);
;     float pre_st[8];
;     if constexpr (Epi::HAS_PRE) E.pre(pre_st, cur, wr, wc, fr, fq);
;     if constexpr (SP2) {
;         PG8_STAGE(PG8_SB(0, 0), cB, voffB); PG8_STAGE(PG8_SB(0, 1), cB + hstepB, voffB); PG8_STAGE(PG8_SA(0, 0), cA, voffA); PG8_STAGE(PG8_SA(0, 1), cA + hstep, voffA);
;         if (wr == 1) PG8_BAR;
;         PG8_WAIT_V(2); PG8_BAR;
;         PG8_STAGE(PG8_SB(1, 0), cB + kstep, voffB); PG8_STAGE(PG8_SA(1, 0), cA + kstep, voffA); PG8_STAGE(PG8_SB(1, 1), cB + hstepB + kstep, voffB);
;         PG8_WAIT_V(6); PG8_BAR;
;     } else {
;         PG8_STAGE(PG8_SB(0, 0), cB, voffB); PG8_STAGE(PG8_SA(0, 0), cA, voffA); PG8_STAGE(PG8_SB(0, 1), cB + hstepB, voffB); PG8_STAGE(PG8_SA(0, 1), cA + hstep, voffA);
;         if (wr == 1) PG8_BAR;
;         PG8_WAIT_V(4); PG8_BAR;
;         PG8_STAGE(PG8_SB(1, 0), cB + kstep, voffB); PG8_STAGE(PG8_SA(1, 0), cA + kstep, voffA); PG8_STAGE(PG8_SB(1, 1), cB + hstepB + kstep, voffB);
;         PG8_WAIT_V(6); PG8_BAR;
;     }
;     for (;;) {
.LBB0_576:
	s_and_b32 s48, s13, 3
	s_lshl_b32 s13, s5, 13
	s_lshl_b32 s16, s48, 12
	s_add_u32 s14, s28, 0x8000
	s_addc_u32 s15, s29, 0
	s_add_i32 m0, s3, 0x18000
	v_lshl_add_u64 v[10:11], s[14:15], 0, v[132:133]
	s_waitcnt vmcnt(2)
	s_barrier
	global_load_lds_dwordx4 v[10:11], off
	s_add_i32 m0, s3, 0x1a000
	v_lshl_add_u64 v[10:11], s[14:15], 0, v[136:137]
	s_add_u32 s14, s26, 0x8000
	s_addc_u32 s15, s27, 0
	s_add_i32 s49, s3, 0x8000
	global_load_lds_dwordx4 v[10:11], off
	s_mov_b32 m0, s49
	s_add_i32 s50, s3, 0xa000
	global_load_lds_dwordx4 v130, s[14:15]
	v_lshl_add_u64 v[10:11], s[14:15], 0, v[134:135]
	s_add_u32 s14, s28, 0x9000
	s_mov_b32 m0, s50
	s_addc_u32 s15, s29, 0
	global_load_lds_dwordx4 v[10:11], off
	s_add_i32 m0, s3, 0x1c000
	s_nop 0
	global_load_lds_dwordx4 v132, s[14:15]
	s_add_i32 m0, s3, 0x1e000
	v_or_b32_e32 v3, s8, v9
	global_load_lds_dwordx4 v136, s[14:15]
	s_sext_i32_i8 s25, s4
	v_and_b32_e32 v10, 48, v218
	v_lshlrev_b32_e32 v11, 6, v3
	s_movk_i32 s4, 0x3c0
	v_lshlrev_b32_e32 v3, 2, v3
	v_and_or_b32 v11, v11, s4, v10
	v_and_b32_e32 v3, 32, v3
	v_bitop3_b32 v11, v11, s13, v3 bitop3:0xde
	v_lshlrev_b32_e32 v3, 6, v218
	s_cmpk_lt_u32 s12, 0x100
	v_and_or_b32 v3, v3, s4, v10
	v_lshlrev_b32_e32 v12, 2, v218
	s_cselect_b64 s[12:13], -1, 0
	s_lshl_b32 s4, s5, 2
	v_and_b32_e32 v12, 32, v12
	s_or_b32 s4, s4, s48
	v_bitop3_b32 v151, s16, v3, v12 bitop3:0xf6
	s_mul_i32 s16, s4, 0x900
	s_lshl_b64 s[14:15], s[8:9], 7
	s_ashr_i32 s51, s33, 31
	s_lshl_b32 s4, s8, 2
	s_add_u32 s4, s30, s4
	s_addc_u32 s5, s31, 0
	v_mov_b32_e32 v3, v133
	v_and_b32_e32 v13, 0x70, v6
	v_lshl_add_u64 v[140:141], s[4:5], 0, v[2:3]
	s_add_i32 s4, s16, 0
	v_and_b32_e32 v6, 0x3800, v6
	v_lshlrev_b32_e32 v7, 7, v7
	s_add_i32 s4, s4, 0x20000
	v_or3_b32 v6, v4, v6, v7
	s_waitcnt vmcnt(6)
	v_lshrrev_b32_e32 v12, 3, v1
	s_movk_i32 s5, 0x90
	v_mov_b32_e32 v2, s4
	v_add_u32_e32 v142, v6, v5
	v_and_b32_e32 v6, 0x7800, v8
	v_mad_u32_u24 v3, v9, s5, v2
	v_mad_u32_u24 v2, v12, s5, v2
	v_or3_b32 v4, v4, v6, v7
	s_add_i32 s8, 0, 0x10000
	s_add_i32 s52, 0, 0x14000
	v_lshlrev_b32_e32 v138, 4, v1
	v_mov_b32_e32 v139, v133
	v_mov_b32_e32 v143, v133
	v_add_u32_e32 v144, v4, v5
	v_mov_b32_e32 v145, v133
	v_mov_b64_e32 v[146:147], 0x1000
	v_mov_b64_e32 v[148:149], 0xfff
	v_add_u32_e32 v153, s8, v151
	v_add_u32_e32 v154, s52, v151
	v_add_u32_e32 v155, 0, v11
	v_mov_b32_e32 v156, 0x358637bd
	v_add_u32_e32 v157, v3, v10
	v_add_u32_e32 v158, v2, v13
	s_movk_i32 s53, 0x1000
	s_movk_i32 s54, 0x5000
	s_barrier
	s_branch .LBB0_579

; #define PG8_STAGE(bufoff, gbase, voff) do { _Pragma("unroll") for (int _i = 0; _i < 2; ++_i) \
;         __builtin_amdgcn_global_load_lds((const unsigned*)((const char*)(gbase) + (voff)[_i]), (PG8_LAS unsigned*)(lds + (bufoff) + ldsw + _i * 8192), 16, 0, 0); } while (0)
; #define PG8_LDA(dst, b, h) do { _Pragma("unroll") for (int m = 0; m < 4; ++m) _Pragma("unroll") for (int k = 0; k < 2; ++k) dst[m][k] = *(const PG8_LAS bf16x8*)(lds + PG8_SA(b, h) + aoff + m * 2048 + k * 1024); } while (0)
; #define PG8_LDB(dst, b, h) do { _Pragma("unroll") for (int n = 0; n < 2; ++n) _Pragma("unroll") for (int k = 0; k < 2; ++k) dst[n][k] = *(const PG8_LAS bf16x8*)(lds + PG8_SB(b, h) + boff + n * 2048 + k * 1024); } while (0)
; #define PG8_MMA(ai, bj, At, Bt) do { __builtin_amdgcn_s_setprio(1); _Pragma("unroll") for (int m = 0; m < 4; ++m) _Pragma("unroll") for (int n = 0; n < 2; ++n) _Pragma("unroll") for (int k = 0; k < 2; ++k) \
;         acc[ai][bj][m][n] = __builtin_amdgcn_mfma_f32_16x16x32_bf16(Bt[n][k], At[m][k], acc[ai][bj][m][n], 0, 0, 0); __builtin_amdgcn_s_setprio(0); } while (0)
; #define PG8_BAR __builtin_amdgcn_s_barrier()
; template <class Epi, class Sched, bool ALIGN_EPI = false, bool SP2 = false>
; __device__ __forceinline__ void gemm_phase(PG8_LAS unsigned char* lds, const Gemm g, const Sched& S, const Epi& E) {
;     ...
;         for (int t = 0; t < nt; t += 2) {
;             if constexpr (Epi::HAS_MID) { if (t == (nt >> 1)) E.mid(acc, cur, wr, wc, fr, fq); }
;             const bool last = (t == nt - 2);
;             const char* a1 = cA + (size_t)(t + 1) * kstep;
;             const char* a2 = last ? nA : cA + (size_t)(t + 2) * kstep; const char* b2 = last ? nB : cB + (size_t)(t + 2) * kstep;
;             const char* a3 = a2 + kstep; const char* b3 = b2 + kstep;
;             if (last && has_next) S.a_ready(nxt);
;             if constexpr (SP2) {
;             PG8_LDB(B0, 0, 0); PG8_LDB(B1, 0, 1); PG8_SCHED; PG8_LDA(At, 0, 0); PG8_STAGE(PG8_SA(1, 1), a1 + hstep, voffA);
;             PG8_WAIT_V(8); PG8_WAIT_L(0); PG8_BAR; PG8_MMA(0, 0, At, B0); PG8_MMA(0, 1, At, B1); PG8_BAR; PG8_SCHED;
;             PG8_LDA(At, 0, 1); PG8_STAGE(PG8_SB(0, 0), b2, voffB); PG8_STAGE(PG8_SB(0, 1), b2 + hstepB, voffB); PG8_STAGE(PG8_SA(0, 0), a2, voffA);
;             PG8_WAIT_V(8); PG8_WAIT_L(0); PG8_BAR; PG8_MMA(1, 0, At, B0); PG8_MMA(1, 1, At, B1); PG8_BAR; PG8_SCHED;
.LBB0_586:
	ds_read_b128 v[166:169], v153
	ds_read_b128 v[170:173], v153 offset:1024
	ds_read_b128 v[174:177], v153 offset:2048
	ds_read_b128 v[178:181], v153 offset:3072
	ds_read_b128 v[182:185], v154
	ds_read_b128 v[186:189], v154 offset:1024
	ds_read_b128 v[190:193], v154 offset:2048
	ds_read_b128 v[194:197], v154 offset:3072
	s_add_u32 s28, s26, 0x4000
	s_addc_u32 s29, s27, 0
	s_cmp_eq_u32 s59, 12
	s_cselect_b32 s42, s55, s28
	s_cselect_b32 s43, s19, s29
	s_cselect_b32 s36, s56, s57
	s_cselect_b32 s37, s17, s58
	s_add_u32 s28, s42, 0x8000
	s_addc_u32 s29, s43, 0
	s_add_i32 m0, s3, 0xc000
	ds_read_b128 v[198:201], v155
	ds_read_b128 v[202:205], v155 offset:1024
	ds_read_b128 v[206:209], v155 offset:2048
	ds_read_b128 v[210:213], v155 offset:3072
	ds_read_b128 v[214:217], v155 offset:4096
	ds_read_b128 v[220:223], v155 offset:5120
	ds_read_b128 v[224:227], v155 offset:6144
	ds_read_b128 v[228:231], v155 offset:7168
	global_load_lds_dwordx4 v142, s[26:27]
	s_add_i32 m0, s3, 0xe000
	s_nop 0
	global_load_lds_dwordx4 v144, s[26:27]
	s_waitcnt vmcnt(8)
	s_waitcnt lgkmcnt(0)
	s_setprio 1
	s_barrier
	v_mfma_f32_16x16x32_bf16 v[126:129], v[166:169], v[198:201], v[126:129]
	v_mfma_f32_16x16x32_bf16 v[122:125], v[174:177], v[198:201], v[122:125]
	v_mfma_f32_16x16x32_bf16 v[110:113], v[166:169], v[206:209], v[110:113]
	v_mfma_f32_16x16x32_bf16 v[106:109], v[174:177], v[206:209], v[106:109]
	v_mfma_f32_16x16x32_bf16 v[94:97], v[166:169], v[214:217], v[94:97]
	v_mfma_f32_16x16x32_bf16 v[90:93], v[174:177], v[214:217], v[90:93]
	v_mfma_f32_16x16x32_bf16 v[78:81], v[166:169], v[224:227], v[78:81]
	v_mfma_f32_16x16x32_bf16 v[74:77], v[174:177], v[224:227], v[74:77]
	v_mfma_f32_16x16x32_bf16 v[126:129], v[170:173], v[202:205], v[126:129]
	v_mfma_f32_16x16x32_bf16 v[122:125], v[178:181], v[202:205], v[122:125]
	v_mfma_f32_16x16x32_bf16 v[110:113], v[170:173], v[210:213], v[110:113]
	v_mfma_f32_16x16x32_bf16 v[106:109], v[178:181], v[210:213], v[106:109]
	v_mfma_f32_16x16x32_bf16 v[94:97], v[170:173], v[220:223], v[94:97]
	v_mfma_f32_16x16x32_bf16 v[90:93], v[178:181], v[220:223], v[90:93]
	v_mfma_f32_16x16x32_bf16 v[78:81], v[170:173], v[228:231], v[78:81]
	v_mfma_f32_16x16x32_bf16 v[74:77], v[178:181], v[228:231], v[74:77]
	s_setprio 0
	s_setprio 1
	v_mfma_f32_16x16x32_bf16 v[118:121], v[182:185], v[198:201], v[118:121]
	v_mfma_f32_16x16x32_bf16 v[114:117], v[190:193], v[198:201], v[114:117]
	v_mfma_f32_16x16x32_bf16 v[102:105], v[182:185], v[206:209], v[102:105]
	v_mfma_f32_16x16x32_bf16 v[98:101], v[190:193], v[206:209], v[98:101]
	v_mfma_f32_16x16x32_bf16 v[86:89], v[182:185], v[214:217], v[86:89]
	v_mfma_f32_16x16x32_bf16 v[82:85], v[190:193], v[214:217], v[82:85]
	v_mfma_f32_16x16x32_bf16 v[70:73], v[182:185], v[224:227], v[70:73]
	v_mfma_f32_16x16x32_bf16 v[66:69], v[190:193], v[224:227], v[66:69]
	v_mfma_f32_16x16x32_bf16 v[118:121], v[186:189], v[202:205], v[118:121]
	v_mfma_f32_16x16x32_bf16 v[114:117], v[194:197], v[202:205], v[114:117]
	v_mfma_f32_16x16x32_bf16 v[102:105], v[186:189], v[210:213], v[102:105]
	v_mfma_f32_16x16x32_bf16 v[98:101], v[194:197], v[210:213], v[98:101]
	v_mfma_f32_16x16x32_bf16 v[86:89], v[186:189], v[220:223], v[86:89]
	v_mfma_f32_16x16x32_bf16 v[82:85], v[194:197], v[220:223], v[82:85]
	v_mfma_f32_16x16x32_bf16 v[70:73], v[186:189], v[228:231], v[70:73]
	v_mfma_f32_16x16x32_bf16 v[66:69], v[194:197], v[228:231], v[66:69]
	s_barrier
	s_setprio 0
	s_add_i32 s66, s8, s1
	s_mov_b32 m0, s66
	ds_read_b128 v[198:201], v155 offset:16384
	ds_read_b128 v[202:205], v155 offset:17408
	ds_read_b128 v[206:209], v155 offset:18432
	ds_read_b128 v[210:213], v155 offset:19456
	ds_read_b128 v[214:217], v155 offset:20480
	ds_read_b128 v[220:223], v155 offset:21504
	ds_read_b128 v[224:227], v155 offset:22528
	ds_read_b128 v[228:231], v155 offset:23552
	global_load_lds_dwordx4 v132, s[36:37]
	s_add_i32 m0, s66, 0x2000
	s_add_u32 s66, s36, 0x1000
	s_addc_u32 s67, s37, 0
	s_add_i32 s68, s52, s1
	global_load_lds_dwordx4 v136, s[36:37]
	s_mov_b32 m0, s68
	s_nop 0
	global_load_lds_dwordx4 v132, s[66:67]
	s_add_i32 m0, s68, 0x2000
	s_nop 0
	global_load_lds_dwordx4 v136, s[66:67]
	s_mov_b32 m0, s3
	s_nop 0
	global_load_lds_dwordx4 v130, s[42:43]
	s_mov_b32 m0, s44
	s_nop 0
	global_load_lds_dwordx4 v134, s[42:43]
	s_waitcnt vmcnt(8)
	s_waitcnt lgkmcnt(0)
	s_setprio 1
	s_barrier
	v_mfma_f32_16x16x32_bf16 v[62:65], v[166:169], v[198:201], v[62:65]
	v_mfma_f32_16x16x32_bf16 v[58:61], v[174:177], v[198:201], v[58:61]
	v_mfma_f32_16x16x32_bf16 v[46:49], v[166:169], v[206:209], v[46:49]
	v_mfma_f32_16x16x32_bf16 v[42:45], v[174:177], v[206:209], v[42:45]
	v_mfma_f32_16x16x32_bf16 v[30:33], v[166:169], v[214:217], v[30:33]
	v_mfma_f32_16x16x32_bf16 v[26:29], v[174:177], v[214:217], v[26:29]
	v_mfma_f32_16x16x32_bf16 v[14:17], v[166:169], v[224:227], v[14:17]
	v_mfma_f32_16x16x32_bf16 v[10:13], v[174:177], v[224:227], v[10:13]
	v_mfma_f32_16x16x32_bf16 v[62:65], v[170:173], v[202:205], v[62:65]
	v_mfma_f32_16x16x32_bf16 v[58:61], v[178:181], v[202:205], v[58:61]
	v_mfma_f32_16x16x32_bf16 v[46:49], v[170:173], v[210:213], v[46:49]
	v_mfma_f32_16x16x32_bf16 v[42:45], v[178:181], v[210:213], v[42:45]
	v_mfma_f32_16x16x32_bf16 v[30:33], v[170:173], v[220:223], v[30:33]
	v_mfma_f32_16x16x32_bf16 v[26:29], v[178:181], v[220:223], v[26:29]
	v_mfma_f32_16x16x32_bf16 v[14:17], v[170:173], v[228:231], v[14:17]
	v_mfma_f32_16x16x32_bf16 v[10:13], v[178:181], v[228:231], v[10:13]
	s_setprio 0
	s_setprio 1
	v_mfma_f32_16x16x32_bf16 v[54:57], v[182:185], v[198:201], v[54:57]
	v_mfma_f32_16x16x32_bf16 v[50:53], v[190:193], v[198:201], v[50:53]
	v_mfma_f32_16x16x32_bf16 v[38:41], v[182:185], v[206:209], v[38:41]
	v_mfma_f32_16x16x32_bf16 v[34:37], v[190:193], v[206:209], v[34:37]
	v_mfma_f32_16x16x32_bf16 v[22:25], v[182:185], v[214:217], v[22:25]
	v_mfma_f32_16x16x32_bf16 v[18:21], v[190:193], v[214:217], v[18:21]
	v_mfma_f32_16x16x32_bf16 v[6:9], v[182:185], v[224:227], v[6:9]
	v_mfma_f32_16x16x32_bf16 v[2:5], v[190:193], v[224:227], v[2:5]
	v_mfma_f32_16x16x32_bf16 v[54:57], v[186:189], v[202:205], v[54:57]
	v_mfma_f32_16x16x32_bf16 v[50:53], v[194:197], v[202:205], v[50:53]
	v_mfma_f32_16x16x32_bf16 v[38:41], v[186:189], v[210:213], v[38:41]
	v_mfma_f32_16x16x32_bf16 v[34:37], v[194:197], v[210:213], v[34:37]
	v_mfma_f32_16x16x32_bf16 v[22:25], v[186:189], v[220:223], v[22:25]
	v_mfma_f32_16x16x32_bf16 v[18:21], v[194:197], v[220:223], v[18:21]
	v_mfma_f32_16x16x32_bf16 v[6:9], v[186:189], v[228:231], v[6:9]
	v_mfma_f32_16x16x32_bf16 v[2:5], v[194:197], v[228:231], v[2:5]
	s_barrier
; #define PG8_STAGE(bufoff, gbase, voff) do { _Pragma("unroll") for (int _i = 0; _i < 2; ++_i) \
;         __builtin_amdgcn_global_load_lds((const unsigned*)((const char*)(gbase) + (voff)[_i]), (PG8_LAS unsigned*)(lds + (bufoff) + ldsw + _i * 8192), 16, 0, 0); } while (0)
; #define PG8_LDA(dst, b, h) do { _Pragma("unroll") for (int m = 0; m < 4; ++m) _Pragma("unroll") for (int k = 0; k < 2; ++k) dst[m][k] = *(const PG8_LAS bf16x8*)(lds + PG8_SA(b, h) + aoff + m * 2048 + k * 1024); } while (0)
; #define PG8_LDB(dst, b, h) do { _Pragma("unroll") for (int n = 0; n < 2; ++n) _Pragma("unroll") for (int k = 0; k < 2; ++k) dst[n][k] = *(const PG8_LAS bf16x8*)(lds + PG8_SB(b, h) + boff + n * 2048 + k * 1024); } while (0)
; #define PG8_MMA(ai, bj, At, Bt) do { __builtin_amdgcn_s_setprio(1); _Pragma("unroll") for (int m = 0; m < 4; ++m) _Pragma("unroll") for (int n = 0; n < 2; ++n) _Pragma("unroll") for (int k = 0; k < 2; ++k) \
;         acc[ai][bj][m][n] = __builtin_amdgcn_mfma_f32_16x16x32_bf16(Bt[n][k], At[m][k], acc[ai][bj][m][n], 0, 0, 0); __builtin_amdgcn_s_setprio(0); } while (0)
; #define PG8_WAIT_V(n) asm volatile("s_waitcnt vmcnt(" #n ")" ::: "memory")
; #define PG8_WAIT_L(n) asm volatile("s_waitcnt lgkmcnt(" #n ")" ::: "memory")
; #define PG8_BAR __builtin_amdgcn_s_barrier()
; #define PG8_SCHED __builtin_amdgcn_sched_barrier(0)
; template <class Epi, class Sched, bool ALIGN_EPI = false, bool SP2 = false>
; __device__ __forceinline__ void gemm_phase(PG8_LAS unsigned char* lds, const Gemm g, const Sched& S, const Epi& E) {
;     ...
;             PG8_LDB(B0, 1, 0); PG8_LDB(B1, 1, 1); PG8_SCHED; PG8_LDA(At, 1, 0); PG8_STAGE(PG8_SA(0, 1), a2 + hstep, voffA);
;             PG8_WAIT_V(8); PG8_WAIT_L(0); PG8_BAR; PG8_MMA(0, 0, At, B0); PG8_MMA(0, 1, At, B1); PG8_BAR; PG8_SCHED;
;             PG8_LDA(At, 1, 1); PG8_STAGE(PG8_SB(1, 0), b3, voffB); PG8_STAGE(PG8_SB(1, 1), b3 + hstepB, voffB); PG8_STAGE(PG8_SA(1, 0), a3, voffA);
;             PG8_WAIT_V(8); PG8_WAIT_L(0); PG8_BAR; PG8_MMA(1, 0, At, B0); PG8_MMA(1, 1, At, B1); PG8_BAR; PG8_SCHED;
;     ...
;         if constexpr (ALIGN_EPI) { if (wr == 0) PG8_BAR; }
	s_setprio 0
	s_add_i32 s66, 0, 0x18000
	v_add_u32_e32 v165, s66, v151
	s_add_i32 s67, 0, 0x1c000
	ds_read_b128 v[166:169], v165
	ds_read_b128 v[170:173], v165 offset:1024
	ds_read_b128 v[174:177], v165 offset:2048
	ds_read_b128 v[178:181], v165 offset:3072
	v_add_u32_e32 v165, s67, v151
	ds_read_b128 v[182:185], v165
	ds_read_b128 v[186:189], v165 offset:1024
	ds_read_b128 v[190:193], v165 offset:2048
	ds_read_b128 v[194:197], v165 offset:3072
	s_add_u32 s42, s42, 0x4000
	s_addc_u32 s43, s43, 0
	s_mov_b32 m0, s45
	ds_read_b128 v[198:201], v155 offset:32768
	ds_read_b128 v[202:205], v155 offset:33792
	ds_read_b128 v[206:209], v155 offset:34816
	ds_read_b128 v[210:213], v155 offset:35840
	ds_read_b128 v[214:217], v155 offset:36864
	ds_read_b128 v[220:223], v155 offset:37888
	ds_read_b128 v[224:227], v155 offset:38912
	ds_read_b128 v[228:231], v155 offset:39936
	global_load_lds_dwordx4 v130, s[42:43]
	s_mov_b32 m0, s46
	s_nop 0
	global_load_lds_dwordx4 v134, s[42:43]
	s_waitcnt vmcnt(8)
	s_waitcnt lgkmcnt(0)
	s_setprio 1
	s_barrier
	v_mfma_f32_16x16x32_bf16 v[126:129], v[166:169], v[198:201], v[126:129]
	v_mfma_f32_16x16x32_bf16 v[122:125], v[174:177], v[198:201], v[122:125]
	v_mfma_f32_16x16x32_bf16 v[110:113], v[166:169], v[206:209], v[110:113]
	v_mfma_f32_16x16x32_bf16 v[106:109], v[174:177], v[206:209], v[106:109]
	v_mfma_f32_16x16x32_bf16 v[94:97], v[166:169], v[214:217], v[94:97]
	v_mfma_f32_16x16x32_bf16 v[90:93], v[174:177], v[214:217], v[90:93]
	v_mfma_f32_16x16x32_bf16 v[78:81], v[166:169], v[224:227], v[78:81]
	v_mfma_f32_16x16x32_bf16 v[74:77], v[174:177], v[224:227], v[74:77]
	v_mfma_f32_16x16x32_bf16 v[126:129], v[170:173], v[202:205], v[126:129]
	v_mfma_f32_16x16x32_bf16 v[122:125], v[178:181], v[202:205], v[122:125]
	v_mfma_f32_16x16x32_bf16 v[110:113], v[170:173], v[210:213], v[110:113]
	v_mfma_f32_16x16x32_bf16 v[106:109], v[178:181], v[210:213], v[106:109]
	v_mfma_f32_16x16x32_bf16 v[94:97], v[170:173], v[220:223], v[94:97]
	v_mfma_f32_16x16x32_bf16 v[90:93], v[178:181], v[220:223], v[90:93]
	v_mfma_f32_16x16x32_bf16 v[78:81], v[170:173], v[228:231], v[78:81]
	v_mfma_f32_16x16x32_bf16 v[74:77], v[178:181], v[228:231], v[74:77]
	s_setprio 0
	s_setprio 1
	v_mfma_f32_16x16x32_bf16 v[118:121], v[182:185], v[198:201], v[118:121]
	v_mfma_f32_16x16x32_bf16 v[114:117], v[190:193], v[198:201], v[114:117]
	v_mfma_f32_16x16x32_bf16 v[102:105], v[182:185], v[206:209], v[102:105]
	v_mfma_f32_16x16x32_bf16 v[98:101], v[190:193], v[206:209], v[98:101]
	v_mfma_f32_16x16x32_bf16 v[86:89], v[182:185], v[214:217], v[86:89]
	v_mfma_f32_16x16x32_bf16 v[82:85], v[190:193], v[214:217], v[82:85]
	v_mfma_f32_16x16x32_bf16 v[70:73], v[182:185], v[224:227], v[70:73]
	v_mfma_f32_16x16x32_bf16 v[66:69], v[190:193], v[224:227], v[66:69]
	v_mfma_f32_16x16x32_bf16 v[118:121], v[186:189], v[202:205], v[118:121]
	v_mfma_f32_16x16x32_bf16 v[114:117], v[194:197], v[202:205], v[114:117]
	v_mfma_f32_16x16x32_bf16 v[102:105], v[186:189], v[210:213], v[102:105]
	v_mfma_f32_16x16x32_bf16 v[98:101], v[194:197], v[210:213], v[98:101]
	v_mfma_f32_16x16x32_bf16 v[86:89], v[186:189], v[220:223], v[86:89]
	v_mfma_f32_16x16x32_bf16 v[82:85], v[194:197], v[220:223], v[82:85]
	v_mfma_f32_16x16x32_bf16 v[70:73], v[186:189], v[228:231], v[70:73]
	v_mfma_f32_16x16x32_bf16 v[66:69], v[194:197], v[228:231], v[66:69]
	s_barrier
	s_setprio 0
	s_add_u32 s42, s36, 0x8000
	s_addc_u32 s43, s37, 0
	s_add_i32 s66, s66, s1
	s_mov_b32 m0, s66
	ds_read_b128 v[198:201], v155 offset:49152
	ds_read_b128 v[202:205], v155 offset:50176
	ds_read_b128 v[206:209], v155 offset:51200
	ds_read_b128 v[210:213], v155 offset:52224
	ds_read_b128 v[214:217], v155 offset:53248
	ds_read_b128 v[220:223], v155 offset:54272
	ds_read_b128 v[224:227], v155 offset:55296
	ds_read_b128 v[228:231], v155 offset:56320
	global_load_lds_dwordx4 v132, s[42:43]
	s_add_i32 m0, s66, 0x2000
	s_add_u32 s36, s36, 0x9000
	v_lshl_add_u64 v[232:233], s[42:43], 0, v[136:137]
	s_addc_u32 s37, s37, 0
	s_add_i32 s42, s67, s1
	global_load_lds_dwordx4 v[232:233], off
	s_mov_b32 m0, s42
	s_nop 0
	global_load_lds_dwordx4 v132, s[36:37]
	s_add_i32 m0, s42, 0x2000
	s_nop 0
	global_load_lds_dwordx4 v136, s[36:37]
	s_mov_b32 m0, s49
	s_nop 0
	global_load_lds_dwordx4 v130, s[28:29]
	s_mov_b32 m0, s50
	s_nop 0
	global_load_lds_dwordx4 v134, s[28:29]
	s_waitcnt vmcnt(8)
	s_waitcnt lgkmcnt(0)
	s_setprio 1
	s_barrier
	v_mfma_f32_16x16x32_bf16 v[62:65], v[166:169], v[198:201], v[62:65]
	v_mfma_f32_16x16x32_bf16 v[58:61], v[174:177], v[198:201], v[58:61]
	v_mfma_f32_16x16x32_bf16 v[46:49], v[166:169], v[206:209], v[46:49]
	v_mfma_f32_16x16x32_bf16 v[42:45], v[174:177], v[206:209], v[42:45]
	v_mfma_f32_16x16x32_bf16 v[30:33], v[166:169], v[214:217], v[30:33]
	v_mfma_f32_16x16x32_bf16 v[26:29], v[174:177], v[214:217], v[26:29]
	v_mfma_f32_16x16x32_bf16 v[14:17], v[166:169], v[224:227], v[14:17]
	v_mfma_f32_16x16x32_bf16 v[10:13], v[174:177], v[224:227], v[10:13]
	v_mfma_f32_16x16x32_bf16 v[62:65], v[170:173], v[202:205], v[62:65]
	v_mfma_f32_16x16x32_bf16 v[58:61], v[178:181], v[202:205], v[58:61]
	v_mfma_f32_16x16x32_bf16 v[46:49], v[170:173], v[210:213], v[46:49]
	v_mfma_f32_16x16x32_bf16 v[42:45], v[178:181], v[210:213], v[42:45]
	v_mfma_f32_16x16x32_bf16 v[30:33], v[170:173], v[220:223], v[30:33]
	v_mfma_f32_16x16x32_bf16 v[26:29], v[178:181], v[220:223], v[26:29]
	v_mfma_f32_16x16x32_bf16 v[14:17], v[170:173], v[228:231], v[14:17]
	v_mfma_f32_16x16x32_bf16 v[10:13], v[178:181], v[228:231], v[10:13]
	s_setprio 0
	s_setprio 1
	v_mfma_f32_16x16x32_bf16 v[54:57], v[182:185], v[198:201], v[54:57]
	v_mfma_f32_16x16x32_bf16 v[50:53], v[190:193], v[198:201], v[50:53]
	v_mfma_f32_16x16x32_bf16 v[38:41], v[182:185], v[206:209], v[38:41]
	v_mfma_f32_16x16x32_bf16 v[34:37], v[190:193], v[206:209], v[34:37]
	v_mfma_f32_16x16x32_bf16 v[22:25], v[182:185], v[214:217], v[22:25]
	v_mfma_f32_16x16x32_bf16 v[18:21], v[190:193], v[214:217], v[18:21]
	v_mfma_f32_16x16x32_bf16 v[6:9], v[182:185], v[224:227], v[6:9]
	v_mfma_f32_16x16x32_bf16 v[2:5], v[190:193], v[224:227], v[2:5]
	v_mfma_f32_16x16x32_bf16 v[54:57], v[186:189], v[202:205], v[54:57]
	v_mfma_f32_16x16x32_bf16 v[50:53], v[194:197], v[202:205], v[50:53]
	v_mfma_f32_16x16x32_bf16 v[38:41], v[186:189], v[210:213], v[38:41]
	v_mfma_f32_16x16x32_bf16 v[34:37], v[194:197], v[210:213], v[34:37]
	v_mfma_f32_16x16x32_bf16 v[22:25], v[186:189], v[220:223], v[22:25]
	v_mfma_f32_16x16x32_bf16 v[18:21], v[194:197], v[220:223], v[18:21]
	v_mfma_f32_16x16x32_bf16 v[6:9], v[186:189], v[228:231], v[6:9]
	v_mfma_f32_16x16x32_bf16 v[2:5], v[194:197], v[228:231], v[2:5]
	s_barrier
	s_setprio 0
	s_add_i32 s59, s59, 2
	s_add_u32 s26, s26, 0x10000
	s_addc_u32 s27, s27, 0
	s_add_u32 s57, s57, 0x10000
	s_addc_u32 s58, s58, 0
	s_cmp_gt_u32 s59, 13
	s_cbranch_scc0 .LBB0_586
	s_and_b64 vcc, exec, s[12:13]
	s_cbranch_vccz .LBB0_589
	s_barrier

; #define PG8_BAR __builtin_amdgcn_s_barrier()
; template <class Epi, class Sched, bool ALIGN_EPI = false, bool SP2 = false>
; __device__ __forceinline__ void gemm_phase(PG8_LAS unsigned char* lds, const Gemm g, const Sched& S, const Epi& E) {
;     ...
;     for (int i = 0; i < 2; ++i) { int R, C; stage_rc(tid * 16 + i * 8192, R, C); const int Rb = Epi::PERM ? (64 * (R >> 5) + perm32(R & 31)) : R;
;         voffA[i] = (unsigned)(R * 64 + C) * 2u; voffB[i] = (unsigned)(Rb * 64 + C) * 2u; }
;     const size_t kstep = (size_t)32768;
;     const size_t hstep = (size_t)HALF * 128;
;     const size_t tstep = (size_t)256 * K * 2; const size_t hstepB = Epi::PERM ? (size_t)32 * 128 : hstep;
;     const unsigned ldsw = (unsigned)wid * 1024u;
;     const int aoff = lds_byte(wr * 64 + fr, fq * 8), boff = lds_byte(wc * 32 + fr, fq * 8);
;     ...
;     Unit cur, nxt; int ui = 0;
;     if (!S.next(0, cur)) return;
;     f32x4 acc[2][2][4][2];
; #pragma unroll
;     for (int a = 0; a < 2; ++a)
; #pragma unroll
;         for (int b = 0; b < 2; ++b)
; #pragma unroll
;             for (int m = 0; m < 4; ++m)
; #pragma unroll
;                 for (int n = 0; n < 2; ++n) acc[a][b][m][n] = (f32x4){0.f, 0.f, 0.f, 0.f};
;     bf16x8 At[4][2], B0[2][2], B1[2][2];
;     const char* cA = (const char*)g.A + (size_t)cur.pm * tstep; const char* cB = (const char*)g.Bt + (size_t)cur.pn * tstep;
;     S.a_ready(cur);
;     float pre_st[8];
;     if constexpr (Epi::HAS_PRE) E.pre(pre_st, cur, wr, wc, fr, fq);
;     if constexpr (SP2) {
;         PG8_STAGE(PG8_SB(0, 0), cB, voffB); PG8_STAGE(PG8_SB(0, 1), cB + hstepB, voffB); PG8_STAGE(PG8_SA(0, 0), cA, voffA); PG8_STAGE(PG8_SA(0, 1), cA + hstep, voffA);
;         if (wr == 1) PG8_BAR;
;         PG8_WAIT_V(2); PG8_BAR;
;         PG8_STAGE(PG8_SB(1, 0), cB + kstep, voffB); PG8_STAGE(PG8_SA(1, 0), cA + kstep, voffA); PG8_STAGE(PG8_SB(1, 1), cB + hstepB + kstep, voffB);
;         PG8_WAIT_V(6); PG8_BAR;
;     } else {
;         PG8_STAGE(PG8_SB(0, 0), cB, voffB); PG8_STAGE(PG8_SA(0, 0), cA, voffA); PG8_STAGE(PG8_SB(0, 1), cB + hstepB, voffB); PG8_STAGE(PG8_SA(0, 1), cA + hstep, voffA);
;         if (wr == 1) PG8_BAR;
;         PG8_WAIT_V(4); PG8_BAR;
;         PG8_STAGE(PG8_SB(1, 0), cB + kstep, voffB); PG8_STAGE(PG8_SA(1, 0), cA + kstep, voffA); PG8_STAGE(PG8_SB(1, 1), cB + hstepB + kstep, voffB);
;         PG8_WAIT_V(6); PG8_BAR;
;     }
;     for (;;) {
.LBB0_672:
	s_and_b32 s51, s5, 3
	s_lshl_b32 s14, s4, 6
	s_lshl_b32 s5, s4, 13
	s_lshl_b32 s9, s51, 12
	s_add_u32 s6, s42, 0x8000
	s_addc_u32 s7, s43, 0
	s_add_i32 m0, s1, 0x18000
	v_lshl_add_u64 v[2:3], s[6:7], 0, v[188:189]
	s_waitcnt vmcnt(2)
	s_barrier
	global_load_lds_dwordx4 v[2:3], off
	s_add_i32 m0, s1, 0x1a000
	v_lshl_add_u64 v[2:3], s[6:7], 0, v[192:193]
	s_add_u32 s6, s36, 0x8000
	s_addc_u32 s7, s37, 0
	s_add_i32 s56, s1, 0x8000
	global_load_lds_dwordx4 v[2:3], off
	s_mov_b32 m0, s56
	s_add_i32 s57, s1, 0xa000
	global_load_lds_dwordx4 v186, s[6:7]
	v_lshl_add_u64 v[2:3], s[6:7], 0, v[190:191]
	s_add_u32 s6, s42, 0x9000
	s_mov_b32 m0, s57
	s_addc_u32 s7, s43, 0
	global_load_lds_dwordx4 v[2:3], off
	s_add_i32 m0, s1, 0x1c000
	s_nop 0
	global_load_lds_dwordx4 v188, s[6:7]
	s_add_i32 m0, s1, 0x1e000
	v_lshlrev_b32_e32 v4, 4, v212
	global_load_lds_dwordx4 v192, s[6:7]
	v_lshlrev_b32_e32 v3, 2, v208
	v_lshl_or_b32 v2, v208, 6, v4
	v_and_b32_e32 v3, 32, v3
	s_cmpk_lt_u32 s18, 0x100
	v_bitop3_b32 v5, v2, s5, v3 bitop3:0xde
	v_lshlrev_b32_e32 v2, 6, v218
	s_movk_i32 s5, 0x3c0
	v_lshlrev_b32_e32 v3, 2, v218
	s_cselect_b64 s[18:19], -1, 0
	s_lshl_b32 s4, s4, 2
	v_and_or_b32 v2, v2, s5, v4
	v_and_b32_e32 v3, 32, v3
	s_or_b32 s4, s4, s51
	v_or_b32_e32 v213, s14, v208
	v_bitop3_b32 v214, s9, v2, v3 bitop3:0xf6
	s_mul_i32 s9, s4, 0x900
	s_lshl_b64 s[4:5], s[14:15], 7
	s_ashr_i32 s14, s33, 31
	s_ashr_i32 s58, s2, 31
	s_add_u32 s20, s62, s4
	s_addc_u32 s21, s63, s5
	s_add_u32 s4, s40, s4
	v_lshlrev_b32_e32 v2, 4, v1
	v_mov_b32_e32 v3, v189
	s_addc_u32 s5, s41, s5
	v_lshl_add_u64 v[196:197], s[4:5], 0, v[2:3]
	s_add_i32 s4, s9, 0
	s_add_i32 s4, s4, 0x20000
	v_lshrrev_b32_e32 v6, 3, v1
	v_lshl_add_u64 v[194:195], s[20:21], 0, v[2:3]
	s_movk_i32 s5, 0x90
	v_mov_b32_e32 v2, s4
	v_mad_u32_u24 v3, v208, s5, v2
	v_mad_u32_u24 v2, v6, s5, v2
	v_and_b32_e32 v6, 0x3800, v209
	v_lshlrev_b32_e32 v8, 7, v210
	v_or3_b32 v6, v206, v6, v8
	s_waitcnt vmcnt(6)
	v_add_u32_e32 v198, v6, v207
	v_and_b32_e32 v6, 0x7800, v211
	v_and_b32_e32 v7, 0x70, v209
	v_or3_b32 v6, v206, v6, v8
	s_add_i32 s59, 0, 0x10000
	s_add_i32 s64, 0, 0x14000
	v_add_u32_e32 v217, 0, v5
	v_mbcnt_lo_u32_b32 v5, -1, 0
	v_cmp_eq_u32_e64 s[6:7], 0, v212
	v_mov_b32_e32 v199, v189
	v_add_u32_e32 v200, v6, v207
	v_mov_b32_e32 v201, v189
	v_mov_b64_e32 v[202:203], 0x400
	v_mov_b64_e32 v[204:205], 0x3ff
	v_add_u32_e32 v215, s59, v214
	v_add_u32_e32 v216, s64, v214
	s_movk_i32 s65, 0x1000
	s_movk_i32 s66, 0x5000
	v_mbcnt_hi_u32_b32 v219, -1, v5
	v_add_u32_e32 v220, v2, v7
	v_add_u32_e32 v221, v3, v4
	s_barrier
	s_branch .LBB0_675

; #define PG8_STAGE(bufoff, gbase, voff) do { _Pragma("unroll") for (int _i = 0; _i < 2; ++_i) \
;         __builtin_amdgcn_global_load_lds((const unsigned*)((const char*)(gbase) + (voff)[_i]), (PG8_LAS unsigned*)(lds + (bufoff) + ldsw + _i * 8192), 16, 0, 0); } while (0)
; #define PG8_LDA(dst, b, h) do { _Pragma("unroll") for (int m = 0; m < 4; ++m) _Pragma("unroll") for (int k = 0; k < 2; ++k) dst[m][k] = *(const PG8_LAS bf16x8*)(lds + PG8_SA(b, h) + aoff + m * 2048 + k * 1024); } while (0)
; #define PG8_LDB(dst, b, h) do { _Pragma("unroll") for (int n = 0; n < 2; ++n) _Pragma("unroll") for (int k = 0; k < 2; ++k) dst[n][k] = *(const PG8_LAS bf16x8*)(lds + PG8_SB(b, h) + boff + n * 2048 + k * 1024); } while (0)
; #define PG8_MMA(ai, bj, At, Bt) do { __builtin_amdgcn_s_setprio(1); _Pragma("unroll") for (int m = 0; m < 4; ++m) _Pragma("unroll") for (int n = 0; n < 2; ++n) _Pragma("unroll") for (int k = 0; k < 2; ++k) \
;         acc[ai][bj][m][n] = __builtin_amdgcn_mfma_f32_16x16x32_bf16(Bt[n][k], At[m][k], acc[ai][bj][m][n], 0, 0, 0); __builtin_amdgcn_s_setprio(0); } while (0)
; #define PG8_BAR __builtin_amdgcn_s_barrier()
; template <class Epi, class Sched, bool ALIGN_EPI = false, bool SP2 = false>
; __device__ __forceinline__ void gemm_phase(PG8_LAS unsigned char* lds, const Gemm g, const Sched& S, const Epi& E) {
;     ...
;         for (int t = 0; t < nt; t += 2) {
;             if constexpr (Epi::HAS_MID) { if (t == (nt >> 1)) E.mid(acc, cur, wr, wc, fr, fq); }
;             const bool last = (t == nt - 2);
;             const char* a1 = cA + (size_t)(t + 1) * kstep;
;             const char* a2 = last ? nA : cA + (size_t)(t + 2) * kstep; const char* b2 = last ? nB : cB + (size_t)(t + 2) * kstep;
;             const char* a3 = a2 + kstep; const char* b3 = b2 + kstep;
;             if (last && has_next) S.a_ready(nxt);
;             if constexpr (SP2) {
;             PG8_LDB(B0, 0, 0); PG8_LDB(B1, 0, 1); PG8_SCHED; PG8_LDA(At, 0, 0); PG8_STAGE(PG8_SA(1, 1), a1 + hstep, voffA);
;             PG8_WAIT_V(8); PG8_WAIT_L(0); PG8_BAR; PG8_MMA(0, 0, At, B0); PG8_MMA(0, 1, At, B1); PG8_BAR; PG8_SCHED;
;             PG8_LDA(At, 0, 1); PG8_STAGE(PG8_SB(0, 0), b2, voffB); PG8_STAGE(PG8_SB(0, 1), b2 + hstepB, voffB); PG8_STAGE(PG8_SA(0, 0), a2, voffA);
;             PG8_WAIT_V(8); PG8_WAIT_L(0); PG8_BAR; PG8_MMA(1, 0, At, B0); PG8_MMA(1, 1, At, B1); PG8_BAR; PG8_SCHED;
.LBB0_682:
	ds_read_b128 v[98:101], v215
	ds_read_b128 v[102:105], v215 offset:1024
	ds_read_b128 v[122:125], v215 offset:2048
	ds_read_b128 v[126:129], v215 offset:3072
	ds_read_b128 v[146:149], v216
	ds_read_b128 v[150:153], v216 offset:1024
	ds_read_b128 v[154:157], v216 offset:2048
	ds_read_b128 v[158:161], v216 offset:3072
	s_add_u32 s42, s36, 0x4000
	s_addc_u32 s43, s37, 0
	s_cmp_eq_u32 s54, 60
	s_cselect_b32 s46, s23, s42
	s_cselect_b32 s47, s9, s43
	s_cselect_b32 s44, s29, s52
	s_cselect_b32 s45, s21, s53
	s_add_u32 s42, s46, 0x8000
	s_addc_u32 s43, s47, 0
	s_add_i32 m0, s1, 0xc000
	ds_read_b128 v[162:165], v217
	ds_read_b128 v[166:169], v217 offset:1024
	ds_read_b128 v[170:173], v217 offset:2048
	ds_read_b128 v[174:177], v217 offset:3072
	ds_read_b128 v[178:181], v217 offset:4096
	ds_read_b128 v[182:185], v217 offset:5120
	ds_read_b128 v[222:225], v217 offset:6144
	ds_read_b128 v[226:229], v217 offset:7168
	global_load_lds_dwordx4 v198, s[36:37]
	s_add_i32 m0, s1, 0xe000
	s_nop 0
	global_load_lds_dwordx4 v200, s[36:37]
	s_waitcnt vmcnt(8)
	s_waitcnt lgkmcnt(0)
	s_setprio 1
	s_barrier
	v_mfma_f32_16x16x32_bf16 v[142:145], v[98:101], v[162:165], v[142:145]
	v_mfma_f32_16x16x32_bf16 v[138:141], v[122:125], v[162:165], v[138:141]
	v_mfma_f32_16x16x32_bf16 v[118:121], v[98:101], v[170:173], v[118:121]
	v_mfma_f32_16x16x32_bf16 v[114:117], v[122:125], v[170:173], v[114:117]
	v_mfma_f32_16x16x32_bf16 v[94:97], v[98:101], v[178:181], v[94:97]
	v_mfma_f32_16x16x32_bf16 v[90:93], v[122:125], v[178:181], v[90:93]
	v_mfma_f32_16x16x32_bf16 v[78:81], v[98:101], v[222:225], v[78:81]
	v_mfma_f32_16x16x32_bf16 v[74:77], v[122:125], v[222:225], v[74:77]
	v_mfma_f32_16x16x32_bf16 v[142:145], v[102:105], v[166:169], v[142:145]
	v_mfma_f32_16x16x32_bf16 v[138:141], v[126:129], v[166:169], v[138:141]
	v_mfma_f32_16x16x32_bf16 v[118:121], v[102:105], v[174:177], v[118:121]
	v_mfma_f32_16x16x32_bf16 v[114:117], v[126:129], v[174:177], v[114:117]
	v_mfma_f32_16x16x32_bf16 v[94:97], v[102:105], v[182:185], v[94:97]
	v_mfma_f32_16x16x32_bf16 v[90:93], v[126:129], v[182:185], v[90:93]
	v_mfma_f32_16x16x32_bf16 v[78:81], v[102:105], v[226:229], v[78:81]
	v_mfma_f32_16x16x32_bf16 v[74:77], v[126:129], v[226:229], v[74:77]
	s_setprio 0
	s_setprio 1
	v_mfma_f32_16x16x32_bf16 v[134:137], v[146:149], v[162:165], v[134:137]
	v_mfma_f32_16x16x32_bf16 v[130:133], v[154:157], v[162:165], v[130:133]
	v_mfma_f32_16x16x32_bf16 v[110:113], v[146:149], v[170:173], v[110:113]
	v_mfma_f32_16x16x32_bf16 v[106:109], v[154:157], v[170:173], v[106:109]
	v_mfma_f32_16x16x32_bf16 v[86:89], v[146:149], v[178:181], v[86:89]
	v_mfma_f32_16x16x32_bf16 v[82:85], v[154:157], v[178:181], v[82:85]
	v_mfma_f32_16x16x32_bf16 v[70:73], v[146:149], v[222:225], v[70:73]
	v_mfma_f32_16x16x32_bf16 v[66:69], v[154:157], v[222:225], v[66:69]
	v_mfma_f32_16x16x32_bf16 v[134:137], v[150:153], v[166:169], v[134:137]
	v_mfma_f32_16x16x32_bf16 v[130:133], v[158:161], v[166:169], v[130:133]
	v_mfma_f32_16x16x32_bf16 v[110:113], v[150:153], v[174:177], v[110:113]
	v_mfma_f32_16x16x32_bf16 v[106:109], v[158:161], v[174:177], v[106:109]
	v_mfma_f32_16x16x32_bf16 v[86:89], v[150:153], v[182:185], v[86:89]
	v_mfma_f32_16x16x32_bf16 v[82:85], v[158:161], v[182:185], v[82:85]
	v_mfma_f32_16x16x32_bf16 v[70:73], v[150:153], v[226:229], v[70:73]
	v_mfma_f32_16x16x32_bf16 v[66:69], v[158:161], v[226:229], v[66:69]
	s_barrier
	s_setprio 0
	s_add_i32 s55, s59, s0
	s_mov_b32 m0, s55
	ds_read_b128 v[162:165], v217 offset:16384
	ds_read_b128 v[166:169], v217 offset:17408
	ds_read_b128 v[170:173], v217 offset:18432
	ds_read_b128 v[174:177], v217 offset:19456
	ds_read_b128 v[178:181], v217 offset:20480
	ds_read_b128 v[182:185], v217 offset:21504
	ds_read_b128 v[222:225], v217 offset:22528
	ds_read_b128 v[226:229], v217 offset:23552
	global_load_lds_dwordx4 v188, s[44:45]
	s_add_i32 m0, s55, 0x2000
	s_add_u32 s68, s44, 0x1000
	s_addc_u32 s69, s45, 0
	s_add_i32 s55, s64, s0
	global_load_lds_dwordx4 v192, s[44:45]
	s_mov_b32 m0, s55
	s_nop 0
	global_load_lds_dwordx4 v188, s[68:69]
	s_add_i32 m0, s55, 0x2000
	s_nop 0
	global_load_lds_dwordx4 v192, s[68:69]
	s_mov_b32 m0, s1
	s_nop 0
	global_load_lds_dwordx4 v186, s[46:47]
	s_mov_b32 m0, s3
	s_nop 0
	global_load_lds_dwordx4 v190, s[46:47]
	s_waitcnt vmcnt(8)
	s_waitcnt lgkmcnt(0)
	s_setprio 1
	s_barrier
	v_mfma_f32_16x16x32_bf16 v[62:65], v[98:101], v[162:165], v[62:65]
	v_mfma_f32_16x16x32_bf16 v[58:61], v[122:125], v[162:165], v[58:61]
	v_mfma_f32_16x16x32_bf16 v[46:49], v[98:101], v[170:173], v[46:49]
	v_mfma_f32_16x16x32_bf16 v[42:45], v[122:125], v[170:173], v[42:45]
	v_mfma_f32_16x16x32_bf16 v[30:33], v[98:101], v[178:181], v[30:33]
	v_mfma_f32_16x16x32_bf16 v[26:29], v[122:125], v[178:181], v[26:29]
	v_mfma_f32_16x16x32_bf16 v[14:17], v[98:101], v[222:225], v[14:17]
	v_mfma_f32_16x16x32_bf16 v[10:13], v[122:125], v[222:225], v[10:13]
	v_mfma_f32_16x16x32_bf16 v[62:65], v[102:105], v[166:169], v[62:65]
	v_mfma_f32_16x16x32_bf16 v[58:61], v[126:129], v[166:169], v[58:61]
	v_mfma_f32_16x16x32_bf16 v[46:49], v[102:105], v[174:177], v[46:49]
	v_mfma_f32_16x16x32_bf16 v[42:45], v[126:129], v[174:177], v[42:45]
	v_mfma_f32_16x16x32_bf16 v[30:33], v[102:105], v[182:185], v[30:33]
	v_mfma_f32_16x16x32_bf16 v[26:29], v[126:129], v[182:185], v[26:29]
	v_mfma_f32_16x16x32_bf16 v[14:17], v[102:105], v[226:229], v[14:17]
	v_mfma_f32_16x16x32_bf16 v[10:13], v[126:129], v[226:229], v[10:13]
	s_setprio 0
	s_setprio 1
	v_mfma_f32_16x16x32_bf16 v[54:57], v[146:149], v[162:165], v[54:57]
	v_mfma_f32_16x16x32_bf16 v[50:53], v[154:157], v[162:165], v[50:53]
	v_mfma_f32_16x16x32_bf16 v[38:41], v[146:149], v[170:173], v[38:41]
	v_mfma_f32_16x16x32_bf16 v[34:37], v[154:157], v[170:173], v[34:37]
	v_mfma_f32_16x16x32_bf16 v[22:25], v[146:149], v[178:181], v[22:25]
	v_mfma_f32_16x16x32_bf16 v[18:21], v[154:157], v[178:181], v[18:21]
	v_mfma_f32_16x16x32_bf16 v[6:9], v[146:149], v[222:225], v[6:9]
	v_mfma_f32_16x16x32_bf16 v[2:5], v[154:157], v[222:225], v[2:5]
	v_mfma_f32_16x16x32_bf16 v[54:57], v[150:153], v[166:169], v[54:57]
	v_mfma_f32_16x16x32_bf16 v[50:53], v[158:161], v[166:169], v[50:53]
	v_mfma_f32_16x16x32_bf16 v[38:41], v[150:153], v[174:177], v[38:41]
	v_mfma_f32_16x16x32_bf16 v[34:37], v[158:161], v[174:177], v[34:37]
	v_mfma_f32_16x16x32_bf16 v[22:25], v[150:153], v[182:185], v[22:25]
	v_mfma_f32_16x16x32_bf16 v[18:21], v[158:161], v[182:185], v[18:21]
	v_mfma_f32_16x16x32_bf16 v[6:9], v[150:153], v[226:229], v[6:9]
	v_mfma_f32_16x16x32_bf16 v[2:5], v[158:161], v[226:229], v[2:5]
	s_barrier
; #define PG8_STAGE(bufoff, gbase, voff) do { _Pragma("unroll") for (int _i = 0; _i < 2; ++_i) \
;         __builtin_amdgcn_global_load_lds((const unsigned*)((const char*)(gbase) + (voff)[_i]), (PG8_LAS unsigned*)(lds + (bufoff) + ldsw + _i * 8192), 16, 0, 0); } while (0)
; #define PG8_LDA(dst, b, h) do { _Pragma("unroll") for (int m = 0; m < 4; ++m) _Pragma("unroll") for (int k = 0; k < 2; ++k) dst[m][k] = *(const PG8_LAS bf16x8*)(lds + PG8_SA(b, h) + aoff + m * 2048 + k * 1024); } while (0)
; #define PG8_LDB(dst, b, h) do { _Pragma("unroll") for (int n = 0; n < 2; ++n) _Pragma("unroll") for (int k = 0; k < 2; ++k) dst[n][k] = *(const PG8_LAS bf16x8*)(lds + PG8_SB(b, h) + boff + n * 2048 + k * 1024); } while (0)
; #define PG8_MMA(ai, bj, At, Bt) do { __builtin_amdgcn_s_setprio(1); _Pragma("unroll") for (int m = 0; m < 4; ++m) _Pragma("unroll") for (int n = 0; n < 2; ++n) _Pragma("unroll") for (int k = 0; k < 2; ++k) \
;         acc[ai][bj][m][n] = __builtin_amdgcn_mfma_f32_16x16x32_bf16(Bt[n][k], At[m][k], acc[ai][bj][m][n], 0, 0, 0); __builtin_amdgcn_s_setprio(0); } while (0)
; #define PG8_WAIT_V(n) asm volatile("s_waitcnt vmcnt(" #n ")" ::: "memory")
; #define PG8_WAIT_L(n) asm volatile("s_waitcnt lgkmcnt(" #n ")" ::: "memory")
; #define PG8_BAR __builtin_amdgcn_s_barrier()
; #define PG8_SCHED __builtin_amdgcn_sched_barrier(0)
; template <class Epi, class Sched, bool ALIGN_EPI = false, bool SP2 = false>
; __device__ __forceinline__ void gemm_phase(PG8_LAS unsigned char* lds, const Gemm g, const Sched& S, const Epi& E) {
;     ...
;             PG8_LDB(B0, 1, 0); PG8_LDB(B1, 1, 1); PG8_SCHED; PG8_LDA(At, 1, 0); PG8_STAGE(PG8_SA(0, 1), a2 + hstep, voffA);
;             PG8_WAIT_V(8); PG8_WAIT_L(0); PG8_BAR; PG8_MMA(0, 0, At, B0); PG8_MMA(0, 1, At, B1); PG8_BAR; PG8_SCHED;
;             PG8_LDA(At, 1, 1); PG8_STAGE(PG8_SB(1, 0), b3, voffB); PG8_STAGE(PG8_SB(1, 1), b3 + hstepB, voffB); PG8_STAGE(PG8_SA(1, 0), a3, voffA);
;             PG8_WAIT_V(8); PG8_WAIT_L(0); PG8_BAR; PG8_MMA(1, 0, At, B0); PG8_MMA(1, 1, At, B1); PG8_BAR; PG8_SCHED;
;     ...
;         if constexpr (ALIGN_EPI) { if (wr == 0) PG8_BAR; }
	s_setprio 0
	s_add_i32 s55, 0, 0x18000
	s_add_i32 s67, 0, 0x1c000
	v_add_u32_e32 v126, s55, v214
	v_add_u32_e32 v158, s67, v214
	ds_read_b128 v[98:101], v126
	ds_read_b128 v[102:105], v126 offset:1024
	ds_read_b128 v[122:125], v126 offset:2048
	ds_read_b128 v[126:129], v126 offset:3072
	ds_read_b128 v[146:149], v158
	ds_read_b128 v[150:153], v158 offset:1024
	ds_read_b128 v[154:157], v158 offset:2048
	ds_read_b128 v[158:161], v158 offset:3072
	s_add_u32 s46, s46, 0x4000
	s_addc_u32 s47, s47, 0
	s_mov_b32 m0, s48
	ds_read_b128 v[162:165], v217 offset:32768
	ds_read_b128 v[166:169], v217 offset:33792
	ds_read_b128 v[170:173], v217 offset:34816
	ds_read_b128 v[174:177], v217 offset:35840
	ds_read_b128 v[178:181], v217 offset:36864
	ds_read_b128 v[182:185], v217 offset:37888
	ds_read_b128 v[222:225], v217 offset:38912
	ds_read_b128 v[226:229], v217 offset:39936
	global_load_lds_dwordx4 v186, s[46:47]
	s_mov_b32 m0, s49
	s_nop 0
	global_load_lds_dwordx4 v190, s[46:47]
	s_waitcnt vmcnt(8)
	s_waitcnt lgkmcnt(0)
	s_setprio 1
	s_barrier
	v_mfma_f32_16x16x32_bf16 v[142:145], v[98:101], v[162:165], v[142:145]
	v_mfma_f32_16x16x32_bf16 v[138:141], v[122:125], v[162:165], v[138:141]
	v_mfma_f32_16x16x32_bf16 v[118:121], v[98:101], v[170:173], v[118:121]
	v_mfma_f32_16x16x32_bf16 v[114:117], v[122:125], v[170:173], v[114:117]
	v_mfma_f32_16x16x32_bf16 v[94:97], v[98:101], v[178:181], v[94:97]
	v_mfma_f32_16x16x32_bf16 v[90:93], v[122:125], v[178:181], v[90:93]
	v_mfma_f32_16x16x32_bf16 v[78:81], v[98:101], v[222:225], v[78:81]
	v_mfma_f32_16x16x32_bf16 v[74:77], v[122:125], v[222:225], v[74:77]
	v_mfma_f32_16x16x32_bf16 v[142:145], v[102:105], v[166:169], v[142:145]
	v_mfma_f32_16x16x32_bf16 v[138:141], v[126:129], v[166:169], v[138:141]
	v_mfma_f32_16x16x32_bf16 v[118:121], v[102:105], v[174:177], v[118:121]
	v_mfma_f32_16x16x32_bf16 v[114:117], v[126:129], v[174:177], v[114:117]
	v_mfma_f32_16x16x32_bf16 v[94:97], v[102:105], v[182:185], v[94:97]
	v_mfma_f32_16x16x32_bf16 v[90:93], v[126:129], v[182:185], v[90:93]
	v_mfma_f32_16x16x32_bf16 v[78:81], v[102:105], v[226:229], v[78:81]
	v_mfma_f32_16x16x32_bf16 v[74:77], v[126:129], v[226:229], v[74:77]
	s_setprio 0
	s_setprio 1
	v_mfma_f32_16x16x32_bf16 v[134:137], v[146:149], v[162:165], v[134:137]
	v_mfma_f32_16x16x32_bf16 v[130:133], v[154:157], v[162:165], v[130:133]
	v_mfma_f32_16x16x32_bf16 v[110:113], v[146:149], v[170:173], v[110:113]
	v_mfma_f32_16x16x32_bf16 v[106:109], v[154:157], v[170:173], v[106:109]
	v_mfma_f32_16x16x32_bf16 v[86:89], v[146:149], v[178:181], v[86:89]
	v_mfma_f32_16x16x32_bf16 v[82:85], v[154:157], v[178:181], v[82:85]
	v_mfma_f32_16x16x32_bf16 v[70:73], v[146:149], v[222:225], v[70:73]
	v_mfma_f32_16x16x32_bf16 v[66:69], v[154:157], v[222:225], v[66:69]
	v_mfma_f32_16x16x32_bf16 v[134:137], v[150:153], v[166:169], v[134:137]
	v_mfma_f32_16x16x32_bf16 v[130:133], v[158:161], v[166:169], v[130:133]
	v_mfma_f32_16x16x32_bf16 v[110:113], v[150:153], v[174:177], v[110:113]
	v_mfma_f32_16x16x32_bf16 v[106:109], v[158:161], v[174:177], v[106:109]
	v_mfma_f32_16x16x32_bf16 v[86:89], v[150:153], v[182:185], v[86:89]
	v_mfma_f32_16x16x32_bf16 v[82:85], v[158:161], v[182:185], v[82:85]
	v_mfma_f32_16x16x32_bf16 v[70:73], v[150:153], v[226:229], v[70:73]
	v_mfma_f32_16x16x32_bf16 v[66:69], v[158:161], v[226:229], v[66:69]
	s_barrier
	s_setprio 0
	s_add_u32 s46, s44, 0x8000
	s_addc_u32 s47, s45, 0
	s_add_i32 s55, s55, s0
	s_mov_b32 m0, s55
	ds_read_b128 v[162:165], v217 offset:49152
	ds_read_b128 v[166:169], v217 offset:50176
	ds_read_b128 v[170:173], v217 offset:51200
	ds_read_b128 v[174:177], v217 offset:52224
	ds_read_b128 v[178:181], v217 offset:53248
	ds_read_b128 v[182:185], v217 offset:54272
	ds_read_b128 v[222:225], v217 offset:55296
	ds_read_b128 v[226:229], v217 offset:56320
	global_load_lds_dwordx4 v188, s[46:47]
	s_add_i32 m0, s55, 0x2000
	s_add_u32 s44, s44, 0x9000
	v_lshl_add_u64 v[230:231], s[46:47], 0, v[192:193]
	s_addc_u32 s45, s45, 0
	s_add_i32 s46, s67, s0
	global_load_lds_dwordx4 v[230:231], off
	s_mov_b32 m0, s46
	s_nop 0
	global_load_lds_dwordx4 v188, s[44:45]
	s_add_i32 m0, s46, 0x2000
	s_nop 0
	global_load_lds_dwordx4 v192, s[44:45]
	s_mov_b32 m0, s56
	s_nop 0
	global_load_lds_dwordx4 v186, s[42:43]
	s_mov_b32 m0, s57
	s_nop 0
	global_load_lds_dwordx4 v190, s[42:43]
	s_waitcnt vmcnt(8)
	s_waitcnt lgkmcnt(0)
	s_setprio 1
	s_barrier
	v_mfma_f32_16x16x32_bf16 v[62:65], v[98:101], v[162:165], v[62:65]
	v_mfma_f32_16x16x32_bf16 v[58:61], v[122:125], v[162:165], v[58:61]
	v_mfma_f32_16x16x32_bf16 v[46:49], v[98:101], v[170:173], v[46:49]
	v_mfma_f32_16x16x32_bf16 v[42:45], v[122:125], v[170:173], v[42:45]
	v_mfma_f32_16x16x32_bf16 v[30:33], v[98:101], v[178:181], v[30:33]
	v_mfma_f32_16x16x32_bf16 v[26:29], v[122:125], v[178:181], v[26:29]
	v_mfma_f32_16x16x32_bf16 v[14:17], v[98:101], v[222:225], v[14:17]
	v_mfma_f32_16x16x32_bf16 v[10:13], v[122:125], v[222:225], v[10:13]
	v_mfma_f32_16x16x32_bf16 v[62:65], v[102:105], v[166:169], v[62:65]
	v_mfma_f32_16x16x32_bf16 v[58:61], v[126:129], v[166:169], v[58:61]
	v_mfma_f32_16x16x32_bf16 v[46:49], v[102:105], v[174:177], v[46:49]
	v_mfma_f32_16x16x32_bf16 v[42:45], v[126:129], v[174:177], v[42:45]
	v_mfma_f32_16x16x32_bf16 v[30:33], v[102:105], v[182:185], v[30:33]
	v_mfma_f32_16x16x32_bf16 v[26:29], v[126:129], v[182:185], v[26:29]
	v_mfma_f32_16x16x32_bf16 v[14:17], v[102:105], v[226:229], v[14:17]
	v_mfma_f32_16x16x32_bf16 v[10:13], v[126:129], v[226:229], v[10:13]
	s_setprio 0
	s_setprio 1
	v_mfma_f32_16x16x32_bf16 v[54:57], v[146:149], v[162:165], v[54:57]
	v_mfma_f32_16x16x32_bf16 v[50:53], v[154:157], v[162:165], v[50:53]
	v_mfma_f32_16x16x32_bf16 v[38:41], v[146:149], v[170:173], v[38:41]
	v_mfma_f32_16x16x32_bf16 v[34:37], v[154:157], v[170:173], v[34:37]
	v_mfma_f32_16x16x32_bf16 v[22:25], v[146:149], v[178:181], v[22:25]
	v_mfma_f32_16x16x32_bf16 v[18:21], v[154:157], v[178:181], v[18:21]
	v_mfma_f32_16x16x32_bf16 v[6:9], v[146:149], v[222:225], v[6:9]
	v_mfma_f32_16x16x32_bf16 v[2:5], v[154:157], v[222:225], v[2:5]
	v_mfma_f32_16x16x32_bf16 v[54:57], v[150:153], v[166:169], v[54:57]
	v_mfma_f32_16x16x32_bf16 v[50:53], v[158:161], v[166:169], v[50:53]
	v_mfma_f32_16x16x32_bf16 v[38:41], v[150:153], v[174:177], v[38:41]
	v_mfma_f32_16x16x32_bf16 v[34:37], v[158:161], v[174:177], v[34:37]
	v_mfma_f32_16x16x32_bf16 v[22:25], v[150:153], v[182:185], v[22:25]
	v_mfma_f32_16x16x32_bf16 v[18:21], v[158:161], v[182:185], v[18:21]
	v_mfma_f32_16x16x32_bf16 v[6:9], v[150:153], v[226:229], v[6:9]
	v_mfma_f32_16x16x32_bf16 v[2:5], v[158:161], v[226:229], v[2:5]
	s_barrier
	s_setprio 0
	s_add_i32 s54, s54, 2
	s_add_u32 s36, s36, 0x10000
	s_addc_u32 s37, s37, 0
	s_add_u32 s52, s52, 0x10000
	s_addc_u32 s53, s53, 0
	s_cmp_gt_u32 s54, 61
	s_cbranch_scc0 .LBB0_682
	s_and_b64 vcc, exec, s[18:19]
	s_cbranch_vccz .LBB0_685
	s_barrier

; #define PG8_BAR __builtin_amdgcn_s_barrier()
; template <class Epi, class Sched, bool ALIGN_EPI = false, bool SP2 = false>
; __device__ __forceinline__ void gemm_phase(PG8_LAS unsigned char* lds, const Gemm g, const Sched& S, const Epi& E) {
;     ...
;     for (int i = 0; i < 2; ++i) { int R, C; stage_rc(tid * 16 + i * 8192, R, C); const int Rb = Epi::PERM ? (64 * (R >> 5) + perm32(R & 31)) : R;
;         voffA[i] = (unsigned)(R * 64 + C) * 2u; voffB[i] = (unsigned)(Rb * 64 + C) * 2u; }
;     const size_t kstep = (size_t)32768;
;     const size_t hstep = (size_t)HALF * 128;
;     const size_t tstep = (size_t)256 * K * 2; const size_t hstepB = Epi::PERM ? (size_t)32 * 128 : hstep;
;     const unsigned ldsw = (unsigned)wid * 1024u;
;     const int aoff = lds_byte(wr * 64 + fr, fq * 8), boff = lds_byte(wc * 32 + fr, fq * 8);
;     ...
;     Unit cur, nxt; int ui = 0;
;     if (!S.next(0, cur)) return;
;     f32x4 acc[2][2][4][2];
; #pragma unroll
;     for (int a = 0; a < 2; ++a)
; #pragma unroll
;         for (int b = 0; b < 2; ++b)
; #pragma unroll
;             for (int m = 0; m < 4; ++m)
; #pragma unroll
;                 for (int n = 0; n < 2; ++n) acc[a][b][m][n] = (f32x4){0.f, 0.f, 0.f, 0.f};
;     bf16x8 At[4][2], B0[2][2], B1[2][2];
;     const char* cA = (const char*)g.A + (size_t)cur.pm * tstep; const char* cB = (const char*)g.Bt + (size_t)cur.pn * tstep;
;     S.a_ready(cur);
;     float pre_st[8];
;     if constexpr (Epi::HAS_PRE) E.pre(pre_st, cur, wr, wc, fr, fq);
;     if constexpr (SP2) {
;         PG8_STAGE(PG8_SB(0, 0), cB, voffB); PG8_STAGE(PG8_SB(0, 1), cB + hstepB, voffB); PG8_STAGE(PG8_SA(0, 0), cA, voffA); PG8_STAGE(PG8_SA(0, 1), cA + hstep, voffA);
;         if (wr == 1) PG8_BAR;
;         PG8_WAIT_V(2); PG8_BAR;
;         PG8_STAGE(PG8_SB(1, 0), cB + kstep, voffB); PG8_STAGE(PG8_SA(1, 0), cA + kstep, voffA); PG8_STAGE(PG8_SB(1, 1), cB + hstepB + kstep, voffB);
;         PG8_WAIT_V(6); PG8_BAR;
;     } else {
;         PG8_STAGE(PG8_SB(0, 0), cB, voffB); PG8_STAGE(PG8_SA(0, 0), cA, voffA); PG8_STAGE(PG8_SB(0, 1), cB + hstepB, voffB); PG8_STAGE(PG8_SA(0, 1), cA + hstep, voffA);
;         if (wr == 1) PG8_BAR;
;         PG8_WAIT_V(4); PG8_BAR;
;         PG8_STAGE(PG8_SB(1, 0), cB + kstep, voffB); PG8_STAGE(PG8_SA(1, 0), cA + kstep, voffA); PG8_STAGE(PG8_SB(1, 1), cB + hstepB + kstep, voffB);
;         PG8_WAIT_V(6); PG8_BAR;
;     }
;     for (;;) {
.LBB0_716:
	s_and_b32 s58, s4, 3
	s_lshl_b32 s18, s6, 6
	s_lshl_b32 s7, s6, 13
	s_lshl_b32 s9, s58, 12
	s_add_u32 s59, s30, 0x80000
	s_addc_u32 s70, s31, 0
	s_add_u32 s4, s64, 0x8000
	s_addc_u32 s5, s65, 0
	s_add_i32 m0, s1, 0x18000
	s_waitcnt lgkmcnt(0)
	v_lshl_add_u64 v[2:3], s[4:5], 0, v[188:189]
	s_waitcnt vmcnt(2)
	s_barrier
	global_load_lds_dwordx4 v[2:3], off
	s_add_i32 m0, s1, 0x1a000
	v_lshl_add_u64 v[2:3], s[4:5], 0, v[192:193]
	s_add_u32 s4, s50, 0x8000
	s_addc_u32 s5, s51, 0
	s_add_i32 s71, s1, 0x8000
	global_load_lds_dwordx4 v[2:3], off
	s_mov_b32 m0, s71
	s_add_i32 s72, s1, 0xa000
	global_load_lds_dwordx4 v186, s[4:5]
	v_lshl_add_u64 v[2:3], s[4:5], 0, v[190:191]
	s_add_u32 s4, s64, 0x9000
	s_mov_b32 m0, s72
	s_addc_u32 s5, s65, 0
	global_load_lds_dwordx4 v[2:3], off
	s_add_i32 m0, s1, 0x1c000
	s_nop 0
	global_load_lds_dwordx4 v188, s[4:5]
	s_add_i32 m0, s1, 0x1e000
	v_lshlrev_b32_e32 v213, 4, v212
	global_load_lds_dwordx4 v192, s[4:5]
	v_lshlrev_b32_e32 v2, 2, v208
	v_lshl_or_b32 v4, v208, 6, v213
	v_and_b32_e32 v2, 32, v2
	v_bitop3_b32 v3, v4, s7, v2 bitop3:0xde
	v_lshlrev_b32_e32 v2, 6, v218
	s_movk_i32 s4, 0x3c0
	s_cmpk_lt_u32 s8, 0x100
	v_and_or_b32 v2, v2, s4, v213
	s_cselect_b64 s[20:21], -1, 0
	s_lshl_b32 s4, s6, 2
	s_mov_b32 s19, s15
	s_or_b32 s4, s4, s58
	s_lshl_b64 s[22:23], s[18:19], 7
	s_or_b32 s6, s58, s6
	s_mul_i32 s7, s4, 0x900
	s_cmp_eq_u32 s6, 0
	v_lshlrev_b32_e32 v4, 2, v218
	s_cselect_b64 s[24:25], -1, 0
	s_add_i32 s7, s7, 0
	v_and_b32_e32 v8, 0x3800, v209
	v_lshlrev_b32_e32 v9, 7, v210
	v_and_b32_e32 v4, 32, v4
	s_add_i32 s7, s7, 0x20000
	v_or3_b32 v8, v206, v8, v9
	v_bitop3_b32 v214, s9, v2, v4 bitop3:0xf6
	s_waitcnt vmcnt(6)
	v_lshrrev_b32_e32 v215, 3, v1
	v_and_b32_e32 v2, 7, v218
	s_movk_i32 s14, 0x90
	v_mov_b32_e32 v7, s7
	v_add_u32_e32 v198, v8, v207
	v_and_b32_e32 v8, 0x7800, v211
	v_and_b32_e32 v4, 0x70, v209
	v_lshlrev_b32_e32 v5, 5, v212
	v_lshlrev_b32_e32 v6, 4, v2
	s_lshl_b32 s6, s58, 6
	v_lshlrev_b32_e32 v2, 2, v2
	v_mad_u32_u24 v216, v208, s14, v7
	v_mad_u32_u24 v7, v215, s14, v7
	v_or3_b32 v8, v206, v8, v9
	s_add_i32 s74, 0, 0x10000
	s_add_i32 s75, 0, 0x14000
	v_add_u32_e32 v211, 0, v3
	v_mbcnt_lo_u32_b32 v3, -1, 0
	v_lshlrev_b32_e32 v196, 4, v1
	v_mov_b32_e32 v197, v195
	v_cmp_eq_u32_e64 s[8:9], 0, v212
	v_cmp_eq_u32_e64 s[4:5], 0, v1
	v_lshl_or_b32 v212, v212, 3, s6
	s_ashr_i32 s19, s2, 31
	s_mov_b32 s73, 0x20000
	v_mov_b32_e32 v199, v195
	v_add_u32_e32 v200, v8, v207
	v_mov_b32_e32 v201, v195
	v_mov_b64_e32 v[202:203], 0x400
	v_mov_b64_e32 v[204:205], 0x3ff
	v_add_u32_e32 v209, s74, v214
	v_add_u32_e32 v210, s75, v214
	s_movk_i32 s76, 0x1000
	s_movk_i32 s77, 0x5000
	v_mbcnt_hi_u32_b32 v217, -1, v3
	s_lshl_b32 s14, s6, 2
	v_lshlrev_b32_e32 v194, 2, v2
	v_mov_b32_e32 v219, 0x358637bd
	v_add_u32_e32 v220, v216, v5
	v_add_u32_e32 v221, v7, v6
	s_mov_b32 s78, 0x28000
	s_mov_b32 s79, 0x30000
	s_mov_b32 s80, 0x38000
	s_mov_b32 s81, 0x80000
	s_mov_b32 s82, 0x88000
	s_mov_b32 s83, 0x90000
	s_mov_b32 s84, 0x98000
	s_mov_b32 s85, 0xa0000
	s_mov_b32 s86, 0xa8000
	s_mov_b32 s87, 0xb0000
	s_mov_b32 s88, 0xb8000
	v_add_u32_e32 v222, v7, v4
	s_mov_b32 s26, s15
	s_barrier
	s_branch .LBB0_719

; #define PG8_STAGE(bufoff, gbase, voff) do { _Pragma("unroll") for (int _i = 0; _i < 2; ++_i) \
;         __builtin_amdgcn_global_load_lds((const unsigned*)((const char*)(gbase) + (voff)[_i]), (PG8_LAS unsigned*)(lds + (bufoff) + ldsw + _i * 8192), 16, 0, 0); } while (0)
; #define PG8_LDA(dst, b, h) do { _Pragma("unroll") for (int m = 0; m < 4; ++m) _Pragma("unroll") for (int k = 0; k < 2; ++k) dst[m][k] = *(const PG8_LAS bf16x8*)(lds + PG8_SA(b, h) + aoff + m * 2048 + k * 1024); } while (0)
; #define PG8_LDB(dst, b, h) do { _Pragma("unroll") for (int n = 0; n < 2; ++n) _Pragma("unroll") for (int k = 0; k < 2; ++k) dst[n][k] = *(const PG8_LAS bf16x8*)(lds + PG8_SB(b, h) + boff + n * 2048 + k * 1024); } while (0)
; #define PG8_MMA(ai, bj, At, Bt) do { __builtin_amdgcn_s_setprio(1); _Pragma("unroll") for (int m = 0; m < 4; ++m) _Pragma("unroll") for (int n = 0; n < 2; ++n) _Pragma("unroll") for (int k = 0; k < 2; ++k) \
;         acc[ai][bj][m][n] = __builtin_amdgcn_mfma_f32_16x16x32_bf16(Bt[n][k], At[m][k], acc[ai][bj][m][n], 0, 0, 0); __builtin_amdgcn_s_setprio(0); } while (0)
; #define PG8_BAR __builtin_amdgcn_s_barrier()
; template <class Epi, class Sched, bool ALIGN_EPI = false, bool SP2 = false>
; __device__ __forceinline__ void gemm_phase(PG8_LAS unsigned char* lds, const Gemm g, const Sched& S, const Epi& E) {
;     ...
;         for (int t = 0; t < nt; t += 2) {
;             if constexpr (Epi::HAS_MID) { if (t == (nt >> 1)) E.mid(acc, cur, wr, wc, fr, fq); }
;             const bool last = (t == nt - 2);
;             const char* a1 = cA + (size_t)(t + 1) * kstep;
;             const char* a2 = last ? nA : cA + (size_t)(t + 2) * kstep; const char* b2 = last ? nB : cB + (size_t)(t + 2) * kstep;
;             const char* a3 = a2 + kstep; const char* b3 = b2 + kstep;
;             if (last && has_next) S.a_ready(nxt);
;             if constexpr (SP2) {
;             PG8_LDB(B0, 0, 0); PG8_LDB(B1, 0, 1); PG8_SCHED; PG8_LDA(At, 0, 0); PG8_STAGE(PG8_SA(1, 1), a1 + hstep, voffA);
;             PG8_WAIT_V(8); PG8_WAIT_L(0); PG8_BAR; PG8_MMA(0, 0, At, B0); PG8_MMA(0, 1, At, B1); PG8_BAR; PG8_SCHED;
;             PG8_LDA(At, 0, 1); PG8_STAGE(PG8_SB(0, 0), b2, voffB); PG8_STAGE(PG8_SB(0, 1), b2 + hstepB, voffB); PG8_STAGE(PG8_SA(0, 0), a2, voffA);
;             PG8_WAIT_V(8); PG8_WAIT_L(0); PG8_BAR; PG8_MMA(1, 0, At, B0); PG8_MMA(1, 1, At, B1); PG8_BAR; PG8_SCHED;
.LBB0_726:
	ds_read_b128 v[130:133], v209
	ds_read_b128 v[134:137], v209 offset:1024
	ds_read_b128 v[138:141], v209 offset:2048
	ds_read_b128 v[142:145], v209 offset:3072
	ds_read_b128 v[146:149], v210
	ds_read_b128 v[150:153], v210 offset:1024
	ds_read_b128 v[154:157], v210 offset:2048
	ds_read_b128 v[158:161], v210 offset:3072
	s_add_u32 s54, s50, 0x4000
	s_addc_u32 s55, s51, 0
	s_cmp_eq_u32 s53, 60
	s_cselect_b32 s68, s29, s54
	s_cselect_b32 s69, s27, s55
	s_cselect_b32 s66, s47, s49
	s_cselect_b32 s67, s37, s52
	s_add_u32 s64, s68, 0x8000
	s_addc_u32 s65, s69, 0
	s_add_i32 m0, s1, 0xc000
	ds_read_b128 v[162:165], v211
	ds_read_b128 v[166:169], v211 offset:1024
	ds_read_b128 v[170:173], v211 offset:2048
	ds_read_b128 v[174:177], v211 offset:3072
	ds_read_b128 v[178:181], v211 offset:4096
	ds_read_b128 v[182:185], v211 offset:5120
	ds_read_b128 v[224:227], v211 offset:6144
	ds_read_b128 v[228:231], v211 offset:7168
	global_load_lds_dwordx4 v198, s[50:51]
	s_add_i32 m0, s1, 0xe000
	s_nop 0
	global_load_lds_dwordx4 v200, s[50:51]
	s_waitcnt vmcnt(8)
	s_waitcnt lgkmcnt(0)
	s_setprio 1
	s_barrier
	v_mfma_f32_16x16x32_bf16 v[126:129], v[130:133], v[162:165], v[126:129]
	v_mfma_f32_16x16x32_bf16 v[122:125], v[138:141], v[162:165], v[122:125]
	v_mfma_f32_16x16x32_bf16 v[110:113], v[130:133], v[170:173], v[110:113]
	v_mfma_f32_16x16x32_bf16 v[106:109], v[138:141], v[170:173], v[106:109]
	v_mfma_f32_16x16x32_bf16 v[94:97], v[130:133], v[178:181], v[94:97]
	v_mfma_f32_16x16x32_bf16 v[90:93], v[138:141], v[178:181], v[90:93]
	v_mfma_f32_16x16x32_bf16 v[78:81], v[130:133], v[224:227], v[78:81]
	v_mfma_f32_16x16x32_bf16 v[74:77], v[138:141], v[224:227], v[74:77]
	v_mfma_f32_16x16x32_bf16 v[126:129], v[134:137], v[166:169], v[126:129]
	v_mfma_f32_16x16x32_bf16 v[122:125], v[142:145], v[166:169], v[122:125]
	v_mfma_f32_16x16x32_bf16 v[110:113], v[134:137], v[174:177], v[110:113]
	v_mfma_f32_16x16x32_bf16 v[106:109], v[142:145], v[174:177], v[106:109]
	v_mfma_f32_16x16x32_bf16 v[94:97], v[134:137], v[182:185], v[94:97]
	v_mfma_f32_16x16x32_bf16 v[90:93], v[142:145], v[182:185], v[90:93]
	v_mfma_f32_16x16x32_bf16 v[78:81], v[134:137], v[228:231], v[78:81]
	v_mfma_f32_16x16x32_bf16 v[74:77], v[142:145], v[228:231], v[74:77]
	s_setprio 0
	s_setprio 1
	v_mfma_f32_16x16x32_bf16 v[118:121], v[146:149], v[162:165], v[118:121]
	v_mfma_f32_16x16x32_bf16 v[114:117], v[154:157], v[162:165], v[114:117]
	v_mfma_f32_16x16x32_bf16 v[102:105], v[146:149], v[170:173], v[102:105]
	v_mfma_f32_16x16x32_bf16 v[98:101], v[154:157], v[170:173], v[98:101]
	v_mfma_f32_16x16x32_bf16 v[86:89], v[146:149], v[178:181], v[86:89]
	v_mfma_f32_16x16x32_bf16 v[82:85], v[154:157], v[178:181], v[82:85]
	v_mfma_f32_16x16x32_bf16 v[70:73], v[146:149], v[224:227], v[70:73]
	v_mfma_f32_16x16x32_bf16 v[66:69], v[154:157], v[224:227], v[66:69]
	v_mfma_f32_16x16x32_bf16 v[118:121], v[150:153], v[166:169], v[118:121]
	v_mfma_f32_16x16x32_bf16 v[114:117], v[158:161], v[166:169], v[114:117]
	v_mfma_f32_16x16x32_bf16 v[102:105], v[150:153], v[174:177], v[102:105]
	v_mfma_f32_16x16x32_bf16 v[98:101], v[158:161], v[174:177], v[98:101]
	v_mfma_f32_16x16x32_bf16 v[86:89], v[150:153], v[182:185], v[86:89]
	v_mfma_f32_16x16x32_bf16 v[82:85], v[158:161], v[182:185], v[82:85]
	v_mfma_f32_16x16x32_bf16 v[70:73], v[150:153], v[228:231], v[70:73]
	v_mfma_f32_16x16x32_bf16 v[66:69], v[158:161], v[228:231], v[66:69]
	s_barrier
	s_setprio 0
	s_add_i32 s54, s74, s0
	s_mov_b32 m0, s54
	ds_read_b128 v[162:165], v211 offset:16384
	ds_read_b128 v[166:169], v211 offset:17408
	ds_read_b128 v[170:173], v211 offset:18432
	ds_read_b128 v[174:177], v211 offset:19456
	ds_read_b128 v[178:181], v211 offset:20480
	ds_read_b128 v[182:185], v211 offset:21504
	ds_read_b128 v[224:227], v211 offset:22528
	ds_read_b128 v[228:231], v211 offset:23552
	global_load_lds_dwordx4 v188, s[66:67]
	s_add_i32 m0, s54, 0x2000
	s_add_u32 s54, s66, 0x1000
	s_addc_u32 s55, s67, 0
	s_add_i32 s89, s75, s0
	global_load_lds_dwordx4 v192, s[66:67]
	s_mov_b32 m0, s89
	s_nop 0
	global_load_lds_dwordx4 v188, s[54:55]
	s_add_i32 m0, s89, 0x2000
	s_nop 0
	global_load_lds_dwordx4 v192, s[54:55]
	s_mov_b32 m0, s1
	s_nop 0
	global_load_lds_dwordx4 v186, s[68:69]
	s_mov_b32 m0, s3
	s_nop 0
	global_load_lds_dwordx4 v190, s[68:69]
	s_waitcnt vmcnt(8)
	s_waitcnt lgkmcnt(0)
	s_setprio 1
	s_barrier
	v_mfma_f32_16x16x32_bf16 v[62:65], v[130:133], v[162:165], v[62:65]
	v_mfma_f32_16x16x32_bf16 v[58:61], v[138:141], v[162:165], v[58:61]
	v_mfma_f32_16x16x32_bf16 v[46:49], v[130:133], v[170:173], v[46:49]
	v_mfma_f32_16x16x32_bf16 v[42:45], v[138:141], v[170:173], v[42:45]
	v_mfma_f32_16x16x32_bf16 v[30:33], v[130:133], v[178:181], v[30:33]
	v_mfma_f32_16x16x32_bf16 v[26:29], v[138:141], v[178:181], v[26:29]
	v_mfma_f32_16x16x32_bf16 v[14:17], v[130:133], v[224:227], v[14:17]
	v_mfma_f32_16x16x32_bf16 v[10:13], v[138:141], v[224:227], v[10:13]
	v_mfma_f32_16x16x32_bf16 v[62:65], v[134:137], v[166:169], v[62:65]
	v_mfma_f32_16x16x32_bf16 v[58:61], v[142:145], v[166:169], v[58:61]
	v_mfma_f32_16x16x32_bf16 v[46:49], v[134:137], v[174:177], v[46:49]
	v_mfma_f32_16x16x32_bf16 v[42:45], v[142:145], v[174:177], v[42:45]
	v_mfma_f32_16x16x32_bf16 v[30:33], v[134:137], v[182:185], v[30:33]
	v_mfma_f32_16x16x32_bf16 v[26:29], v[142:145], v[182:185], v[26:29]
	v_mfma_f32_16x16x32_bf16 v[14:17], v[134:137], v[228:231], v[14:17]
	v_mfma_f32_16x16x32_bf16 v[10:13], v[142:145], v[228:231], v[10:13]
	s_setprio 0
	s_setprio 1
	v_mfma_f32_16x16x32_bf16 v[54:57], v[146:149], v[162:165], v[54:57]
	v_mfma_f32_16x16x32_bf16 v[50:53], v[154:157], v[162:165], v[50:53]
	v_mfma_f32_16x16x32_bf16 v[38:41], v[146:149], v[170:173], v[38:41]
	v_mfma_f32_16x16x32_bf16 v[34:37], v[154:157], v[170:173], v[34:37]
	v_mfma_f32_16x16x32_bf16 v[22:25], v[146:149], v[178:181], v[22:25]
	v_mfma_f32_16x16x32_bf16 v[18:21], v[154:157], v[178:181], v[18:21]
	v_mfma_f32_16x16x32_bf16 v[6:9], v[146:149], v[224:227], v[6:9]
	v_mfma_f32_16x16x32_bf16 v[2:5], v[154:157], v[224:227], v[2:5]
	v_mfma_f32_16x16x32_bf16 v[54:57], v[150:153], v[166:169], v[54:57]
	v_mfma_f32_16x16x32_bf16 v[50:53], v[158:161], v[166:169], v[50:53]
	v_mfma_f32_16x16x32_bf16 v[38:41], v[150:153], v[174:177], v[38:41]
	v_mfma_f32_16x16x32_bf16 v[34:37], v[158:161], v[174:177], v[34:37]
	v_mfma_f32_16x16x32_bf16 v[22:25], v[150:153], v[182:185], v[22:25]
	v_mfma_f32_16x16x32_bf16 v[18:21], v[158:161], v[182:185], v[18:21]
	v_mfma_f32_16x16x32_bf16 v[6:9], v[150:153], v[228:231], v[6:9]
	v_mfma_f32_16x16x32_bf16 v[2:5], v[158:161], v[228:231], v[2:5]
	s_barrier
; #define PG8_STAGE(bufoff, gbase, voff) do { _Pragma("unroll") for (int _i = 0; _i < 2; ++_i) \
;         __builtin_amdgcn_global_load_lds((const unsigned*)((const char*)(gbase) + (voff)[_i]), (PG8_LAS unsigned*)(lds + (bufoff) + ldsw + _i * 8192), 16, 0, 0); } while (0)
; #define PG8_LDA(dst, b, h) do { _Pragma("unroll") for (int m = 0; m < 4; ++m) _Pragma("unroll") for (int k = 0; k < 2; ++k) dst[m][k] = *(const PG8_LAS bf16x8*)(lds + PG8_SA(b, h) + aoff + m * 2048 + k * 1024); } while (0)
; #define PG8_LDB(dst, b, h) do { _Pragma("unroll") for (int n = 0; n < 2; ++n) _Pragma("unroll") for (int k = 0; k < 2; ++k) dst[n][k] = *(const PG8_LAS bf16x8*)(lds + PG8_SB(b, h) + boff + n * 2048 + k * 1024); } while (0)
; #define PG8_MMA(ai, bj, At, Bt) do { __builtin_amdgcn_s_setprio(1); _Pragma("unroll") for (int m = 0; m < 4; ++m) _Pragma("unroll") for (int n = 0; n < 2; ++n) _Pragma("unroll") for (int k = 0; k < 2; ++k) \
;         acc[ai][bj][m][n] = __builtin_amdgcn_mfma_f32_16x16x32_bf16(Bt[n][k], At[m][k], acc[ai][bj][m][n], 0, 0, 0); __builtin_amdgcn_s_setprio(0); } while (0)
; #define PG8_WAIT_V(n) asm volatile("s_waitcnt vmcnt(" #n ")" ::: "memory")
; #define PG8_WAIT_L(n) asm volatile("s_waitcnt lgkmcnt(" #n ")" ::: "memory")
; #define PG8_BAR __builtin_amdgcn_s_barrier()
; #define PG8_SCHED __builtin_amdgcn_sched_barrier(0)
; template <class Epi, class Sched, bool ALIGN_EPI = false, bool SP2 = false>
; __device__ __forceinline__ void gemm_phase(PG8_LAS unsigned char* lds, const Gemm g, const Sched& S, const Epi& E) {
;     ...
;             PG8_LDB(B0, 1, 0); PG8_LDB(B1, 1, 1); PG8_SCHED; PG8_LDA(At, 1, 0); PG8_STAGE(PG8_SA(0, 1), a2 + hstep, voffA);
;             PG8_WAIT_V(8); PG8_WAIT_L(0); PG8_BAR; PG8_MMA(0, 0, At, B0); PG8_MMA(0, 1, At, B1); PG8_BAR; PG8_SCHED;
;             PG8_LDA(At, 1, 1); PG8_STAGE(PG8_SB(1, 0), b3, voffB); PG8_STAGE(PG8_SB(1, 1), b3 + hstepB, voffB); PG8_STAGE(PG8_SA(1, 0), a3, voffA);
;             PG8_WAIT_V(8); PG8_WAIT_L(0); PG8_BAR; PG8_MMA(1, 0, At, B0); PG8_MMA(1, 1, At, B1); PG8_BAR; PG8_SCHED;
;     ...
;         if constexpr (ALIGN_EPI) { if (wr == 0) PG8_BAR; }
	s_setprio 0
	s_add_i32 s89, 0, 0x18000
	s_add_i32 s90, 0, 0x1c000
	v_add_u32_e32 v142, s89, v214
	v_add_u32_e32 v158, s90, v214
	ds_read_b128 v[130:133], v142
	ds_read_b128 v[134:137], v142 offset:1024
	ds_read_b128 v[138:141], v142 offset:2048
	ds_read_b128 v[142:145], v142 offset:3072
	ds_read_b128 v[146:149], v158
	ds_read_b128 v[150:153], v158 offset:1024
	ds_read_b128 v[154:157], v158 offset:2048
	ds_read_b128 v[158:161], v158 offset:3072
	s_add_u32 s54, s68, 0x4000
	s_addc_u32 s55, s69, 0
	s_mov_b32 m0, s56
	ds_read_b128 v[162:165], v211 offset:32768
	ds_read_b128 v[166:169], v211 offset:33792
	ds_read_b128 v[170:173], v211 offset:34816
	ds_read_b128 v[174:177], v211 offset:35840
	ds_read_b128 v[178:181], v211 offset:36864
	ds_read_b128 v[182:185], v211 offset:37888
	ds_read_b128 v[224:227], v211 offset:38912
	ds_read_b128 v[228:231], v211 offset:39936
	global_load_lds_dwordx4 v186, s[54:55]
	s_mov_b32 m0, s57
	s_nop 0
	global_load_lds_dwordx4 v190, s[54:55]
	s_waitcnt vmcnt(8)
	s_waitcnt lgkmcnt(0)
	s_setprio 1
	s_barrier
	v_mfma_f32_16x16x32_bf16 v[126:129], v[130:133], v[162:165], v[126:129]
	v_mfma_f32_16x16x32_bf16 v[122:125], v[138:141], v[162:165], v[122:125]
	v_mfma_f32_16x16x32_bf16 v[110:113], v[130:133], v[170:173], v[110:113]
	v_mfma_f32_16x16x32_bf16 v[106:109], v[138:141], v[170:173], v[106:109]
	v_mfma_f32_16x16x32_bf16 v[94:97], v[130:133], v[178:181], v[94:97]
	v_mfma_f32_16x16x32_bf16 v[90:93], v[138:141], v[178:181], v[90:93]
	v_mfma_f32_16x16x32_bf16 v[78:81], v[130:133], v[224:227], v[78:81]
	v_mfma_f32_16x16x32_bf16 v[74:77], v[138:141], v[224:227], v[74:77]
	v_mfma_f32_16x16x32_bf16 v[126:129], v[134:137], v[166:169], v[126:129]
	v_mfma_f32_16x16x32_bf16 v[122:125], v[142:145], v[166:169], v[122:125]
	v_mfma_f32_16x16x32_bf16 v[110:113], v[134:137], v[174:177], v[110:113]
	v_mfma_f32_16x16x32_bf16 v[106:109], v[142:145], v[174:177], v[106:109]
	v_mfma_f32_16x16x32_bf16 v[94:97], v[134:137], v[182:185], v[94:97]
	v_mfma_f32_16x16x32_bf16 v[90:93], v[142:145], v[182:185], v[90:93]
	v_mfma_f32_16x16x32_bf16 v[78:81], v[134:137], v[228:231], v[78:81]
	v_mfma_f32_16x16x32_bf16 v[74:77], v[142:145], v[228:231], v[74:77]
	s_setprio 0
	s_setprio 1
	v_mfma_f32_16x16x32_bf16 v[118:121], v[146:149], v[162:165], v[118:121]
	v_mfma_f32_16x16x32_bf16 v[114:117], v[154:157], v[162:165], v[114:117]
	v_mfma_f32_16x16x32_bf16 v[102:105], v[146:149], v[170:173], v[102:105]
	v_mfma_f32_16x16x32_bf16 v[98:101], v[154:157], v[170:173], v[98:101]
	v_mfma_f32_16x16x32_bf16 v[86:89], v[146:149], v[178:181], v[86:89]
	v_mfma_f32_16x16x32_bf16 v[82:85], v[154:157], v[178:181], v[82:85]
	v_mfma_f32_16x16x32_bf16 v[70:73], v[146:149], v[224:227], v[70:73]
	v_mfma_f32_16x16x32_bf16 v[66:69], v[154:157], v[224:227], v[66:69]
	v_mfma_f32_16x16x32_bf16 v[118:121], v[150:153], v[166:169], v[118:121]
	v_mfma_f32_16x16x32_bf16 v[114:117], v[158:161], v[166:169], v[114:117]
	v_mfma_f32_16x16x32_bf16 v[102:105], v[150:153], v[174:177], v[102:105]
	v_mfma_f32_16x16x32_bf16 v[98:101], v[158:161], v[174:177], v[98:101]
	v_mfma_f32_16x16x32_bf16 v[86:89], v[150:153], v[182:185], v[86:89]
	v_mfma_f32_16x16x32_bf16 v[82:85], v[158:161], v[182:185], v[82:85]
	v_mfma_f32_16x16x32_bf16 v[70:73], v[150:153], v[228:231], v[70:73]
	v_mfma_f32_16x16x32_bf16 v[66:69], v[158:161], v[228:231], v[66:69]
	s_barrier
	s_setprio 0
	s_add_u32 s54, s66, 0x8000
	s_addc_u32 s55, s67, 0
	s_add_i32 s68, s89, s0
	s_mov_b32 m0, s68
	ds_read_b128 v[162:165], v211 offset:49152
	ds_read_b128 v[166:169], v211 offset:50176
	ds_read_b128 v[170:173], v211 offset:51200
	ds_read_b128 v[174:177], v211 offset:52224
	ds_read_b128 v[178:181], v211 offset:53248
	ds_read_b128 v[182:185], v211 offset:54272
	ds_read_b128 v[224:227], v211 offset:55296
	ds_read_b128 v[228:231], v211 offset:56320
	global_load_lds_dwordx4 v188, s[54:55]
	s_add_i32 m0, s68, 0x2000
	v_lshl_add_u64 v[206:207], s[54:55], 0, v[192:193]
	s_add_u32 s54, s66, 0x9000
	s_addc_u32 s55, s67, 0
	s_add_i32 s66, s90, s0
	global_load_lds_dwordx4 v[206:207], off
	s_mov_b32 m0, s66
	s_nop 0
	global_load_lds_dwordx4 v188, s[54:55]
	s_add_i32 m0, s66, 0x2000
	s_nop 0
	global_load_lds_dwordx4 v192, s[54:55]
	s_mov_b32 m0, s71
	s_nop 0
	global_load_lds_dwordx4 v186, s[64:65]
	s_mov_b32 m0, s72
	s_nop 0
	global_load_lds_dwordx4 v190, s[64:65]
	s_waitcnt vmcnt(8)
	s_waitcnt lgkmcnt(0)
	s_setprio 1
	s_barrier
	v_mfma_f32_16x16x32_bf16 v[62:65], v[130:133], v[162:165], v[62:65]
	v_mfma_f32_16x16x32_bf16 v[58:61], v[138:141], v[162:165], v[58:61]
	v_mfma_f32_16x16x32_bf16 v[46:49], v[130:133], v[170:173], v[46:49]
	v_mfma_f32_16x16x32_bf16 v[42:45], v[138:141], v[170:173], v[42:45]
	v_mfma_f32_16x16x32_bf16 v[30:33], v[130:133], v[178:181], v[30:33]
	v_mfma_f32_16x16x32_bf16 v[26:29], v[138:141], v[178:181], v[26:29]
	v_mfma_f32_16x16x32_bf16 v[14:17], v[130:133], v[224:227], v[14:17]
	v_mfma_f32_16x16x32_bf16 v[10:13], v[138:141], v[224:227], v[10:13]
	v_mfma_f32_16x16x32_bf16 v[62:65], v[134:137], v[166:169], v[62:65]
	v_mfma_f32_16x16x32_bf16 v[58:61], v[142:145], v[166:169], v[58:61]
	v_mfma_f32_16x16x32_bf16 v[46:49], v[134:137], v[174:177], v[46:49]
	v_mfma_f32_16x16x32_bf16 v[42:45], v[142:145], v[174:177], v[42:45]
	v_mfma_f32_16x16x32_bf16 v[30:33], v[134:137], v[182:185], v[30:33]
	v_mfma_f32_16x16x32_bf16 v[26:29], v[142:145], v[182:185], v[26:29]
	v_mfma_f32_16x16x32_bf16 v[14:17], v[134:137], v[228:231], v[14:17]
	v_mfma_f32_16x16x32_bf16 v[10:13], v[142:145], v[228:231], v[10:13]
	s_setprio 0
	s_setprio 1
	v_mfma_f32_16x16x32_bf16 v[54:57], v[146:149], v[162:165], v[54:57]
	v_mfma_f32_16x16x32_bf16 v[50:53], v[154:157], v[162:165], v[50:53]
	v_mfma_f32_16x16x32_bf16 v[38:41], v[146:149], v[170:173], v[38:41]
	v_mfma_f32_16x16x32_bf16 v[34:37], v[154:157], v[170:173], v[34:37]
	v_mfma_f32_16x16x32_bf16 v[22:25], v[146:149], v[178:181], v[22:25]
	v_mfma_f32_16x16x32_bf16 v[18:21], v[154:157], v[178:181], v[18:21]
	v_mfma_f32_16x16x32_bf16 v[6:9], v[146:149], v[224:227], v[6:9]
	v_mfma_f32_16x16x32_bf16 v[2:5], v[154:157], v[224:227], v[2:5]
	v_mfma_f32_16x16x32_bf16 v[54:57], v[150:153], v[166:169], v[54:57]
	v_mfma_f32_16x16x32_bf16 v[50:53], v[158:161], v[166:169], v[50:53]
	v_mfma_f32_16x16x32_bf16 v[38:41], v[150:153], v[174:177], v[38:41]
	v_mfma_f32_16x16x32_bf16 v[34:37], v[158:161], v[174:177], v[34:37]
	v_mfma_f32_16x16x32_bf16 v[22:25], v[150:153], v[182:185], v[22:25]
	v_mfma_f32_16x16x32_bf16 v[18:21], v[158:161], v[182:185], v[18:21]
	v_mfma_f32_16x16x32_bf16 v[6:9], v[150:153], v[228:231], v[6:9]
	v_mfma_f32_16x16x32_bf16 v[2:5], v[158:161], v[228:231], v[2:5]
	s_barrier
	s_setprio 0
	s_add_i32 s53, s53, 2
	s_add_u32 s50, s50, 0x10000
	s_addc_u32 s51, s51, 0
	s_add_u32 s49, s49, 0x10000
	s_addc_u32 s52, s52, 0
	s_cmp_gt_u32 s53, 61
	s_cbranch_scc0 .LBB0_726
	s_and_b64 vcc, exec, s[20:21]
	s_cbranch_vccz .LBB0_729
	s_barrier
